# EpiRes epilogues: the two 8-byte stores of adjacent 16-column fragments paired into one 16-byte store via v_permlane32_swap + v_permlane16_swap (cached, not write-through)
# baseline (speedup 1.0000x reference)
; __device__ __forceinline__ u32x2 pk4(f32x4 v) { u32x2 r; r.x = pk2(v.x, v.y); r.y = pk2(v.z, v.w); return r; }
;     __device__ __forceinline__ void operator()(const f32x4 (&acc)[2][2][4][2], const pg8::Unit& u, int wr, int wc, int fr, int fq) const {
;     ...
;                 for (int bj = 0; bj < 2; ++bj)
; #pragma unroll
;                     for (int n = 0; n < 2; ++n) {
;                         const int col = u.pn * 256 + bj * 128 + wc * 32 + n * 16 + fq * 4;
;                         const u32x2 raw = *(const u32x2*)(src + (size_t)row * DM + col);
;                         f32x4 x = (f32x4){bflo(raw.x), bfhi(raw.x), bflo(raw.y), bfhi(raw.y)};
;                         if (ln) x = (x - mu) * rs * *(const f32x4*)(g + col) + *(const f32x4*)(b + col);
;                         const u32x2 pz = pk4(x * ALPHA + acc[ai][bj][m][n]);
;                         *(u32x2*)(dst + (size_t)row * DM + col) = pz;
;                         const float z0 = bflo(pz.x), z1 = bfhi(pz.x), z2 = bflo(pz.y), z3 = bfhi(pz.y);
;                         s1 += (z0 + z1) + (z2 + z3); s2 += (z0 * z0 + z1 * z1) + (z2 * z2 + z3 * z3);
;                     }
;                 s1 += __shfl_xor(s1, 16); s2 += __shfl_xor(s2, 16); s1 += __shfl_xor(s1, 32); s2 += __shfl_xor(s2, 32);
;                 if (fq == 0) { float* p = stm_n + (size_t)row * 32 + (u.pn * 4 + wc) * 2; p[0] = s1; p[1] = s2; }
.LBB0_1858:
	v_pk_fma_f32 v[106:107], v[124:125], s[72:73], v[106:107] op_sel_hi:[1,0,1]
	v_pk_fma_f32 v[104:105], v[110:111], s[72:73], v[104:105] op_sel_hi:[1,0,1]
	s_and_b64 vcc, exec, s[44:45]
	v_cvt_pk_bf16_f32 v104, v104, v105
	v_cvt_pk_bf16_f32 v105, v106, v107
	v_mov_b64_e32 v[148:149], v[104:105]
	s_waitcnt vmcnt(11)
	v_mov_b64_e32 v[110:111], v[240:241]
	global_load_dwordx2 v[240:241], v243, s[46:47] offset:288
	s_waitcnt lgkmcnt(0)
	v_lshlrev_b32_e32 v106, 16, v110
	v_and_b32_e32 v107, 0xffff0000, v110
	v_lshlrev_b32_e32 v110, 16, v111
	v_and_b32_e32 v111, 0xffff0000, v111
	s_cbranch_vccnz .LBB0_1860
	v_sub_f32_e32 v107, v107, v119
	v_sub_f32_e32 v106, v106, v119
	v_sub_f32_e32 v111, v111, v119
	v_sub_f32_e32 v110, v110, v119
	v_pk_mul_f32 v[106:107], v[120:121], v[106:107]
	v_mov_b32_e32 v121, v120
	v_pk_mul_f32 v[110:111], v[120:121], v[110:111]
	ds_read_b128 v[118:121], v244 offset:192
	ds_read_b128 v[122:125], v244 offset:448
	s_waitcnt lgkmcnt(0)
	v_pk_fma_f32 v[110:111], v[110:111], v[120:121], v[124:125]
	v_pk_fma_f32 v[106:107], v[106:107], v[118:119], v[122:123]
.LBB0_1860:
	v_and_b32_e32 v121, 16, v114
	v_and_b32_e32 v120, 0xffff0000, v114
	v_lshlrev_b32_e32 v122, 16, v114
	v_lshlrev_b32_e32 v118, 16, v115
	v_and_b32_e32 v125, 0xffff0000, v114
	v_and_b32_e32 v124, 0xffff0000, v115
	v_mov_b32_e32 v3, v120
	v_mov_b32_e32 v119, v120
	v_pk_add_f32 v[114:115], v[122:123], v[120:121] op_sel_hi:[0,1]
	v_mul_f32_e32 v115, v122, v122
	v_pk_add_f32 v[120:121], v[124:125], v[118:119]
	v_pk_mul_f32 v[122:123], v[124:125], v[2:3]
	v_mov_b32_e32 v119, v124
	v_mov_b32_e32 v121, v123
	v_pk_add_f32 v[114:115], v[114:115], v[120:121]
	v_mul_f32_e32 v120, v118, v118
	v_pk_fma_f32 v[118:119], v[118:119], v[118:119], v[120:121] op_sel_hi:[1,1,0]
	v_lshlrev_b32_e32 v120, 16, v109
	v_lshlrev_b32_e32 v118, 16, v108
	v_and_b32_e32 v108, 0xffff0000, v108
	v_and_b32_e32 v122, 0xffff0000, v109
	v_mov_b32_e32 v3, v119
	v_mul_f32_e32 v119, v118, v118
	v_mul_f32_e32 v109, v108, v108
	v_mul_f32_e32 v121, v120, v120
	v_mul_f32_e32 v123, v122, v122
	v_pk_add_f32 v[108:109], v[118:119], v[108:109]
	v_pk_add_f32 v[118:119], v[120:121], v[122:123]
	v_pk_add_f32 v[114:115], v[114:115], v[2:3]
	v_pk_add_f32 v[108:109], v[108:109], v[118:119]
	v_lshlrev_b32_e32 v118, 16, v105
	v_pk_add_f32 v[108:109], v[114:115], v[108:109]
	v_lshlrev_b32_e32 v114, 16, v104
	v_and_b32_e32 v104, 0xffff0000, v104
	v_and_b32_e32 v120, 0xffff0000, v105
	v_mul_f32_e32 v115, v114, v114
	v_mul_f32_e32 v105, v104, v104
	v_mul_f32_e32 v119, v118, v118
	v_mul_f32_e32 v121, v120, v120
	v_pk_add_f32 v[104:105], v[114:115], v[104:105]
	v_pk_add_f32 v[114:115], v[118:119], v[120:121]
	v_pk_fma_f32 v[102:103], v[110:111], s[72:73], v[102:103] op_sel_hi:[1,0,1]
	v_pk_fma_f32 v[100:101], v[106:107], s[72:73], v[100:101] op_sel_hi:[1,0,1]
	v_pk_add_f32 v[104:105], v[104:105], v[114:115]
	v_cvt_pk_bf16_f32 v106, v100, v101
	v_cvt_pk_bf16_f32 v107, v102, v103
	v_pk_add_f32 v[104:105], v[108:109], v[104:105]
	v_lshlrev_b32_e32 v100, 16, v106
	v_and_b32_e32 v102, 0xffff0000, v106
	v_lshlrev_b32_e32 v108, 16, v107
	v_and_b32_e32 v110, 0xffff0000, v107
	v_mul_f32_e32 v101, v100, v100
	v_mul_f32_e32 v103, v102, v102
	v_mul_f32_e32 v109, v108, v108
	v_mul_f32_e32 v111, v110, v110
	v_pk_add_f32 v[100:101], v[100:101], v[102:103]
	v_pk_add_f32 v[102:103], v[108:109], v[110:111]
	v_mov_b64_e32 v[150:151], v[106:107]
	v_lshrrev_b32_e32 v152, 4, v219
	v_lshlrev_b32_e32 v152, 3, v152
	v_mov_b32_e32 v153, v2
	v_permlane32_swap_b32_e32 v148, v150
	v_permlane32_swap_b32_e32 v149, v151
	v_lshl_add_u64 v[152:153], v[152:153], 0, v[112:113]
	s_nop 0
	v_permlane16_swap_b32_e32 v148, v150
	v_permlane16_swap_b32_e32 v149, v151
	global_store_dwordx4 v[152:153], v[148:151], off offset:256 sc0
	v_pk_add_f32 v[100:101], v[100:101], v[102:103]
	s_nop 0
	v_pk_add_f32 v[100:101], v[104:105], v[100:101]
	ds_bpermute_b32 v102, v165, v100
	ds_bpermute_b32 v103, v165, v101
	s_waitcnt lgkmcnt(0)
	v_pk_add_f32 v[100:101], v[100:101], v[102:103]
	ds_bpermute_b32 v102, v164, v100
	ds_bpermute_b32 v103, v164, v101
	s_and_saveexec_b64 s[0:1], s[40:41]
	s_cbranch_execz .LBB0_1862
	v_lshl_add_u64 v[104:105], s[48:49], 0, v[116:117]
	v_lshl_add_u64 v[104:105], s[58:59], 2, v[104:105]
	s_waitcnt lgkmcnt(0)
	v_pk_add_f32 v[100:101], v[100:101], v[102:103]
	global_store_dwordx2 v[104:105], v[100:101], off

; __device__ __forceinline__ u32x2 pk4(f32x4 v) { u32x2 r; r.x = pk2(v.x, v.y); r.y = pk2(v.z, v.w); return r; }
;     __device__ __forceinline__ void operator()(const f32x4 (&acc)[2][2][4][2], const pg8::Unit& u, int wr, int wc, int fr, int fq) const {
;     ...
;                 for (int bj = 0; bj < 2; ++bj)
; #pragma unroll
;                     for (int n = 0; n < 2; ++n) {
;                         const int col = u.pn * 256 + bj * 128 + wc * 32 + n * 16 + fq * 4;
;                         const u32x2 raw = *(const u32x2*)(src + (size_t)row * DM + col);
;                         f32x4 x = (f32x4){bflo(raw.x), bfhi(raw.x), bflo(raw.y), bfhi(raw.y)};
;                         if (ln) x = (x - mu) * rs * *(const f32x4*)(g + col) + *(const f32x4*)(b + col);
;                         const u32x2 pz = pk4(x * ALPHA + acc[ai][bj][m][n]);
;                         *(u32x2*)(dst + (size_t)row * DM + col) = pz;
;                         const float z0 = bflo(pz.x), z1 = bfhi(pz.x), z2 = bflo(pz.y), z3 = bfhi(pz.y);
;                         s1 += (z0 + z1) + (z2 + z3); s2 += (z0 * z0 + z1 * z1) + (z2 * z2 + z3 * z3);
;                     }
;                 s1 += __shfl_xor(s1, 16); s2 += __shfl_xor(s2, 16); s1 += __shfl_xor(s1, 32); s2 += __shfl_xor(s2, 32);
;                 if (fq == 0) { float* p = stm_n + (size_t)row * 32 + (u.pn * 4 + wc) * 2; p[0] = s1; p[1] = s2; }
.LBB0_1867:
	v_lshlrev_b64 v[108:109], 10, v[108:109]
	v_pk_fma_f32 v[96:97], v[110:111], s[72:73], v[96:97] op_sel_hi:[1,0,1]
	v_pk_fma_f32 v[112:113], v[112:113], s[72:73], v[98:99] op_sel_hi:[1,0,1]
	v_cvt_pk_bf16_f32 v98, v96, v97
	v_lshl_add_u64 v[96:97], v[108:109], 1, s[70:71]
	v_cvt_pk_bf16_f32 v99, v112, v113
	v_lshl_add_u64 v[96:97], v[144:145], 1, v[96:97]
	v_mov_b64_e32 v[148:149], v[98:99]
	s_waitcnt vmcnt(11)
	v_mov_b64_e32 v[110:111], v[200:201]
	global_load_dwordx2 v[200:201], v243, s[46:47] offset:32
	s_and_b64 vcc, exec, s[44:45]
	s_waitcnt lgkmcnt(0)
	v_lshlrev_b32_e32 v108, 16, v110
	v_and_b32_e32 v109, 0xffff0000, v110
	v_lshlrev_b32_e32 v110, 16, v111
	v_and_b32_e32 v111, 0xffff0000, v111
	s_cbranch_vccnz .LBB0_1869
	v_sub_f32_e32 v109, v109, v103
	v_sub_f32_e32 v108, v108, v103
	v_sub_f32_e32 v111, v111, v103
	v_sub_f32_e32 v110, v110, v103
	v_pk_mul_f32 v[116:117], v[104:105], v[108:109]
	v_mov_b32_e32 v108, v104
	v_mov_b32_e32 v109, v104
	v_pk_mul_f32 v[118:119], v[108:109], v[110:111]
	ds_read_b128 v[108:111], v244 offset:64
	ds_read_b128 v[112:115], v244 offset:320
	s_waitcnt lgkmcnt(0)
	v_pk_fma_f32 v[110:111], v[118:119], v[110:111], v[114:115]
	v_pk_fma_f32 v[108:109], v[116:117], v[108:109], v[112:113]
.LBB0_1869:
	v_pk_fma_f32 v[94:95], v[110:111], s[72:73], v[94:95] op_sel_hi:[1,0,1]
	v_pk_fma_f32 v[92:93], v[108:109], s[72:73], v[92:93] op_sel_hi:[1,0,1]
	s_and_b64 vcc, exec, s[44:45]
	v_cvt_pk_bf16_f32 v92, v92, v93
	v_cvt_pk_bf16_f32 v93, v94, v95
	v_mov_b64_e32 v[150:151], v[92:93]
	v_lshrrev_b32_e32 v152, 4, v219
	v_lshlrev_b32_e32 v152, 3, v152
	v_mov_b32_e32 v153, v2
	v_permlane32_swap_b32_e32 v148, v150
	v_permlane32_swap_b32_e32 v149, v151
	v_lshl_add_u64 v[152:153], v[152:153], 0, v[96:97]
	s_nop 0
	v_permlane16_swap_b32_e32 v148, v150
	v_permlane16_swap_b32_e32 v149, v151
	global_store_dwordx4 v[152:153], v[148:151], off sc0
	s_waitcnt vmcnt(11)
	v_mov_b64_e32 v[108:109], v[202:203]
	global_load_dwordx2 v[202:203], v243, s[46:47] offset:256
	s_waitcnt lgkmcnt(0)
	v_lshlrev_b32_e32 v94, 16, v108
	v_and_b32_e32 v95, 0xffff0000, v108
	v_lshlrev_b32_e32 v108, 16, v109
	v_and_b32_e32 v109, 0xffff0000, v109
	s_cbranch_vccnz .LBB0_1871
	v_sub_f32_e32 v109, v109, v103
	v_sub_f32_e32 v108, v108, v103
	v_mov_b32_e32 v110, v104
	v_mov_b32_e32 v111, v104
	v_pk_mul_f32 v[108:109], v[110:111], v[108:109]
	ds_read_b128 v[110:113], v244 offset:128
	ds_read_b128 v[114:117], v244 offset:384
	v_sub_f32_e32 v95, v95, v103
	v_sub_f32_e32 v94, v94, v103
	v_pk_mul_f32 v[94:95], v[104:105], v[94:95]
	s_waitcnt lgkmcnt(0)
	v_pk_fma_f32 v[108:109], v[108:109], v[112:113], v[116:117]
	v_pk_fma_f32 v[94:95], v[94:95], v[110:111], v[114:115]
.LBB0_1871:
	v_pk_fma_f32 v[90:91], v[108:109], s[72:73], v[90:91] op_sel_hi:[1,0,1]
	v_pk_fma_f32 v[88:89], v[94:95], s[72:73], v[88:89] op_sel_hi:[1,0,1]
	s_and_b64 vcc, exec, s[44:45]
	v_cvt_pk_bf16_f32 v88, v88, v89
	v_cvt_pk_bf16_f32 v89, v90, v91
	v_mov_b64_e32 v[148:149], v[88:89]
	s_waitcnt vmcnt(11)
	v_mov_b64_e32 v[94:95], v[204:205]
	global_load_dwordx2 v[204:205], v243, s[46:47] offset:288
	s_waitcnt lgkmcnt(0)
	v_lshlrev_b32_e32 v90, 16, v94
	v_and_b32_e32 v91, 0xffff0000, v94
	v_lshlrev_b32_e32 v94, 16, v95
	v_and_b32_e32 v95, 0xffff0000, v95
	s_cbranch_vccnz .LBB0_1873
	v_sub_f32_e32 v91, v91, v103
	v_sub_f32_e32 v90, v90, v103
	v_sub_f32_e32 v95, v95, v103
	v_sub_f32_e32 v94, v94, v103
	v_pk_mul_f32 v[90:91], v[104:105], v[90:91]
	v_mov_b32_e32 v105, v104
	v_pk_mul_f32 v[94:95], v[104:105], v[94:95]
	ds_read_b128 v[102:105], v244 offset:192
	ds_read_b128 v[106:109], v244 offset:448
	s_waitcnt lgkmcnt(0)
	v_pk_fma_f32 v[94:95], v[94:95], v[104:105], v[108:109]
	v_pk_fma_f32 v[90:91], v[90:91], v[102:103], v[106:107]
.LBB0_1873:
	v_and_b32_e32 v105, 16, v98
	v_and_b32_e32 v104, 0xffff0000, v98
	v_lshlrev_b32_e32 v106, 16, v98
	v_lshlrev_b32_e32 v102, 16, v99
	v_and_b32_e32 v109, 0xffff0000, v98
	v_and_b32_e32 v108, 0xffff0000, v99
	v_mov_b32_e32 v3, v104
	v_mov_b32_e32 v103, v104
	v_pk_add_f32 v[98:99], v[106:107], v[104:105] op_sel_hi:[0,1]
	v_mul_f32_e32 v99, v106, v106
	v_pk_add_f32 v[104:105], v[108:109], v[102:103]
	v_pk_mul_f32 v[106:107], v[108:109], v[2:3]
	v_mov_b32_e32 v103, v108
	v_mov_b32_e32 v105, v107
	v_pk_add_f32 v[98:99], v[98:99], v[104:105]
	v_mul_f32_e32 v104, v102, v102
	v_pk_fma_f32 v[102:103], v[102:103], v[102:103], v[104:105] op_sel_hi:[1,1,0]
	v_lshlrev_b32_e32 v104, 16, v93
	v_lshlrev_b32_e32 v102, 16, v92
	v_and_b32_e32 v92, 0xffff0000, v92
	v_and_b32_e32 v106, 0xffff0000, v93
	v_mov_b32_e32 v3, v103
	v_mul_f32_e32 v103, v102, v102
	v_mul_f32_e32 v93, v92, v92
	v_mul_f32_e32 v105, v104, v104
	v_mul_f32_e32 v107, v106, v106
	v_pk_add_f32 v[92:93], v[102:103], v[92:93]
	v_pk_add_f32 v[102:103], v[104:105], v[106:107]
	v_pk_add_f32 v[98:99], v[98:99], v[2:3]
	v_pk_add_f32 v[92:93], v[92:93], v[102:103]
	v_lshlrev_b32_e32 v102, 16, v89
	v_pk_add_f32 v[92:93], v[98:99], v[92:93]
	v_lshlrev_b32_e32 v98, 16, v88
	v_and_b32_e32 v88, 0xffff0000, v88
	v_and_b32_e32 v104, 0xffff0000, v89
	v_mul_f32_e32 v99, v98, v98
	v_mul_f32_e32 v89, v88, v88
	v_mul_f32_e32 v103, v102, v102
	v_mul_f32_e32 v105, v104, v104
	v_pk_add_f32 v[88:89], v[98:99], v[88:89]
	v_pk_add_f32 v[98:99], v[102:103], v[104:105]
	v_pk_fma_f32 v[86:87], v[94:95], s[72:73], v[86:87] op_sel_hi:[1,0,1]
	v_pk_fma_f32 v[84:85], v[90:91], s[72:73], v[84:85] op_sel_hi:[1,0,1]
	v_pk_add_f32 v[88:89], v[88:89], v[98:99]
	v_cvt_pk_bf16_f32 v90, v84, v85
	v_cvt_pk_bf16_f32 v91, v86, v87
	v_pk_add_f32 v[88:89], v[92:93], v[88:89]
	v_lshlrev_b32_e32 v84, 16, v90
	v_and_b32_e32 v86, 0xffff0000, v90
	v_lshlrev_b32_e32 v92, 16, v91
	v_and_b32_e32 v94, 0xffff0000, v91
	v_mul_f32_e32 v85, v84, v84
	v_mul_f32_e32 v87, v86, v86
	v_mul_f32_e32 v93, v92, v92
	v_mul_f32_e32 v95, v94, v94
	v_pk_add_f32 v[84:85], v[84:85], v[86:87]
	v_pk_add_f32 v[86:87], v[92:93], v[94:95]
	v_mov_b64_e32 v[150:151], v[90:91]
	v_lshrrev_b32_e32 v152, 4, v219
	v_lshlrev_b32_e32 v152, 3, v152
	v_mov_b32_e32 v153, v2
	v_permlane32_swap_b32_e32 v148, v150
	v_permlane32_swap_b32_e32 v149, v151
	v_lshl_add_u64 v[152:153], v[152:153], 0, v[96:97]
	s_nop 0
	v_permlane16_swap_b32_e32 v148, v150
	v_permlane16_swap_b32_e32 v149, v151
	global_store_dwordx4 v[152:153], v[148:151], off offset:256 sc0
	v_pk_add_f32 v[84:85], v[84:85], v[86:87]
	s_nop 0
	v_pk_add_f32 v[84:85], v[88:89], v[84:85]
	ds_bpermute_b32 v86, v165, v84
	ds_bpermute_b32 v87, v165, v85
	s_waitcnt lgkmcnt(0)
	v_pk_add_f32 v[84:85], v[84:85], v[86:87]
	ds_bpermute_b32 v86, v164, v84
	ds_bpermute_b32 v87, v164, v85
	s_and_saveexec_b64 s[0:1], s[40:41]
	s_cbranch_execz .LBB0_1875
	v_lshl_add_u64 v[88:89], s[48:49], 0, v[100:101]
	v_lshl_add_u64 v[88:89], s[58:59], 2, v[88:89]
	s_waitcnt lgkmcnt(0)
	v_pk_add_f32 v[84:85], v[84:85], v[86:87]
	global_store_dwordx2 v[88:89], v[84:85], off

; __device__ __forceinline__ u32x2 pk4(f32x4 v) { u32x2 r; r.x = pk2(v.x, v.y); r.y = pk2(v.z, v.w); return r; }
;     __device__ __forceinline__ void operator()(const f32x4 (&acc)[2][2][4][2], const pg8::Unit& u, int wr, int wc, int fr, int fq) const {
;     ...
;                 for (int bj = 0; bj < 2; ++bj)
; #pragma unroll
;                     for (int n = 0; n < 2; ++n) {
;                         const int col = u.pn * 256 + bj * 128 + wc * 32 + n * 16 + fq * 4;
;                         const u32x2 raw = *(const u32x2*)(src + (size_t)row * DM + col);
;                         f32x4 x = (f32x4){bflo(raw.x), bfhi(raw.x), bflo(raw.y), bfhi(raw.y)};
;                         if (ln) x = (x - mu) * rs * *(const f32x4*)(g + col) + *(const f32x4*)(b + col);
;                         const u32x2 pz = pk4(x * ALPHA + acc[ai][bj][m][n]);
;                         *(u32x2*)(dst + (size_t)row * DM + col) = pz;
;                         const float z0 = bflo(pz.x), z1 = bfhi(pz.x), z2 = bflo(pz.y), z3 = bfhi(pz.y);
;                         s1 += (z0 + z1) + (z2 + z3); s2 += (z0 * z0 + z1 * z1) + (z2 * z2 + z3 * z3);
;                     }
;                 s1 += __shfl_xor(s1, 16); s2 += __shfl_xor(s2, 16); s1 += __shfl_xor(s1, 32); s2 += __shfl_xor(s2, 32);
;                 if (fq == 0) { float* p = stm_n + (size_t)row * 32 + (u.pn * 4 + wc) * 2; p[0] = s1; p[1] = s2; }
.LBB0_1880:
	v_lshlrev_b64 v[92:93], 10, v[92:93]
	v_pk_fma_f32 v[80:81], v[94:95], s[72:73], v[80:81] op_sel_hi:[1,0,1]
	v_pk_fma_f32 v[96:97], v[96:97], s[72:73], v[82:83] op_sel_hi:[1,0,1]
	v_cvt_pk_bf16_f32 v82, v80, v81
	v_lshl_add_u64 v[80:81], v[92:93], 1, s[70:71]
	v_cvt_pk_bf16_f32 v83, v96, v97
	v_lshl_add_u64 v[80:81], v[144:145], 1, v[80:81]
	v_mov_b64_e32 v[148:149], v[82:83]
	s_waitcnt vmcnt(11)
	v_mov_b64_e32 v[94:95], v[236:237]
	global_load_dwordx2 v[236:237], v243, s[46:47] offset:32
	s_and_b64 vcc, exec, s[44:45]
	s_waitcnt lgkmcnt(0)
	v_lshlrev_b32_e32 v92, 16, v94
	v_and_b32_e32 v93, 0xffff0000, v94
	v_lshlrev_b32_e32 v94, 16, v95
	v_and_b32_e32 v95, 0xffff0000, v95
	s_cbranch_vccnz .LBB0_1882
	v_sub_f32_e32 v93, v93, v87
	v_sub_f32_e32 v92, v92, v87
	v_sub_f32_e32 v95, v95, v87
	v_sub_f32_e32 v94, v94, v87
	v_pk_mul_f32 v[100:101], v[88:89], v[92:93]
	v_mov_b32_e32 v92, v88
	v_mov_b32_e32 v93, v88
	v_pk_mul_f32 v[102:103], v[92:93], v[94:95]
	ds_read_b128 v[92:95], v244 offset:64
	ds_read_b128 v[96:99], v244 offset:320
	s_waitcnt lgkmcnt(0)
	v_pk_fma_f32 v[94:95], v[102:103], v[94:95], v[98:99]
	v_pk_fma_f32 v[92:93], v[100:101], v[92:93], v[96:97]
.LBB0_1882:
	v_pk_fma_f32 v[78:79], v[94:95], s[72:73], v[78:79] op_sel_hi:[1,0,1]
	v_pk_fma_f32 v[76:77], v[92:93], s[72:73], v[76:77] op_sel_hi:[1,0,1]
	s_and_b64 vcc, exec, s[44:45]
	v_cvt_pk_bf16_f32 v76, v76, v77
	v_cvt_pk_bf16_f32 v77, v78, v79
	v_mov_b64_e32 v[150:151], v[76:77]
	v_lshrrev_b32_e32 v152, 4, v219
	v_lshlrev_b32_e32 v152, 3, v152
	v_mov_b32_e32 v153, v2
	v_permlane32_swap_b32_e32 v148, v150
	v_permlane32_swap_b32_e32 v149, v151
	v_lshl_add_u64 v[152:153], v[152:153], 0, v[80:81]
	s_nop 0
	v_permlane16_swap_b32_e32 v148, v150
	v_permlane16_swap_b32_e32 v149, v151
	global_store_dwordx4 v[152:153], v[148:151], off sc0
	s_waitcnt vmcnt(11)
	v_mov_b64_e32 v[92:93], v[238:239]
	global_load_dwordx2 v[238:239], v243, s[46:47] offset:256
	s_waitcnt lgkmcnt(0)
	v_lshlrev_b32_e32 v78, 16, v92
	v_and_b32_e32 v79, 0xffff0000, v92
	v_lshlrev_b32_e32 v92, 16, v93
	v_and_b32_e32 v93, 0xffff0000, v93
	s_cbranch_vccnz .LBB0_1884
	v_sub_f32_e32 v93, v93, v87
	v_sub_f32_e32 v92, v92, v87
	v_mov_b32_e32 v94, v88
	v_mov_b32_e32 v95, v88
	v_pk_mul_f32 v[92:93], v[94:95], v[92:93]
	ds_read_b128 v[94:97], v244 offset:128
	ds_read_b128 v[98:101], v244 offset:384
	v_sub_f32_e32 v79, v79, v87
	v_sub_f32_e32 v78, v78, v87
	v_pk_mul_f32 v[78:79], v[88:89], v[78:79]
	s_waitcnt lgkmcnt(0)
	v_pk_fma_f32 v[92:93], v[92:93], v[96:97], v[100:101]
	v_pk_fma_f32 v[78:79], v[78:79], v[94:95], v[98:99]
.LBB0_1884:
	v_pk_fma_f32 v[74:75], v[92:93], s[72:73], v[74:75] op_sel_hi:[1,0,1]
	v_pk_fma_f32 v[72:73], v[78:79], s[72:73], v[72:73] op_sel_hi:[1,0,1]
	s_and_b64 vcc, exec, s[44:45]
	v_cvt_pk_bf16_f32 v72, v72, v73
	v_cvt_pk_bf16_f32 v73, v74, v75
	v_mov_b64_e32 v[148:149], v[72:73]
	s_waitcnt vmcnt(11)
	v_mov_b64_e32 v[78:79], v[240:241]
	global_load_dwordx2 v[240:241], v243, s[46:47] offset:288
	s_waitcnt lgkmcnt(0)
	v_lshlrev_b32_e32 v74, 16, v78
	v_and_b32_e32 v75, 0xffff0000, v78
	v_lshlrev_b32_e32 v78, 16, v79
	v_and_b32_e32 v79, 0xffff0000, v79
	s_cbranch_vccnz .LBB0_1886
	v_sub_f32_e32 v75, v75, v87
	v_sub_f32_e32 v74, v74, v87
	v_sub_f32_e32 v79, v79, v87
	v_sub_f32_e32 v78, v78, v87
	v_pk_mul_f32 v[74:75], v[88:89], v[74:75]
	v_mov_b32_e32 v89, v88
	v_pk_mul_f32 v[78:79], v[88:89], v[78:79]
	ds_read_b128 v[86:89], v244 offset:192
	ds_read_b128 v[90:93], v244 offset:448
	s_waitcnt lgkmcnt(0)
	v_pk_fma_f32 v[78:79], v[78:79], v[88:89], v[92:93]
	v_pk_fma_f32 v[74:75], v[74:75], v[86:87], v[90:91]
.LBB0_1886:
	v_and_b32_e32 v89, 16, v82
	v_and_b32_e32 v88, 0xffff0000, v82
	v_lshlrev_b32_e32 v90, 16, v82
	v_lshlrev_b32_e32 v86, 16, v83
	v_and_b32_e32 v93, 0xffff0000, v82
	v_and_b32_e32 v92, 0xffff0000, v83
	v_mov_b32_e32 v3, v88
	v_mov_b32_e32 v87, v88
	v_pk_add_f32 v[82:83], v[90:91], v[88:89] op_sel_hi:[0,1]
	v_mul_f32_e32 v83, v90, v90
	v_pk_add_f32 v[88:89], v[92:93], v[86:87]
	v_pk_mul_f32 v[90:91], v[92:93], v[2:3]
	v_mov_b32_e32 v87, v92
	v_mov_b32_e32 v89, v91
	v_pk_add_f32 v[82:83], v[82:83], v[88:89]
	v_mul_f32_e32 v88, v86, v86
	v_pk_fma_f32 v[86:87], v[86:87], v[86:87], v[88:89] op_sel_hi:[1,1,0]
	v_lshlrev_b32_e32 v88, 16, v77
	v_lshlrev_b32_e32 v86, 16, v76
	v_and_b32_e32 v76, 0xffff0000, v76
	v_and_b32_e32 v90, 0xffff0000, v77
	v_mov_b32_e32 v3, v87
	v_mul_f32_e32 v87, v86, v86
	v_mul_f32_e32 v77, v76, v76
	v_mul_f32_e32 v89, v88, v88
	v_mul_f32_e32 v91, v90, v90
	v_pk_add_f32 v[76:77], v[86:87], v[76:77]
	v_pk_add_f32 v[86:87], v[88:89], v[90:91]
	v_pk_add_f32 v[82:83], v[82:83], v[2:3]
	v_pk_add_f32 v[76:77], v[76:77], v[86:87]
	v_lshlrev_b32_e32 v86, 16, v73
	v_pk_add_f32 v[76:77], v[82:83], v[76:77]
	v_lshlrev_b32_e32 v82, 16, v72
	v_and_b32_e32 v72, 0xffff0000, v72
	v_and_b32_e32 v88, 0xffff0000, v73
	v_mul_f32_e32 v83, v82, v82
	v_mul_f32_e32 v73, v72, v72
	v_mul_f32_e32 v87, v86, v86
	v_mul_f32_e32 v89, v88, v88
	v_pk_add_f32 v[72:73], v[82:83], v[72:73]
	v_pk_add_f32 v[82:83], v[86:87], v[88:89]
	v_pk_fma_f32 v[70:71], v[78:79], s[72:73], v[70:71] op_sel_hi:[1,0,1]
	v_pk_fma_f32 v[68:69], v[74:75], s[72:73], v[68:69] op_sel_hi:[1,0,1]
	v_pk_add_f32 v[72:73], v[72:73], v[82:83]
	v_cvt_pk_bf16_f32 v74, v68, v69
	v_cvt_pk_bf16_f32 v75, v70, v71
	v_pk_add_f32 v[72:73], v[76:77], v[72:73]
	v_lshlrev_b32_e32 v68, 16, v74
	v_and_b32_e32 v70, 0xffff0000, v74
	v_lshlrev_b32_e32 v76, 16, v75
	v_and_b32_e32 v78, 0xffff0000, v75
	v_mul_f32_e32 v69, v68, v68
	v_mul_f32_e32 v71, v70, v70
	v_mul_f32_e32 v77, v76, v76
	v_mul_f32_e32 v79, v78, v78
	v_pk_add_f32 v[68:69], v[68:69], v[70:71]
	v_pk_add_f32 v[70:71], v[76:77], v[78:79]
	v_mov_b64_e32 v[150:151], v[74:75]
	v_lshrrev_b32_e32 v152, 4, v219
	v_lshlrev_b32_e32 v152, 3, v152
	v_mov_b32_e32 v153, v2
	v_permlane32_swap_b32_e32 v148, v150
	v_permlane32_swap_b32_e32 v149, v151
	v_lshl_add_u64 v[152:153], v[152:153], 0, v[80:81]
	s_nop 0
	v_permlane16_swap_b32_e32 v148, v150
	v_permlane16_swap_b32_e32 v149, v151
	global_store_dwordx4 v[152:153], v[148:151], off offset:256 sc0
	v_pk_add_f32 v[68:69], v[68:69], v[70:71]
	s_nop 0
	v_pk_add_f32 v[68:69], v[72:73], v[68:69]
	ds_bpermute_b32 v70, v165, v68
	ds_bpermute_b32 v71, v165, v69
	s_waitcnt lgkmcnt(0)
	v_pk_add_f32 v[68:69], v[68:69], v[70:71]
	ds_bpermute_b32 v70, v164, v68
	ds_bpermute_b32 v71, v164, v69
	s_and_saveexec_b64 s[0:1], s[40:41]
	s_cbranch_execz .LBB0_1888
	v_lshl_add_u64 v[72:73], s[48:49], 0, v[84:85]
	v_lshl_add_u64 v[72:73], s[58:59], 2, v[72:73]
	s_waitcnt lgkmcnt(0)
	v_pk_add_f32 v[68:69], v[68:69], v[70:71]
	global_store_dwordx2 v[72:73], v[68:69], off

; __device__ __forceinline__ u32x2 pk4(f32x4 v) { u32x2 r; r.x = pk2(v.x, v.y); r.y = pk2(v.z, v.w); return r; }
;     __device__ __forceinline__ void operator()(const f32x4 (&acc)[2][2][4][2], const pg8::Unit& u, int wr, int wc, int fr, int fq) const {
;     ...
;                 for (int bj = 0; bj < 2; ++bj)
; #pragma unroll
;                     for (int n = 0; n < 2; ++n) {
;                         const int col = u.pn * 256 + bj * 128 + wc * 32 + n * 16 + fq * 4;
;                         const u32x2 raw = *(const u32x2*)(src + (size_t)row * DM + col);
;                         f32x4 x = (f32x4){bflo(raw.x), bfhi(raw.x), bflo(raw.y), bfhi(raw.y)};
;                         if (ln) x = (x - mu) * rs * *(const f32x4*)(g + col) + *(const f32x4*)(b + col);
;                         const u32x2 pz = pk4(x * ALPHA + acc[ai][bj][m][n]);
;                         *(u32x2*)(dst + (size_t)row * DM + col) = pz;
;                         const float z0 = bflo(pz.x), z1 = bfhi(pz.x), z2 = bflo(pz.y), z3 = bfhi(pz.y);
;                         s1 += (z0 + z1) + (z2 + z3); s2 += (z0 * z0 + z1 * z1) + (z2 * z2 + z3 * z3);
;                     }
;                 s1 += __shfl_xor(s1, 16); s2 += __shfl_xor(s2, 16); s1 += __shfl_xor(s1, 32); s2 += __shfl_xor(s2, 32);
;                 if (fq == 0) { float* p = stm_n + (size_t)row * 32 + (u.pn * 4 + wc) * 2; p[0] = s1; p[1] = s2; }
.LBB0_1893:
	v_lshlrev_b64 v[76:77], 10, v[76:77]
	v_pk_fma_f32 v[64:65], v[78:79], s[72:73], v[64:65] op_sel_hi:[1,0,1]
	v_pk_fma_f32 v[80:81], v[80:81], s[72:73], v[66:67] op_sel_hi:[1,0,1]
	v_cvt_pk_bf16_f32 v66, v64, v65
	v_lshl_add_u64 v[64:65], v[76:77], 1, s[70:71]
	v_cvt_pk_bf16_f32 v67, v80, v81
	v_lshl_add_u64 v[64:65], v[144:145], 1, v[64:65]
	v_mov_b64_e32 v[148:149], v[66:67]
	s_waitcnt vmcnt(11)
	v_mov_b64_e32 v[78:79], v[200:201]
	global_load_dwordx2 v[200:201], v243, s[46:47] offset:32
	s_and_b64 vcc, exec, s[44:45]
	s_waitcnt lgkmcnt(0)
	v_lshlrev_b32_e32 v76, 16, v78
	v_and_b32_e32 v77, 0xffff0000, v78
	v_lshlrev_b32_e32 v78, 16, v79
	v_and_b32_e32 v79, 0xffff0000, v79
	s_cbranch_vccnz .LBB0_1895
	v_sub_f32_e32 v77, v77, v71
	v_sub_f32_e32 v76, v76, v71
	v_sub_f32_e32 v79, v79, v71
	v_sub_f32_e32 v78, v78, v71
	v_pk_mul_f32 v[84:85], v[72:73], v[76:77]
	v_mov_b32_e32 v76, v72
	v_mov_b32_e32 v77, v72
	v_pk_mul_f32 v[86:87], v[76:77], v[78:79]
	ds_read_b128 v[76:79], v244 offset:64
	ds_read_b128 v[80:83], v244 offset:320
	s_waitcnt lgkmcnt(0)
	v_pk_fma_f32 v[78:79], v[86:87], v[78:79], v[82:83]
	v_pk_fma_f32 v[76:77], v[84:85], v[76:77], v[80:81]
.LBB0_1895:
	v_pk_fma_f32 v[62:63], v[78:79], s[72:73], v[62:63] op_sel_hi:[1,0,1]
	v_pk_fma_f32 v[60:61], v[76:77], s[72:73], v[60:61] op_sel_hi:[1,0,1]
	s_and_b64 vcc, exec, s[44:45]
	v_cvt_pk_bf16_f32 v60, v60, v61
	v_cvt_pk_bf16_f32 v61, v62, v63
	v_mov_b64_e32 v[150:151], v[60:61]
	v_lshrrev_b32_e32 v152, 4, v219
	v_lshlrev_b32_e32 v152, 3, v152
	v_mov_b32_e32 v153, v2
	v_permlane32_swap_b32_e32 v148, v150
	v_permlane32_swap_b32_e32 v149, v151
	v_lshl_add_u64 v[152:153], v[152:153], 0, v[64:65]
	s_nop 0
	v_permlane16_swap_b32_e32 v148, v150
	v_permlane16_swap_b32_e32 v149, v151
	global_store_dwordx4 v[152:153], v[148:151], off sc0
	s_waitcnt vmcnt(11)
	v_mov_b64_e32 v[76:77], v[202:203]
	global_load_dwordx2 v[202:203], v243, s[46:47] offset:256
	s_waitcnt lgkmcnt(0)
	v_lshlrev_b32_e32 v62, 16, v76
	v_and_b32_e32 v63, 0xffff0000, v76
	v_lshlrev_b32_e32 v76, 16, v77
	v_and_b32_e32 v77, 0xffff0000, v77
	s_cbranch_vccnz .LBB0_1897
	v_sub_f32_e32 v77, v77, v71
	v_sub_f32_e32 v76, v76, v71
	v_mov_b32_e32 v78, v72
	v_mov_b32_e32 v79, v72
	v_pk_mul_f32 v[76:77], v[78:79], v[76:77]
	ds_read_b128 v[78:81], v244 offset:128
	ds_read_b128 v[82:85], v244 offset:384
	v_sub_f32_e32 v63, v63, v71
	v_sub_f32_e32 v62, v62, v71
	v_pk_mul_f32 v[62:63], v[72:73], v[62:63]
	s_waitcnt lgkmcnt(0)
	v_pk_fma_f32 v[76:77], v[76:77], v[80:81], v[84:85]
	v_pk_fma_f32 v[62:63], v[62:63], v[78:79], v[82:83]
.LBB0_1897:
	v_pk_fma_f32 v[58:59], v[76:77], s[72:73], v[58:59] op_sel_hi:[1,0,1]
	v_pk_fma_f32 v[56:57], v[62:63], s[72:73], v[56:57] op_sel_hi:[1,0,1]
	s_and_b64 vcc, exec, s[44:45]
	v_cvt_pk_bf16_f32 v56, v56, v57
	v_cvt_pk_bf16_f32 v57, v58, v59
	v_mov_b64_e32 v[148:149], v[56:57]
	s_waitcnt vmcnt(11)
	v_mov_b64_e32 v[62:63], v[204:205]
	global_load_dwordx2 v[204:205], v243, s[46:47] offset:288
	s_waitcnt lgkmcnt(0)
	v_lshlrev_b32_e32 v58, 16, v62
	v_and_b32_e32 v59, 0xffff0000, v62
	v_lshlrev_b32_e32 v62, 16, v63
	v_and_b32_e32 v63, 0xffff0000, v63
	s_cbranch_vccnz .LBB0_1899
	v_sub_f32_e32 v59, v59, v71
	v_sub_f32_e32 v58, v58, v71
	v_sub_f32_e32 v63, v63, v71
	v_sub_f32_e32 v62, v62, v71
	v_pk_mul_f32 v[58:59], v[72:73], v[58:59]
	v_mov_b32_e32 v73, v72
	v_pk_mul_f32 v[62:63], v[72:73], v[62:63]
	ds_read_b128 v[70:73], v244 offset:192
	ds_read_b128 v[74:77], v244 offset:448
	s_waitcnt lgkmcnt(0)
	v_pk_fma_f32 v[62:63], v[62:63], v[72:73], v[76:77]
	v_pk_fma_f32 v[58:59], v[58:59], v[70:71], v[74:75]
.LBB0_1899:
	v_and_b32_e32 v73, 16, v66
	v_and_b32_e32 v72, 0xffff0000, v66
	v_lshlrev_b32_e32 v74, 16, v66
	v_lshlrev_b32_e32 v70, 16, v67
	v_and_b32_e32 v77, 0xffff0000, v66
	v_and_b32_e32 v76, 0xffff0000, v67
	v_mov_b32_e32 v3, v72
	v_mov_b32_e32 v71, v72
	v_pk_add_f32 v[66:67], v[74:75], v[72:73] op_sel_hi:[0,1]
	v_mul_f32_e32 v67, v74, v74
	v_pk_add_f32 v[72:73], v[76:77], v[70:71]
	v_pk_mul_f32 v[74:75], v[76:77], v[2:3]
	v_mov_b32_e32 v71, v76
	v_mov_b32_e32 v73, v75
	v_pk_add_f32 v[66:67], v[66:67], v[72:73]
	v_mul_f32_e32 v72, v70, v70
	v_pk_fma_f32 v[70:71], v[70:71], v[70:71], v[72:73] op_sel_hi:[1,1,0]
	v_lshlrev_b32_e32 v72, 16, v61
	v_lshlrev_b32_e32 v70, 16, v60
	v_and_b32_e32 v60, 0xffff0000, v60
	v_and_b32_e32 v74, 0xffff0000, v61
	v_mov_b32_e32 v3, v71
	v_mul_f32_e32 v71, v70, v70
	v_mul_f32_e32 v61, v60, v60
	v_mul_f32_e32 v73, v72, v72
	v_mul_f32_e32 v75, v74, v74
	v_pk_add_f32 v[60:61], v[70:71], v[60:61]
	v_pk_add_f32 v[70:71], v[72:73], v[74:75]
	v_pk_add_f32 v[66:67], v[66:67], v[2:3]
	v_pk_add_f32 v[60:61], v[60:61], v[70:71]
	v_lshlrev_b32_e32 v70, 16, v57
	v_pk_add_f32 v[60:61], v[66:67], v[60:61]
	v_lshlrev_b32_e32 v66, 16, v56
	v_and_b32_e32 v56, 0xffff0000, v56
	v_and_b32_e32 v72, 0xffff0000, v57
	v_mul_f32_e32 v67, v66, v66
	v_mul_f32_e32 v57, v56, v56
	v_mul_f32_e32 v71, v70, v70
	v_mul_f32_e32 v73, v72, v72
	v_pk_add_f32 v[56:57], v[66:67], v[56:57]
	v_pk_add_f32 v[66:67], v[70:71], v[72:73]
	v_pk_fma_f32 v[54:55], v[62:63], s[72:73], v[54:55] op_sel_hi:[1,0,1]
	v_pk_fma_f32 v[52:53], v[58:59], s[72:73], v[52:53] op_sel_hi:[1,0,1]
	v_pk_add_f32 v[56:57], v[56:57], v[66:67]
	v_cvt_pk_bf16_f32 v58, v52, v53
	v_cvt_pk_bf16_f32 v59, v54, v55
	v_pk_add_f32 v[56:57], v[60:61], v[56:57]
	v_lshlrev_b32_e32 v52, 16, v58
	v_and_b32_e32 v54, 0xffff0000, v58
	v_lshlrev_b32_e32 v60, 16, v59
	v_and_b32_e32 v62, 0xffff0000, v59
	v_mul_f32_e32 v53, v52, v52
	v_mul_f32_e32 v55, v54, v54
	v_mul_f32_e32 v61, v60, v60
	v_mul_f32_e32 v63, v62, v62
	v_pk_add_f32 v[52:53], v[52:53], v[54:55]
	v_pk_add_f32 v[54:55], v[60:61], v[62:63]
	v_mov_b64_e32 v[150:151], v[58:59]
	v_lshrrev_b32_e32 v152, 4, v219
	v_lshlrev_b32_e32 v152, 3, v152
	v_mov_b32_e32 v153, v2
	v_permlane32_swap_b32_e32 v148, v150
	v_permlane32_swap_b32_e32 v149, v151
	v_lshl_add_u64 v[152:153], v[152:153], 0, v[64:65]
	s_nop 0
	v_permlane16_swap_b32_e32 v148, v150
	v_permlane16_swap_b32_e32 v149, v151
	global_store_dwordx4 v[152:153], v[148:151], off offset:256 sc0
	v_pk_add_f32 v[52:53], v[52:53], v[54:55]
	s_nop 0
	v_pk_add_f32 v[52:53], v[56:57], v[52:53]
	ds_bpermute_b32 v54, v165, v52
	ds_bpermute_b32 v55, v165, v53
	s_waitcnt lgkmcnt(0)
	v_pk_add_f32 v[52:53], v[52:53], v[54:55]
	ds_bpermute_b32 v54, v164, v52
	ds_bpermute_b32 v55, v164, v53
	s_and_saveexec_b64 s[0:1], s[40:41]
	s_cbranch_execz .LBB0_1901
	v_lshl_add_u64 v[56:57], s[48:49], 0, v[68:69]
	v_lshl_add_u64 v[56:57], s[58:59], 2, v[56:57]
	s_waitcnt lgkmcnt(0)
	v_pk_add_f32 v[52:53], v[52:53], v[54:55]
	global_store_dwordx2 v[56:57], v[52:53], off

; __device__ __forceinline__ u32x2 pk4(f32x4 v) { u32x2 r; r.x = pk2(v.x, v.y); r.y = pk2(v.z, v.w); return r; }
;     __device__ __forceinline__ void operator()(const f32x4 (&acc)[2][2][4][2], const pg8::Unit& u, int wr, int wc, int fr, int fq) const {
;     ...
;                 for (int bj = 0; bj < 2; ++bj)
; #pragma unroll
;                     for (int n = 0; n < 2; ++n) {
;                         const int col = u.pn * 256 + bj * 128 + wc * 32 + n * 16 + fq * 4;
;                         const u32x2 raw = *(const u32x2*)(src + (size_t)row * DM + col);
;                         f32x4 x = (f32x4){bflo(raw.x), bfhi(raw.x), bflo(raw.y), bfhi(raw.y)};
;                         if (ln) x = (x - mu) * rs * *(const f32x4*)(g + col) + *(const f32x4*)(b + col);
;                         const u32x2 pz = pk4(x * ALPHA + acc[ai][bj][m][n]);
;                         *(u32x2*)(dst + (size_t)row * DM + col) = pz;
;                         const float z0 = bflo(pz.x), z1 = bfhi(pz.x), z2 = bflo(pz.y), z3 = bfhi(pz.y);
;                         s1 += (z0 + z1) + (z2 + z3); s2 += (z0 * z0 + z1 * z1) + (z2 * z2 + z3 * z3);
;                     }
;                 s1 += __shfl_xor(s1, 16); s2 += __shfl_xor(s2, 16); s1 += __shfl_xor(s1, 32); s2 += __shfl_xor(s2, 32);
;                 if (fq == 0) { float* p = stm_n + (size_t)row * 32 + (u.pn * 4 + wc) * 2; p[0] = s1; p[1] = s2; }
.LBB0_1906:
	v_lshlrev_b64 v[60:61], 10, v[60:61]
	v_pk_fma_f32 v[48:49], v[62:63], s[72:73], v[48:49] op_sel_hi:[1,0,1]
	v_pk_fma_f32 v[64:65], v[64:65], s[72:73], v[50:51] op_sel_hi:[1,0,1]
	v_cvt_pk_bf16_f32 v50, v48, v49
	v_lshl_add_u64 v[48:49], v[60:61], 1, s[70:71]
	v_cvt_pk_bf16_f32 v51, v64, v65
	v_lshl_add_u64 v[48:49], v[144:145], 1, v[48:49]
	v_mov_b64_e32 v[148:149], v[50:51]
	s_waitcnt vmcnt(11)
	v_mov_b64_e32 v[62:63], v[236:237]
	global_load_dwordx2 v[236:237], v243, s[46:47] offset:32
	s_and_b64 vcc, exec, s[44:45]
	s_waitcnt lgkmcnt(0)
	v_lshlrev_b32_e32 v60, 16, v62
	v_and_b32_e32 v61, 0xffff0000, v62
	v_lshlrev_b32_e32 v62, 16, v63
	v_and_b32_e32 v63, 0xffff0000, v63
	s_cbranch_vccnz .LBB0_1908
	v_sub_f32_e32 v61, v61, v55
	v_sub_f32_e32 v60, v60, v55
	v_sub_f32_e32 v63, v63, v55
	v_sub_f32_e32 v62, v62, v55
	v_pk_mul_f32 v[68:69], v[56:57], v[60:61]
	v_mov_b32_e32 v60, v56
	v_mov_b32_e32 v61, v56
	v_pk_mul_f32 v[70:71], v[60:61], v[62:63]
	ds_read_b128 v[60:63], v244 offset:64
	ds_read_b128 v[64:67], v244 offset:320
	s_waitcnt lgkmcnt(0)
	v_pk_fma_f32 v[62:63], v[70:71], v[62:63], v[66:67]
	v_pk_fma_f32 v[60:61], v[68:69], v[60:61], v[64:65]
.LBB0_1908:
	v_pk_fma_f32 v[46:47], v[62:63], s[72:73], v[46:47] op_sel_hi:[1,0,1]
	v_pk_fma_f32 v[44:45], v[60:61], s[72:73], v[44:45] op_sel_hi:[1,0,1]
	s_and_b64 vcc, exec, s[44:45]
	v_cvt_pk_bf16_f32 v44, v44, v45
	v_cvt_pk_bf16_f32 v45, v46, v47
	v_mov_b64_e32 v[150:151], v[44:45]
	v_lshrrev_b32_e32 v152, 4, v219
	v_lshlrev_b32_e32 v152, 3, v152
	v_mov_b32_e32 v153, v2
	v_permlane32_swap_b32_e32 v148, v150
	v_permlane32_swap_b32_e32 v149, v151
	v_lshl_add_u64 v[152:153], v[152:153], 0, v[48:49]
	s_nop 0
	v_permlane16_swap_b32_e32 v148, v150
	v_permlane16_swap_b32_e32 v149, v151
	global_store_dwordx4 v[152:153], v[148:151], off sc0
	s_waitcnt vmcnt(11)
	v_mov_b64_e32 v[60:61], v[238:239]
	global_load_dwordx2 v[238:239], v243, s[46:47] offset:256
	s_waitcnt lgkmcnt(0)
	v_lshlrev_b32_e32 v46, 16, v60
	v_and_b32_e32 v47, 0xffff0000, v60
	v_lshlrev_b32_e32 v60, 16, v61
	v_and_b32_e32 v61, 0xffff0000, v61
	s_cbranch_vccnz .LBB0_1910
	v_sub_f32_e32 v61, v61, v55
	v_sub_f32_e32 v60, v60, v55
	v_mov_b32_e32 v62, v56
	v_mov_b32_e32 v63, v56
	v_pk_mul_f32 v[60:61], v[62:63], v[60:61]
	ds_read_b128 v[62:65], v244 offset:128
	ds_read_b128 v[66:69], v244 offset:384
	v_sub_f32_e32 v47, v47, v55
	v_sub_f32_e32 v46, v46, v55
	v_pk_mul_f32 v[46:47], v[56:57], v[46:47]
	s_waitcnt lgkmcnt(0)
	v_pk_fma_f32 v[60:61], v[60:61], v[64:65], v[68:69]
	v_pk_fma_f32 v[46:47], v[46:47], v[62:63], v[66:67]
.LBB0_1910:
	v_pk_fma_f32 v[42:43], v[60:61], s[72:73], v[42:43] op_sel_hi:[1,0,1]
	v_pk_fma_f32 v[40:41], v[46:47], s[72:73], v[40:41] op_sel_hi:[1,0,1]
	s_and_b64 vcc, exec, s[44:45]
	v_cvt_pk_bf16_f32 v40, v40, v41
	v_cvt_pk_bf16_f32 v41, v42, v43
	v_mov_b64_e32 v[148:149], v[40:41]
	s_waitcnt vmcnt(11)
	v_mov_b64_e32 v[46:47], v[240:241]
	global_load_dwordx2 v[240:241], v243, s[46:47] offset:288
	s_waitcnt lgkmcnt(0)
	v_lshlrev_b32_e32 v42, 16, v46
	v_and_b32_e32 v43, 0xffff0000, v46
	v_lshlrev_b32_e32 v46, 16, v47
	v_and_b32_e32 v47, 0xffff0000, v47
	s_cbranch_vccnz .LBB0_1912
	v_sub_f32_e32 v43, v43, v55
	v_sub_f32_e32 v42, v42, v55
	v_sub_f32_e32 v47, v47, v55
	v_sub_f32_e32 v46, v46, v55
	v_pk_mul_f32 v[42:43], v[56:57], v[42:43]
	v_mov_b32_e32 v57, v56
	v_pk_mul_f32 v[46:47], v[56:57], v[46:47]
	ds_read_b128 v[54:57], v244 offset:192
	ds_read_b128 v[58:61], v244 offset:448
	s_waitcnt lgkmcnt(0)
	v_pk_fma_f32 v[46:47], v[46:47], v[56:57], v[60:61]
	v_pk_fma_f32 v[42:43], v[42:43], v[54:55], v[58:59]
.LBB0_1912:
	v_and_b32_e32 v57, 16, v50
	v_and_b32_e32 v56, 0xffff0000, v50
	v_lshlrev_b32_e32 v58, 16, v50
	v_lshlrev_b32_e32 v54, 16, v51
	v_and_b32_e32 v61, 0xffff0000, v50
	v_and_b32_e32 v60, 0xffff0000, v51
	v_mov_b32_e32 v3, v56
	v_mov_b32_e32 v55, v56
	v_pk_add_f32 v[50:51], v[58:59], v[56:57] op_sel_hi:[0,1]
	v_mul_f32_e32 v51, v58, v58
	v_pk_add_f32 v[56:57], v[60:61], v[54:55]
	v_pk_mul_f32 v[58:59], v[60:61], v[2:3]
	v_mov_b32_e32 v55, v60
	v_mov_b32_e32 v57, v59
	v_pk_add_f32 v[50:51], v[50:51], v[56:57]
	v_mul_f32_e32 v56, v54, v54
	v_pk_fma_f32 v[54:55], v[54:55], v[54:55], v[56:57] op_sel_hi:[1,1,0]
	v_lshlrev_b32_e32 v56, 16, v45
	v_lshlrev_b32_e32 v54, 16, v44
	v_and_b32_e32 v44, 0xffff0000, v44
	v_and_b32_e32 v58, 0xffff0000, v45
	v_mov_b32_e32 v3, v55
	v_mul_f32_e32 v55, v54, v54
	v_mul_f32_e32 v45, v44, v44
	v_mul_f32_e32 v57, v56, v56
	v_mul_f32_e32 v59, v58, v58
	v_pk_add_f32 v[44:45], v[54:55], v[44:45]
	v_pk_add_f32 v[54:55], v[56:57], v[58:59]
	v_pk_add_f32 v[50:51], v[50:51], v[2:3]
	v_pk_add_f32 v[44:45], v[44:45], v[54:55]
	v_lshlrev_b32_e32 v54, 16, v41
	v_pk_add_f32 v[44:45], v[50:51], v[44:45]
	v_lshlrev_b32_e32 v50, 16, v40
	v_and_b32_e32 v40, 0xffff0000, v40
	v_and_b32_e32 v56, 0xffff0000, v41
	v_mul_f32_e32 v51, v50, v50
	v_mul_f32_e32 v41, v40, v40
	v_mul_f32_e32 v55, v54, v54
	v_mul_f32_e32 v57, v56, v56
	v_pk_add_f32 v[40:41], v[50:51], v[40:41]
	v_pk_add_f32 v[50:51], v[54:55], v[56:57]
	v_pk_fma_f32 v[38:39], v[46:47], s[72:73], v[38:39] op_sel_hi:[1,0,1]
	v_pk_fma_f32 v[36:37], v[42:43], s[72:73], v[36:37] op_sel_hi:[1,0,1]
	v_pk_add_f32 v[40:41], v[40:41], v[50:51]
	v_cvt_pk_bf16_f32 v42, v36, v37
	v_cvt_pk_bf16_f32 v43, v38, v39
	v_pk_add_f32 v[40:41], v[44:45], v[40:41]
	v_lshlrev_b32_e32 v36, 16, v42
	v_and_b32_e32 v38, 0xffff0000, v42
	v_lshlrev_b32_e32 v44, 16, v43
	v_and_b32_e32 v46, 0xffff0000, v43
	v_mul_f32_e32 v37, v36, v36
	v_mul_f32_e32 v39, v38, v38
	v_mul_f32_e32 v45, v44, v44
	v_mul_f32_e32 v47, v46, v46
	v_pk_add_f32 v[36:37], v[36:37], v[38:39]
	v_pk_add_f32 v[38:39], v[44:45], v[46:47]
	v_mov_b64_e32 v[150:151], v[42:43]
	v_lshrrev_b32_e32 v152, 4, v219
	v_lshlrev_b32_e32 v152, 3, v152
	v_mov_b32_e32 v153, v2
	v_permlane32_swap_b32_e32 v148, v150
	v_permlane32_swap_b32_e32 v149, v151
	v_lshl_add_u64 v[152:153], v[152:153], 0, v[48:49]
	s_nop 0
	v_permlane16_swap_b32_e32 v148, v150
	v_permlane16_swap_b32_e32 v149, v151
	global_store_dwordx4 v[152:153], v[148:151], off offset:256 sc0
	v_pk_add_f32 v[36:37], v[36:37], v[38:39]
	s_nop 0
	v_pk_add_f32 v[36:37], v[40:41], v[36:37]
	ds_bpermute_b32 v38, v165, v36
	ds_bpermute_b32 v39, v165, v37
	s_waitcnt lgkmcnt(0)
	v_pk_add_f32 v[36:37], v[36:37], v[38:39]
	ds_bpermute_b32 v38, v164, v36
	ds_bpermute_b32 v39, v164, v37
	s_and_saveexec_b64 s[0:1], s[40:41]
	s_cbranch_execz .LBB0_1914
	v_lshl_add_u64 v[40:41], s[48:49], 0, v[52:53]
	v_lshl_add_u64 v[40:41], s[58:59], 2, v[40:41]
	s_waitcnt lgkmcnt(0)
	v_pk_add_f32 v[36:37], v[36:37], v[38:39]
	global_store_dwordx2 v[40:41], v[36:37], off

; __device__ __forceinline__ u32x2 pk4(f32x4 v) { u32x2 r; r.x = pk2(v.x, v.y); r.y = pk2(v.z, v.w); return r; }
;     __device__ __forceinline__ void operator()(const f32x4 (&acc)[2][2][4][2], const pg8::Unit& u, int wr, int wc, int fr, int fq) const {
;     ...
;                 for (int bj = 0; bj < 2; ++bj)
; #pragma unroll
;                     for (int n = 0; n < 2; ++n) {
;                         const int col = u.pn * 256 + bj * 128 + wc * 32 + n * 16 + fq * 4;
;                         const u32x2 raw = *(const u32x2*)(src + (size_t)row * DM + col);
;                         f32x4 x = (f32x4){bflo(raw.x), bfhi(raw.x), bflo(raw.y), bfhi(raw.y)};
;                         if (ln) x = (x - mu) * rs * *(const f32x4*)(g + col) + *(const f32x4*)(b + col);
;                         const u32x2 pz = pk4(x * ALPHA + acc[ai][bj][m][n]);
;                         *(u32x2*)(dst + (size_t)row * DM + col) = pz;
;                         const float z0 = bflo(pz.x), z1 = bfhi(pz.x), z2 = bflo(pz.y), z3 = bfhi(pz.y);
;                         s1 += (z0 + z1) + (z2 + z3); s2 += (z0 * z0 + z1 * z1) + (z2 * z2 + z3 * z3);
;                     }
;                 s1 += __shfl_xor(s1, 16); s2 += __shfl_xor(s2, 16); s1 += __shfl_xor(s1, 32); s2 += __shfl_xor(s2, 32);
;                 if (fq == 0) { float* p = stm_n + (size_t)row * 32 + (u.pn * 4 + wc) * 2; p[0] = s1; p[1] = s2; }
.LBB0_1919:
	v_lshlrev_b64 v[44:45], 10, v[44:45]
	v_pk_fma_f32 v[32:33], v[46:47], s[72:73], v[32:33] op_sel_hi:[1,0,1]
	v_pk_fma_f32 v[48:49], v[48:49], s[72:73], v[34:35] op_sel_hi:[1,0,1]
	v_cvt_pk_bf16_f32 v34, v32, v33
	v_lshl_add_u64 v[32:33], v[44:45], 1, s[70:71]
	v_cvt_pk_bf16_f32 v35, v48, v49
	v_lshl_add_u64 v[32:33], v[144:145], 1, v[32:33]
	v_mov_b64_e32 v[148:149], v[34:35]
	s_waitcnt vmcnt(8)
	v_mov_b64_e32 v[46:47], v[200:201]
	s_and_b64 vcc, exec, s[44:45]
	s_waitcnt lgkmcnt(0)
	v_lshlrev_b32_e32 v44, 16, v46
	v_and_b32_e32 v45, 0xffff0000, v46
	v_lshlrev_b32_e32 v46, 16, v47
	v_and_b32_e32 v47, 0xffff0000, v47
	s_cbranch_vccnz .LBB0_1921
	v_sub_f32_e32 v45, v45, v39
	v_sub_f32_e32 v44, v44, v39
	v_sub_f32_e32 v47, v47, v39
	v_sub_f32_e32 v46, v46, v39
	v_pk_mul_f32 v[52:53], v[40:41], v[44:45]
	v_mov_b32_e32 v44, v40
	v_mov_b32_e32 v45, v40
	v_pk_mul_f32 v[54:55], v[44:45], v[46:47]
	ds_read_b128 v[44:47], v244 offset:64
	ds_read_b128 v[48:51], v244 offset:320
	s_waitcnt lgkmcnt(0)
	v_pk_fma_f32 v[46:47], v[54:55], v[46:47], v[50:51]
	v_pk_fma_f32 v[44:45], v[52:53], v[44:45], v[48:49]
.LBB0_1921:
	v_pk_fma_f32 v[30:31], v[46:47], s[72:73], v[30:31] op_sel_hi:[1,0,1]
	v_pk_fma_f32 v[28:29], v[44:45], s[72:73], v[28:29] op_sel_hi:[1,0,1]
	s_and_b64 vcc, exec, s[44:45]
	v_cvt_pk_bf16_f32 v28, v28, v29
	v_cvt_pk_bf16_f32 v29, v30, v31
	v_mov_b64_e32 v[150:151], v[28:29]
	v_lshrrev_b32_e32 v152, 4, v219
	v_lshlrev_b32_e32 v152, 3, v152
	v_mov_b32_e32 v153, v2
	v_permlane32_swap_b32_e32 v148, v150
	v_permlane32_swap_b32_e32 v149, v151
	v_lshl_add_u64 v[152:153], v[152:153], 0, v[32:33]
	s_nop 0
	v_permlane16_swap_b32_e32 v148, v150
	v_permlane16_swap_b32_e32 v149, v151
	global_store_dwordx4 v[152:153], v[148:151], off sc0
	s_waitcnt vmcnt(7)
	v_mov_b64_e32 v[44:45], v[202:203]
	s_waitcnt lgkmcnt(0)
	v_lshlrev_b32_e32 v30, 16, v44
	v_and_b32_e32 v31, 0xffff0000, v44
	v_lshlrev_b32_e32 v44, 16, v45
	v_and_b32_e32 v45, 0xffff0000, v45
	s_cbranch_vccnz .LBB0_1923
	v_sub_f32_e32 v45, v45, v39
	v_sub_f32_e32 v44, v44, v39
	v_mov_b32_e32 v46, v40
	v_mov_b32_e32 v47, v40
	v_pk_mul_f32 v[44:45], v[46:47], v[44:45]
	ds_read_b128 v[46:49], v244 offset:128
	ds_read_b128 v[50:53], v244 offset:384
	v_sub_f32_e32 v31, v31, v39
	v_sub_f32_e32 v30, v30, v39
	v_pk_mul_f32 v[30:31], v[40:41], v[30:31]
	s_waitcnt lgkmcnt(0)
	v_pk_fma_f32 v[44:45], v[44:45], v[48:49], v[52:53]
	v_pk_fma_f32 v[30:31], v[30:31], v[46:47], v[50:51]
.LBB0_1923:
	v_pk_fma_f32 v[26:27], v[44:45], s[72:73], v[26:27] op_sel_hi:[1,0,1]
	v_pk_fma_f32 v[24:25], v[30:31], s[72:73], v[24:25] op_sel_hi:[1,0,1]
	s_and_b64 vcc, exec, s[44:45]
	v_cvt_pk_bf16_f32 v24, v24, v25
	v_cvt_pk_bf16_f32 v25, v26, v27
	v_mov_b64_e32 v[148:149], v[24:25]
	s_waitcnt vmcnt(6)
	v_mov_b64_e32 v[30:31], v[204:205]
	s_waitcnt lgkmcnt(0)
	v_lshlrev_b32_e32 v26, 16, v30
	v_and_b32_e32 v27, 0xffff0000, v30
	v_lshlrev_b32_e32 v30, 16, v31
	v_and_b32_e32 v31, 0xffff0000, v31
	s_cbranch_vccnz .LBB0_1925
	v_sub_f32_e32 v27, v27, v39
	v_sub_f32_e32 v26, v26, v39
	v_sub_f32_e32 v31, v31, v39
	v_sub_f32_e32 v30, v30, v39
	v_pk_mul_f32 v[26:27], v[40:41], v[26:27]
	v_mov_b32_e32 v41, v40
	v_pk_mul_f32 v[30:31], v[40:41], v[30:31]
	ds_read_b128 v[38:41], v244 offset:192
	ds_read_b128 v[42:45], v244 offset:448
	s_waitcnt lgkmcnt(0)
	v_pk_fma_f32 v[30:31], v[30:31], v[40:41], v[44:45]
	v_pk_fma_f32 v[26:27], v[26:27], v[38:39], v[42:43]
.LBB0_1925:
	v_and_b32_e32 v41, 16, v34
	v_and_b32_e32 v40, 0xffff0000, v34
	v_lshlrev_b32_e32 v42, 16, v34
	v_lshlrev_b32_e32 v38, 16, v35
	v_and_b32_e32 v45, 0xffff0000, v34
	v_and_b32_e32 v44, 0xffff0000, v35
	v_mov_b32_e32 v3, v40
	v_mov_b32_e32 v39, v40
	v_pk_add_f32 v[34:35], v[42:43], v[40:41] op_sel_hi:[0,1]
	v_mul_f32_e32 v35, v42, v42
	v_pk_add_f32 v[40:41], v[44:45], v[38:39]
	v_pk_mul_f32 v[42:43], v[44:45], v[2:3]
	v_mov_b32_e32 v39, v44
	v_mov_b32_e32 v41, v43
	v_pk_add_f32 v[34:35], v[34:35], v[40:41]
	v_mul_f32_e32 v40, v38, v38
	v_pk_fma_f32 v[38:39], v[38:39], v[38:39], v[40:41] op_sel_hi:[1,1,0]
	v_lshlrev_b32_e32 v40, 16, v29
	v_lshlrev_b32_e32 v38, 16, v28
	v_and_b32_e32 v28, 0xffff0000, v28
	v_and_b32_e32 v42, 0xffff0000, v29
	v_mov_b32_e32 v3, v39
	v_mul_f32_e32 v39, v38, v38
	v_mul_f32_e32 v29, v28, v28
	v_mul_f32_e32 v41, v40, v40
	v_mul_f32_e32 v43, v42, v42
	v_pk_add_f32 v[28:29], v[38:39], v[28:29]
	v_pk_add_f32 v[38:39], v[40:41], v[42:43]
	v_pk_add_f32 v[34:35], v[34:35], v[2:3]
	v_pk_add_f32 v[28:29], v[28:29], v[38:39]
	v_lshlrev_b32_e32 v38, 16, v25
	v_pk_add_f32 v[28:29], v[34:35], v[28:29]
	v_lshlrev_b32_e32 v34, 16, v24
	v_and_b32_e32 v24, 0xffff0000, v24
	v_and_b32_e32 v40, 0xffff0000, v25
	v_mul_f32_e32 v35, v34, v34
	v_mul_f32_e32 v25, v24, v24
	v_mul_f32_e32 v39, v38, v38
	v_mul_f32_e32 v41, v40, v40
	v_pk_add_f32 v[24:25], v[34:35], v[24:25]
	v_pk_add_f32 v[34:35], v[38:39], v[40:41]
	v_pk_fma_f32 v[22:23], v[30:31], s[72:73], v[22:23] op_sel_hi:[1,0,1]
	v_pk_fma_f32 v[20:21], v[26:27], s[72:73], v[20:21] op_sel_hi:[1,0,1]
	v_pk_add_f32 v[24:25], v[24:25], v[34:35]
	v_cvt_pk_bf16_f32 v26, v20, v21
	v_cvt_pk_bf16_f32 v27, v22, v23
	v_pk_add_f32 v[24:25], v[28:29], v[24:25]
	v_lshlrev_b32_e32 v20, 16, v26
	v_and_b32_e32 v22, 0xffff0000, v26
	v_lshlrev_b32_e32 v28, 16, v27
	v_and_b32_e32 v30, 0xffff0000, v27
	v_mul_f32_e32 v21, v20, v20
	v_mul_f32_e32 v23, v22, v22
	v_mul_f32_e32 v29, v28, v28
	v_mul_f32_e32 v31, v30, v30
	v_pk_add_f32 v[20:21], v[20:21], v[22:23]
	v_pk_add_f32 v[22:23], v[28:29], v[30:31]
	v_mov_b64_e32 v[150:151], v[26:27]
	v_lshrrev_b32_e32 v152, 4, v219
	v_lshlrev_b32_e32 v152, 3, v152
	v_mov_b32_e32 v153, v2
	v_permlane32_swap_b32_e32 v148, v150
	v_permlane32_swap_b32_e32 v149, v151
	v_lshl_add_u64 v[152:153], v[152:153], 0, v[32:33]
	s_nop 0
	v_permlane16_swap_b32_e32 v148, v150
	v_permlane16_swap_b32_e32 v149, v151
	global_store_dwordx4 v[152:153], v[148:151], off offset:256 sc0
	v_pk_add_f32 v[20:21], v[20:21], v[22:23]
	s_nop 0
	v_pk_add_f32 v[20:21], v[24:25], v[20:21]
	ds_bpermute_b32 v22, v165, v20
	ds_bpermute_b32 v23, v165, v21
	s_waitcnt lgkmcnt(0)
	v_pk_add_f32 v[20:21], v[20:21], v[22:23]
	ds_bpermute_b32 v22, v164, v20
	ds_bpermute_b32 v23, v164, v21
	s_and_saveexec_b64 s[0:1], s[40:41]
	s_cbranch_execz .LBB0_1927
	v_lshl_add_u64 v[24:25], s[48:49], 0, v[36:37]
	v_lshl_add_u64 v[24:25], s[58:59], 2, v[24:25]
	s_waitcnt lgkmcnt(0)
	v_pk_add_f32 v[20:21], v[20:21], v[22:23]
	global_store_dwordx2 v[24:25], v[20:21], off

; __device__ __forceinline__ u32x2 pk4(f32x4 v) { u32x2 r; r.x = pk2(v.x, v.y); r.y = pk2(v.z, v.w); return r; }
;     __device__ __forceinline__ void operator()(const f32x4 (&acc)[2][2][4][2], const pg8::Unit& u, int wr, int wc, int fr, int fq) const {
;     ...
;                 for (int bj = 0; bj < 2; ++bj)
; #pragma unroll
;                     for (int n = 0; n < 2; ++n) {
;                         const int col = u.pn * 256 + bj * 128 + wc * 32 + n * 16 + fq * 4;
;                         const u32x2 raw = *(const u32x2*)(src + (size_t)row * DM + col);
;                         f32x4 x = (f32x4){bflo(raw.x), bfhi(raw.x), bflo(raw.y), bfhi(raw.y)};
;                         if (ln) x = (x - mu) * rs * *(const f32x4*)(g + col) + *(const f32x4*)(b + col);
;                         const u32x2 pz = pk4(x * ALPHA + acc[ai][bj][m][n]);
;                         *(u32x2*)(dst + (size_t)row * DM + col) = pz;
;                         const float z0 = bflo(pz.x), z1 = bfhi(pz.x), z2 = bflo(pz.y), z3 = bfhi(pz.y);
;                         s1 += (z0 + z1) + (z2 + z3); s2 += (z0 * z0 + z1 * z1) + (z2 * z2 + z3 * z3);
;                     }
;                 s1 += __shfl_xor(s1, 16); s2 += __shfl_xor(s2, 16); s1 += __shfl_xor(s1, 32); s2 += __shfl_xor(s2, 32);
;                 if (fq == 0) { float* p = stm_n + (size_t)row * 32 + (u.pn * 4 + wc) * 2; p[0] = s1; p[1] = s2; }
.LBB0_1932:
	v_lshlrev_b64 v[28:29], 10, v[28:29]
	v_pk_fma_f32 v[16:17], v[30:31], s[72:73], v[16:17] op_sel_hi:[1,0,1]
	v_pk_fma_f32 v[32:33], v[32:33], s[72:73], v[18:19] op_sel_hi:[1,0,1]
	v_cvt_pk_bf16_f32 v18, v16, v17
	v_lshl_add_u64 v[16:17], v[28:29], 1, s[70:71]
	v_cvt_pk_bf16_f32 v19, v32, v33
	v_lshl_add_u64 v[16:17], v[144:145], 1, v[16:17]
	v_mov_b64_e32 v[148:149], v[18:19]
	s_waitcnt vmcnt(2)
	v_mov_b64_e32 v[30:31], v[236:237]
	s_and_b64 vcc, exec, s[44:45]
	s_waitcnt lgkmcnt(0)
	v_lshlrev_b32_e32 v28, 16, v30
	v_and_b32_e32 v29, 0xffff0000, v30
	v_lshlrev_b32_e32 v30, 16, v31
	v_and_b32_e32 v31, 0xffff0000, v31
	s_cbranch_vccnz .LBB0_1934
	v_sub_f32_e32 v29, v29, v23
	v_sub_f32_e32 v28, v28, v23
	v_sub_f32_e32 v31, v31, v23
	v_sub_f32_e32 v30, v30, v23
	v_pk_mul_f32 v[36:37], v[24:25], v[28:29]
	v_mov_b32_e32 v28, v24
	v_mov_b32_e32 v29, v24
	v_pk_mul_f32 v[38:39], v[28:29], v[30:31]
	ds_read_b128 v[28:31], v244 offset:64
	ds_read_b128 v[32:35], v244 offset:320
	s_waitcnt lgkmcnt(0)
	v_pk_fma_f32 v[30:31], v[38:39], v[30:31], v[34:35]
	v_pk_fma_f32 v[28:29], v[36:37], v[28:29], v[32:33]
.LBB0_1934:
	v_pk_fma_f32 v[14:15], v[30:31], s[72:73], v[14:15] op_sel_hi:[1,0,1]
	v_pk_fma_f32 v[12:13], v[28:29], s[72:73], v[12:13] op_sel_hi:[1,0,1]
	s_and_b64 vcc, exec, s[44:45]
	v_cvt_pk_bf16_f32 v12, v12, v13
	v_cvt_pk_bf16_f32 v13, v14, v15
	v_mov_b64_e32 v[150:151], v[12:13]
	v_lshrrev_b32_e32 v146, 4, v219
	v_lshlrev_b32_e32 v146, 3, v146
	v_mov_b32_e32 v147, v2
	v_permlane32_swap_b32_e32 v148, v150
	v_permlane32_swap_b32_e32 v149, v151
	v_lshl_add_u64 v[146:147], v[146:147], 0, v[16:17]
	s_nop 0
	v_permlane16_swap_b32_e32 v148, v150
	v_permlane16_swap_b32_e32 v149, v151
	global_store_dwordx4 v[146:147], v[148:151], off sc0
	s_waitcnt vmcnt(1)
	v_mov_b64_e32 v[28:29], v[238:239]
	s_waitcnt lgkmcnt(0)
	v_lshlrev_b32_e32 v14, 16, v28
	v_and_b32_e32 v15, 0xffff0000, v28
	v_lshlrev_b32_e32 v28, 16, v29
	v_and_b32_e32 v29, 0xffff0000, v29
	s_cbranch_vccnz .LBB0_1936
	v_sub_f32_e32 v29, v29, v23
	v_sub_f32_e32 v28, v28, v23
	v_mov_b32_e32 v30, v24
	v_mov_b32_e32 v31, v24
	v_pk_mul_f32 v[28:29], v[30:31], v[28:29]
	ds_read_b128 v[30:33], v244 offset:128
	ds_read_b128 v[34:37], v244 offset:384
	v_sub_f32_e32 v15, v15, v23
	v_sub_f32_e32 v14, v14, v23
	v_pk_mul_f32 v[14:15], v[24:25], v[14:15]
	s_waitcnt lgkmcnt(0)
	v_pk_fma_f32 v[28:29], v[28:29], v[32:33], v[36:37]
	v_pk_fma_f32 v[14:15], v[14:15], v[30:31], v[34:35]
.LBB0_1936:
	v_pk_fma_f32 v[10:11], v[28:29], s[72:73], v[10:11] op_sel_hi:[1,0,1]
	v_pk_fma_f32 v[8:9], v[14:15], s[72:73], v[8:9] op_sel_hi:[1,0,1]
	s_and_b64 vcc, exec, s[44:45]
	v_cvt_pk_bf16_f32 v8, v8, v9
	v_cvt_pk_bf16_f32 v9, v10, v11
	v_mov_b64_e32 v[148:149], v[8:9]
	s_waitcnt vmcnt(0)
	v_mov_b64_e32 v[14:15], v[240:241]
	s_waitcnt lgkmcnt(0)
	v_lshlrev_b32_e32 v10, 16, v14
	v_and_b32_e32 v11, 0xffff0000, v14
	v_lshlrev_b32_e32 v14, 16, v15
	v_and_b32_e32 v15, 0xffff0000, v15
	s_cbranch_vccnz .LBB0_1938
	v_sub_f32_e32 v11, v11, v23
	v_sub_f32_e32 v10, v10, v23
	v_sub_f32_e32 v15, v15, v23
	v_sub_f32_e32 v14, v14, v23
	v_pk_mul_f32 v[10:11], v[24:25], v[10:11]
	v_mov_b32_e32 v25, v24
	v_pk_mul_f32 v[14:15], v[24:25], v[14:15]
	ds_read_b128 v[22:25], v244 offset:192
	ds_read_b128 v[26:29], v244 offset:448
	s_waitcnt lgkmcnt(0)
	v_pk_fma_f32 v[14:15], v[14:15], v[24:25], v[28:29]
	v_pk_fma_f32 v[10:11], v[10:11], v[22:23], v[26:27]
.LBB0_1938:
	v_and_b32_e32 v25, 16, v18
	v_and_b32_e32 v24, 0xffff0000, v18
	v_lshlrev_b32_e32 v26, 16, v18
	v_lshlrev_b32_e32 v22, 16, v19
	v_and_b32_e32 v29, 0xffff0000, v18
	v_and_b32_e32 v28, 0xffff0000, v19
	v_mov_b32_e32 v3, v24
	v_mov_b32_e32 v23, v24
	v_pk_add_f32 v[18:19], v[26:27], v[24:25] op_sel_hi:[0,1]
	v_mul_f32_e32 v19, v26, v26
	v_pk_add_f32 v[24:25], v[28:29], v[22:23]
	v_pk_mul_f32 v[26:27], v[28:29], v[2:3]
	v_mov_b32_e32 v23, v28
	v_mov_b32_e32 v25, v27
	v_pk_add_f32 v[18:19], v[18:19], v[24:25]
	v_mul_f32_e32 v24, v22, v22
	v_pk_fma_f32 v[22:23], v[22:23], v[22:23], v[24:25] op_sel_hi:[1,1,0]
	v_lshlrev_b32_e32 v24, 16, v13
	v_lshlrev_b32_e32 v22, 16, v12
	v_and_b32_e32 v12, 0xffff0000, v12
	v_and_b32_e32 v26, 0xffff0000, v13
	v_mov_b32_e32 v3, v23
	v_mul_f32_e32 v23, v22, v22
	v_mul_f32_e32 v13, v12, v12
	v_mul_f32_e32 v25, v24, v24
	v_mul_f32_e32 v27, v26, v26
	v_pk_add_f32 v[12:13], v[22:23], v[12:13]
	v_pk_add_f32 v[22:23], v[24:25], v[26:27]
	v_pk_add_f32 v[18:19], v[18:19], v[2:3]
	v_pk_add_f32 v[12:13], v[12:13], v[22:23]
	v_lshlrev_b32_e32 v22, 16, v9
	v_pk_add_f32 v[12:13], v[18:19], v[12:13]
	v_lshlrev_b32_e32 v18, 16, v8
	v_and_b32_e32 v8, 0xffff0000, v8
	v_and_b32_e32 v24, 0xffff0000, v9
	v_mul_f32_e32 v19, v18, v18
	v_mul_f32_e32 v9, v8, v8
	v_mul_f32_e32 v23, v22, v22
	v_mul_f32_e32 v25, v24, v24
	v_pk_add_f32 v[8:9], v[18:19], v[8:9]
	v_pk_add_f32 v[18:19], v[22:23], v[24:25]
	v_pk_fma_f32 v[6:7], v[14:15], s[72:73], v[6:7] op_sel_hi:[1,0,1]
	v_pk_fma_f32 v[4:5], v[10:11], s[72:73], v[4:5] op_sel_hi:[1,0,1]
	v_pk_add_f32 v[8:9], v[8:9], v[18:19]
	v_cvt_pk_bf16_f32 v10, v4, v5
	v_cvt_pk_bf16_f32 v11, v6, v7
	v_pk_add_f32 v[8:9], v[12:13], v[8:9]
	v_lshlrev_b32_e32 v4, 16, v10
	v_and_b32_e32 v6, 0xffff0000, v10
	v_lshlrev_b32_e32 v12, 16, v11
	v_and_b32_e32 v14, 0xffff0000, v11
	v_mul_f32_e32 v5, v4, v4
	v_mul_f32_e32 v7, v6, v6
	v_mul_f32_e32 v13, v12, v12
	v_mul_f32_e32 v15, v14, v14
	v_pk_add_f32 v[4:5], v[4:5], v[6:7]
	v_pk_add_f32 v[6:7], v[12:13], v[14:15]
	v_mov_b64_e32 v[150:151], v[10:11]
	v_lshrrev_b32_e32 v146, 4, v219
	v_lshlrev_b32_e32 v146, 3, v146
	v_mov_b32_e32 v147, v2
	v_permlane32_swap_b32_e32 v148, v150
	v_permlane32_swap_b32_e32 v149, v151
	v_lshl_add_u64 v[146:147], v[146:147], 0, v[16:17]
	s_nop 0
	v_permlane16_swap_b32_e32 v148, v150
	v_permlane16_swap_b32_e32 v149, v151
	global_store_dwordx4 v[146:147], v[148:151], off offset:256 sc0
	v_pk_add_f32 v[4:5], v[4:5], v[6:7]
	s_nop 0
	v_pk_add_f32 v[4:5], v[8:9], v[4:5]
	ds_bpermute_b32 v6, v165, v4
	ds_bpermute_b32 v7, v165, v5
	s_waitcnt lgkmcnt(0)
	v_pk_add_f32 v[4:5], v[4:5], v[6:7]
	ds_bpermute_b32 v6, v164, v4
	ds_bpermute_b32 v7, v164, v5
	s_and_saveexec_b64 s[0:1], s[40:41]
	s_cbranch_execz .LBB0_1940
	v_lshl_add_u64 v[8:9], s[48:49], 0, v[20:21]
	v_lshl_add_u64 v[8:9], s[58:59], 2, v[8:9]
	s_waitcnt lgkmcnt(0)
	v_pk_add_f32 v[4:5], v[4:5], v[6:7]
	global_store_dwordx2 v[8:9], v[4:5], off

; __device__ __forceinline__ u32x2 pk4(f32x4 v) { u32x2 r; r.x = pk2(v.x, v.y); r.y = pk2(v.z, v.w); return r; }
; __device__ __forceinline__ void stats_main(const float* stm, int row, int fq, float& mu, float& rs) {
;     const f32x4* p = (const f32x4*)(stm + (size_t)row * 32 + fq * 8);
;     const f32x4 a = p[0], b = p[1];
;     float s1 = (a.x + a.z) + (b.x + b.z), s2 = (a.y + a.w) + (b.y + b.w);
;     s1 += __shfl_xor(s1, 16); s2 += __shfl_xor(s2, 16); s1 += __shfl_xor(s1, 32); s2 += __shfl_xor(s2, 32);
;     mu = s1 * (1.f / DM); rs = __builtin_amdgcn_rsqf(fmaxf(s2 * (1.f / DM) - mu * mu, 0.f) + LN_EPS);
; }
;     __device__ __forceinline__ void operator()(const f32x4 (&acc)[2][2][4][2], const pg8::Unit& u, int wr, int wc, int fr, int fq) const {
;     ...
;                 const int row = u.pm * 256 + ai * 128 + wr * 64 + m * 16 + fr;
;                 float mu = 0.f, rs = 1.f; if (ln) stats_main(stm_p, row, fq, mu, rs);
;                 float s1 = 0.f, s2 = 0.f;
; #pragma unroll
;                 for (int bj = 0; bj < 2; ++bj)
; #pragma unroll
;                     for (int n = 0; n < 2; ++n) {
;                         const int col = u.pn * 256 + bj * 128 + wc * 32 + n * 16 + fq * 4;
;                         const u32x2 raw = *(const u32x2*)(src + (size_t)row * DM + col);
;                         f32x4 x = (f32x4){bflo(raw.x), bfhi(raw.x), bflo(raw.y), bfhi(raw.y)};
;                         if (ln) x = (x - mu) * rs * *(const f32x4*)(g + col) + *(const f32x4*)(b + col);
;                         const u32x2 pz = pk4(x * ALPHA + acc[ai][bj][m][n]);
;                         *(u32x2*)(dst + (size_t)row * DM + col) = pz;
;                         const float z0 = bflo(pz.x), z1 = bfhi(pz.x), z2 = bflo(pz.y), z3 = bfhi(pz.y);
;                         s1 += (z0 + z1) + (z2 + z3); s2 += (z0 * z0 + z1 * z1) + (z2 * z2 + z3 * z3);
;                     }
;                 s1 += __shfl_xor(s1, 16); s2 += __shfl_xor(s2, 16); s1 += __shfl_xor(s1, 32); s2 += __shfl_xor(s2, 32);
;                 if (fq == 0) { float* p = stm_n + (size_t)row * 32 + (u.pn * 4 + wc) * 2; p[0] = s1; p[1] = s2; }
.LBB0_2207:
	s_or_b64 exec, exec, s[0:1]
	v_or_b32_e32 v110, 32, v146
	v_ashrrev_i32_e32 v111, 31, v110
	v_lshlrev_b64 v[100:101], 7, v[110:111]
	v_lshl_add_u64 v[106:107], v[134:135], 0, v[100:101]
	s_waitcnt lgkmcnt(0)
	s_waitcnt vmcnt(11)
	v_mov_b64_e32 v[102:103], v[190:191]
	v_mov_b64_e32 v[104:105], v[192:193]
	global_load_dwordx4 v[190:193], v[248:249], off offset:-4080
	s_nop 0
	s_waitcnt vmcnt(11)
	v_mov_b64_e32 v[106:107], v[194:195]
	v_mov_b64_e32 v[108:109], v[196:197]
	global_load_dwordx4 v[194:197], v[248:249], off offset:-4096
	s_waitcnt lgkmcnt(0)
	v_pk_add_f32 v[102:103], v[102:103], v[104:105]
	s_waitcnt lgkmcnt(0)
	v_pk_add_f32 v[106:107], v[106:107], v[108:109]
	s_nop 0
	v_pk_add_f32 v[102:103], v[106:107], v[102:103]
	ds_bpermute_b32 v104, v181, v102
	ds_bpermute_b32 v105, v181, v103
	s_waitcnt lgkmcnt(0)
	v_pk_add_f32 v[102:103], v[102:103], v[104:105]
	ds_bpermute_b32 v104, v180, v102
	ds_bpermute_b32 v105, v180, v103
	s_waitcnt lgkmcnt(0)
	v_pk_add_f32 v[102:103], v[102:103], v[104:105]
	s_nop 0
	v_pk_mul_f32 v[112:113], v[102:103], s[82:83] op_sel_hi:[1,0]
	v_lshlrev_b64 v[102:103], 11, v[110:111]
	v_lshl_add_u64 v[102:103], s[70:71], 0, v[102:103]
	v_lshl_add_u64 v[108:109], v[144:145], 1, v[102:103]
	v_add_u32_e32 v243, 0x40000, v242
	s_waitcnt vmcnt(11)
	v_mov_b64_e32 v[102:103], v[198:199]
	global_load_dwordx2 v[198:199], v243, s[70:71]
	v_fma_f32 v3, -v112, v112, v113
	v_max_f32_e32 v3, 0, v3
	v_add_f32_e32 v3, 0x3727c5ac, v3
	v_rsq_f32_e32 v114, v3
	s_waitcnt lgkmcnt(0)
	v_lshlrev_b32_e32 v3, 16, v102
	v_and_b32_e32 v102, 0xffff0000, v102
	v_lshlrev_b32_e32 v104, 16, v103
	v_and_b32_e32 v105, 0xffff0000, v103
	v_sub_f32_e32 v103, v102, v112
	v_sub_f32_e32 v102, v3, v112
	v_sub_f32_e32 v105, v105, v112
	v_sub_f32_e32 v104, v104, v112
	v_pk_mul_f32 v[106:107], v[104:105], v[114:115] op_sel_hi:[1,0]
	v_pk_mul_f32 v[110:111], v[102:103], v[114:115] op_sel_hi:[1,0]
	ds_read_b128 v[102:105], v244
	ds_read_b128 v[116:119], v244 offset:256
	s_waitcnt lgkmcnt(0)
	v_pk_fma_f32 v[104:105], v[104:105], v[106:107], v[118:119]
	s_nop 0
	v_pk_fma_f32 v[98:99], v[104:105], s[72:73], v[98:99] op_sel_hi:[1,0,1]
	s_waitcnt vmcnt(11)
	v_mov_b64_e32 v[104:105], v[200:201]
	global_load_dwordx2 v[200:201], v243, s[70:71] offset:32
	v_pk_fma_f32 v[102:103], v[102:103], v[110:111], v[116:117]
	s_waitcnt lgkmcnt(0)
	v_lshlrev_b32_e32 v3, 16, v104
	v_pk_fma_f32 v[96:97], v[102:103], s[72:73], v[96:97] op_sel_hi:[1,0,1]
	v_cvt_pk_bf16_f32 v103, v98, v99
	v_cvt_pk_bf16_f32 v102, v96, v97
	v_and_b32_e32 v97, 0xffff0000, v104
	v_lshlrev_b32_e32 v99, 16, v105
	v_and_b32_e32 v106, 0xffff0000, v105
	v_mov_b64_e32 v[148:149], v[102:103]
	v_sub_f32_e32 v105, v97, v112
	v_sub_f32_e32 v104, v3, v112
	v_sub_f32_e32 v107, v106, v112
	v_sub_f32_e32 v106, v99, v112
	v_pk_mul_f32 v[110:111], v[114:115], v[106:107] op_sel_hi:[0,1]
	v_pk_mul_f32 v[120:121], v[114:115], v[104:105] op_sel_hi:[0,1]
	ds_read_b128 v[104:107], v244 offset:64
	ds_read_b128 v[116:119], v244 offset:320
	v_and_b32_e32 v98, 0xffff0000, v102
	v_lshlrev_b32_e32 v96, 16, v103
	s_waitcnt lgkmcnt(0)
	v_pk_fma_f32 v[104:105], v[104:105], v[120:121], v[116:117]
	s_nop 0
	v_pk_fma_f32 v[92:93], v[104:105], s[72:73], v[92:93] op_sel_hi:[1,0,1]
	s_waitcnt vmcnt(11)
	v_mov_b64_e32 v[104:105], v[202:203]
	global_load_dwordx2 v[202:203], v243, s[70:71] offset:256
	v_pk_fma_f32 v[106:107], v[106:107], v[110:111], v[118:119]
	v_cvt_pk_bf16_f32 v110, v92, v93
	v_pk_fma_f32 v[94:95], v[106:107], s[72:73], v[94:95] op_sel_hi:[1,0,1]
	s_waitcnt lgkmcnt(0)
	v_lshlrev_b32_e32 v3, 16, v104
	v_cvt_pk_bf16_f32 v111, v94, v95
	v_lshlrev_b32_e32 v94, 16, v111
	v_and_b32_e32 v95, 0xffff0000, v111
	v_mul_f32_e32 v92, v94, v94
	v_pk_fma_f32 v[92:93], v[94:95], v[94:95], v[92:93] op_sel_hi:[1,1,0]
	v_lshlrev_b32_e32 v97, 16, v105
	v_and_b32_e32 v92, 0xffff0000, v104
	v_and_b32_e32 v99, 0xffff0000, v105
	v_mov_b64_e32 v[150:151], v[110:111]
	v_lshrrev_b32_e32 v122, 4, v219
	v_lshlrev_b32_e32 v122, 3, v122
	v_mov_b32_e32 v123, v2
	v_permlane32_swap_b32_e32 v148, v150
	v_permlane32_swap_b32_e32 v149, v151
	v_lshl_add_u64 v[122:123], v[122:123], 0, v[108:109]
	s_nop 0
	v_permlane16_swap_b32_e32 v148, v150
	v_permlane16_swap_b32_e32 v149, v151
	global_store_dwordx4 v[122:123], v[148:151], off sc0
	v_sub_f32_e32 v105, v92, v112
	v_sub_f32_e32 v104, v3, v112
	v_sub_f32_e32 v107, v99, v112
	v_sub_f32_e32 v106, v97, v112
	v_pk_mul_f32 v[120:121], v[114:115], v[106:107] op_sel_hi:[0,1]
	v_pk_mul_f32 v[122:123], v[114:115], v[104:105] op_sel_hi:[0,1]
	ds_read_b128 v[104:107], v244 offset:128
	ds_read_b128 v[116:119], v244 offset:384
	v_and_b32_e32 v111, 0xffff0000, v110
	s_waitcnt lgkmcnt(0)
	v_pk_fma_f32 v[104:105], v[104:105], v[122:123], v[116:117]
	s_waitcnt vmcnt(11)
	v_mov_b64_e32 v[116:117], v[204:205]
	global_load_dwordx2 v[204:205], v243, s[70:71] offset:288
	v_pk_fma_f32 v[106:107], v[106:107], v[120:121], v[118:119]
	v_pk_fma_f32 v[88:89], v[104:105], s[72:73], v[88:89] op_sel_hi:[1,0,1]
	v_pk_fma_f32 v[90:91], v[106:107], s[72:73], v[90:91] op_sel_hi:[1,0,1]
	v_cvt_pk_bf16_f32 v88, v88, v89
	v_cvt_pk_bf16_f32 v89, v90, v91
	v_mov_b64_e32 v[148:149], v[88:89]
	v_lshlrev_b32_e32 v104, 16, v88
	v_and_b32_e32 v106, 0xffff0000, v88
	v_lshlrev_b32_e32 v88, 16, v89
	v_and_b32_e32 v90, 0xffff0000, v89
	v_mul_f32_e32 v105, v104, v104
	v_mul_f32_e32 v107, v106, v106
	v_mul_f32_e32 v89, v88, v88
	v_mul_f32_e32 v91, v90, v90
	v_pk_add_f32 v[88:89], v[88:89], v[90:91]
	s_waitcnt lgkmcnt(0)
; __device__ __forceinline__ u32x2 pk4(f32x4 v) { u32x2 r; r.x = pk2(v.x, v.y); r.y = pk2(v.z, v.w); return r; }
; __device__ __forceinline__ void stats_main(const float* stm, int row, int fq, float& mu, float& rs) {
;     const f32x4* p = (const f32x4*)(stm + (size_t)row * 32 + fq * 8);
;     const f32x4 a = p[0], b = p[1];
;     float s1 = (a.x + a.z) + (b.x + b.z), s2 = (a.y + a.w) + (b.y + b.w);
;     s1 += __shfl_xor(s1, 16); s2 += __shfl_xor(s2, 16); s1 += __shfl_xor(s1, 32); s2 += __shfl_xor(s2, 32);
;     mu = s1 * (1.f / DM); rs = __builtin_amdgcn_rsqf(fmaxf(s2 * (1.f / DM) - mu * mu, 0.f) + LN_EPS);
; }
;     __device__ __forceinline__ void operator()(const f32x4 (&acc)[2][2][4][2], const pg8::Unit& u, int wr, int wc, int fr, int fq) const {
;     ...
;                 for (int bj = 0; bj < 2; ++bj)
; #pragma unroll
;                     for (int n = 0; n < 2; ++n) {
;                         const int col = u.pn * 256 + bj * 128 + wc * 32 + n * 16 + fq * 4;
;                         const u32x2 raw = *(const u32x2*)(src + (size_t)row * DM + col);
;                         f32x4 x = (f32x4){bflo(raw.x), bfhi(raw.x), bflo(raw.y), bfhi(raw.y)};
;                         if (ln) x = (x - mu) * rs * *(const f32x4*)(g + col) + *(const f32x4*)(b + col);
;                         const u32x2 pz = pk4(x * ALPHA + acc[ai][bj][m][n]);
;                         *(u32x2*)(dst + (size_t)row * DM + col) = pz;
;                         const float z0 = bflo(pz.x), z1 = bfhi(pz.x), z2 = bflo(pz.y), z3 = bfhi(pz.y);
;                         s1 += (z0 + z1) + (z2 + z3); s2 += (z0 * z0 + z1 * z1) + (z2 * z2 + z3 * z3);
;                     }
;                 s1 += __shfl_xor(s1, 16); s2 += __shfl_xor(s2, 16); s1 += __shfl_xor(s1, 32); s2 += __shfl_xor(s2, 32);
;                 if (fq == 0) { float* p = stm_n + (size_t)row * 32 + (u.pn * 4 + wc) * 2; p[0] = s1; p[1] = s2; }
	v_lshlrev_b32_e32 v3, 16, v116
	v_and_b32_e32 v92, 0xffff0000, v116
	v_lshlrev_b32_e32 v97, 16, v117
	v_and_b32_e32 v99, 0xffff0000, v117
	v_sub_f32_e32 v117, v92, v112
	v_sub_f32_e32 v116, v3, v112
	v_sub_f32_e32 v113, v99, v112
	v_sub_f32_e32 v112, v97, v112
	v_pk_mul_f32 v[112:113], v[114:115], v[112:113] op_sel_hi:[0,1]
	v_pk_mul_f32 v[114:115], v[114:115], v[116:117] op_sel_hi:[0,1]
	ds_read_b128 v[116:119], v244 offset:192
	ds_read_b128 v[120:123], v244 offset:448
	v_mov_b32_e32 v97, v111
	v_mov_b32_e32 v3, v93
	s_waitcnt lgkmcnt(0)
	v_pk_fma_f32 v[114:115], v[116:117], v[114:115], v[120:121]
	s_nop 0
	v_pk_fma_f32 v[84:85], v[114:115], s[72:73], v[84:85] op_sel_hi:[1,0,1]
	v_lshlrev_b32_e32 v115, 16, v110
	v_lshlrev_b32_e32 v114, 16, v102
	v_mov_b32_e32 v99, v115
	v_pk_fma_f32 v[112:113], v[118:119], v[112:113], v[122:123]
	v_pk_mul_f32 v[116:117], v[114:115], v[114:115]
	v_pk_mul_f32 v[118:119], v[98:99], v[98:99]
	v_and_b32_e32 v110, 0xffff0000, v103
	v_pk_mul_f32 v[102:103], v[96:97], v[96:97]
	v_pk_mul_f32 v[120:121], v[110:111], v[110:111]
	v_pk_mov_b32 v[122:123], v[114:115], v[116:117] op_sel:[1,0]
	v_pk_mov_b32 v[118:119], v[110:111], v[118:119] op_sel:[1,0]
	v_pk_add_f32 v[98:99], v[114:115], v[98:99]
	v_pk_add_f32 v[96:97], v[110:111], v[96:97]
	v_pk_fma_f32 v[86:87], v[112:113], s[72:73], v[86:87] op_sel_hi:[1,0,1]
	v_pk_add_f32 v[118:119], v[122:123], v[118:119]
	v_mov_b32_e32 v122, v94
	v_mov_b32_e32 v123, v102
	v_pk_mov_b32 v[94:95], v[94:95], v[120:121] op_sel:[1,0]
	v_mov_b32_e32 v99, v117
	v_mov_b32_e32 v97, v121
	v_cvt_pk_bf16_f32 v84, v84, v85
	v_cvt_pk_bf16_f32 v85, v86, v87
	v_pk_add_f32 v[94:95], v[122:123], v[94:95]
	v_pk_add_f32 v[96:97], v[98:99], v[96:97]
	v_mov_b64_e32 v[150:151], v[84:85]
	v_lshrrev_b32_e32 v152, 4, v219
	v_lshlrev_b32_e32 v152, 3, v152
	v_mov_b32_e32 v153, v2
	v_permlane32_swap_b32_e32 v148, v150
	v_permlane32_swap_b32_e32 v149, v151
	v_lshl_add_u64 v[152:153], v[152:153], 0, v[108:109]
	s_nop 0
	v_permlane16_swap_b32_e32 v148, v150
	v_permlane16_swap_b32_e32 v149, v151
	global_store_dwordx4 v[152:153], v[148:151], off offset:256 sc0
	v_lshlrev_b32_e32 v108, 16, v84
	v_and_b32_e32 v112, 0xffff0000, v84
	v_lshlrev_b32_e32 v84, 16, v85
	v_and_b32_e32 v86, 0xffff0000, v85
	v_pk_add_f32 v[94:95], v[118:119], v[94:95]
	v_pk_add_f32 v[92:93], v[96:97], v[2:3]
	v_mul_f32_e32 v109, v108, v108
	v_mul_f32_e32 v113, v112, v112
	v_mul_f32_e32 v85, v84, v84
	v_mul_f32_e32 v87, v86, v86
	v_pk_add_f32 v[92:93], v[94:95], v[92:93]
	v_pk_add_f32 v[94:95], v[104:105], v[106:107]
	v_pk_add_f32 v[90:91], v[108:109], v[112:113]
	v_pk_add_f32 v[88:89], v[94:95], v[88:89]
	v_pk_add_f32 v[84:85], v[84:85], v[86:87]
	v_pk_add_f32 v[88:89], v[92:93], v[88:89]
	v_pk_add_f32 v[84:85], v[90:91], v[84:85]
	s_nop 0
	v_pk_add_f32 v[84:85], v[88:89], v[84:85]
	ds_bpermute_b32 v86, v181, v84
	ds_bpermute_b32 v87, v181, v85
	s_waitcnt lgkmcnt(0)
	v_pk_add_f32 v[84:85], v[84:85], v[86:87]
	ds_bpermute_b32 v86, v180, v84
	ds_bpermute_b32 v87, v180, v85
	s_and_saveexec_b64 s[0:1], s[40:41]
	v_readlane_b32 s24, v251, 0
	v_readlane_b32 s25, v251, 1
	v_readlane_b32 s26, v251, 2
	v_readlane_b32 s27, v251, 3
	s_mov_b32 s76, 0x30000
	s_cbranch_execz .LBB0_2209
	v_lshl_add_u64 v[88:89], s[50:51], 0, v[100:101]
	v_lshl_add_u64 v[88:89], s[60:61], 2, v[88:89]
	s_waitcnt lgkmcnt(0)
	v_pk_add_f32 v[84:85], v[84:85], v[86:87]
	global_store_dwordx2 v[88:89], v[84:85], off
.LBB0_2209:
	s_or_b64 exec, exec, s[0:1]
	v_or_b32_e32 v94, 48, v146
	v_ashrrev_i32_e32 v95, 31, v94
	v_lshlrev_b64 v[84:85], 7, v[94:95]
	v_lshl_add_u64 v[90:91], v[134:135], 0, v[84:85]
	s_waitcnt lgkmcnt(0)
	s_waitcnt vmcnt(11)
	v_mov_b64_e32 v[86:87], v[206:207]
	v_mov_b64_e32 v[88:89], v[208:209]
	global_load_dwordx4 v[206:209], v[248:249], off offset:-2032
	s_nop 0
	s_waitcnt vmcnt(11)
	v_mov_b64_e32 v[90:91], v[214:215]
	v_mov_b64_e32 v[92:93], v[216:217]
	global_load_dwordx4 v[214:217], v[248:249], off offset:-2048
	s_waitcnt lgkmcnt(0)
	v_pk_add_f32 v[86:87], v[86:87], v[88:89]
	s_waitcnt lgkmcnt(0)
	v_pk_add_f32 v[90:91], v[90:91], v[92:93]
	s_nop 0
	v_pk_add_f32 v[86:87], v[90:91], v[86:87]
	ds_bpermute_b32 v88, v181, v86
	ds_bpermute_b32 v89, v181, v87
	s_waitcnt lgkmcnt(0)
	v_pk_add_f32 v[86:87], v[86:87], v[88:89]
	ds_bpermute_b32 v88, v180, v86
	ds_bpermute_b32 v89, v180, v87
	s_waitcnt lgkmcnt(0)
	v_pk_add_f32 v[86:87], v[86:87], v[88:89]
	s_nop 0
	v_pk_mul_f32 v[96:97], v[86:87], s[82:83] op_sel_hi:[1,0]
	v_lshlrev_b64 v[86:87], 11, v[94:95]
	v_lshl_add_u64 v[86:87], s[70:71], 0, v[86:87]
	v_lshl_add_u64 v[92:93], v[144:145], 1, v[86:87]
	v_add_u32_e32 v243, 0x48000, v242
	s_waitcnt vmcnt(11)
	v_mov_b64_e32 v[86:87], v[234:235]
	global_load_dwordx2 v[234:235], v243, s[70:71]
	v_fma_f32 v3, -v96, v96, v97
	v_max_f32_e32 v3, 0, v3
	v_add_f32_e32 v3, 0x3727c5ac, v3
	v_rsq_f32_e32 v98, v3
	s_waitcnt lgkmcnt(0)
	v_lshlrev_b32_e32 v3, 16, v86
	v_and_b32_e32 v86, 0xffff0000, v86
	v_lshlrev_b32_e32 v88, 16, v87
	v_and_b32_e32 v89, 0xffff0000, v87
	v_sub_f32_e32 v87, v86, v96
	v_sub_f32_e32 v86, v3, v96
	v_sub_f32_e32 v89, v89, v96
	v_sub_f32_e32 v88, v88, v96
	v_pk_mul_f32 v[90:91], v[88:89], v[98:99] op_sel_hi:[1,0]
	v_pk_mul_f32 v[94:95], v[86:87], v[98:99] op_sel_hi:[1,0]
	ds_read_b128 v[86:89], v244
	ds_read_b128 v[100:103], v244 offset:256
	s_waitcnt lgkmcnt(0)
	v_pk_fma_f32 v[88:89], v[88:89], v[90:91], v[102:103]
	s_nop 0
	v_pk_fma_f32 v[82:83], v[88:89], s[72:73], v[82:83] op_sel_hi:[1,0,1]
	s_waitcnt vmcnt(11)
	v_mov_b64_e32 v[88:89], v[236:237]
	global_load_dwordx2 v[236:237], v243, s[70:71] offset:32
	v_pk_fma_f32 v[86:87], v[86:87], v[94:95], v[100:101]
	s_waitcnt lgkmcnt(0)
; __device__ __forceinline__ u32x2 pk4(f32x4 v) { u32x2 r; r.x = pk2(v.x, v.y); r.y = pk2(v.z, v.w); return r; }
;     __device__ __forceinline__ void operator()(const f32x4 (&acc)[2][2][4][2], const pg8::Unit& u, int wr, int wc, int fr, int fq) const {
;     ...
;                 for (int bj = 0; bj < 2; ++bj)
; #pragma unroll
;                     for (int n = 0; n < 2; ++n) {
;                         const int col = u.pn * 256 + bj * 128 + wc * 32 + n * 16 + fq * 4;
;                         const u32x2 raw = *(const u32x2*)(src + (size_t)row * DM + col);
;                         f32x4 x = (f32x4){bflo(raw.x), bfhi(raw.x), bflo(raw.y), bfhi(raw.y)};
;                         if (ln) x = (x - mu) * rs * *(const f32x4*)(g + col) + *(const f32x4*)(b + col);
;                         const u32x2 pz = pk4(x * ALPHA + acc[ai][bj][m][n]);
;                         *(u32x2*)(dst + (size_t)row * DM + col) = pz;
;                         const float z0 = bflo(pz.x), z1 = bfhi(pz.x), z2 = bflo(pz.y), z3 = bfhi(pz.y);
;                         s1 += (z0 + z1) + (z2 + z3); s2 += (z0 * z0 + z1 * z1) + (z2 * z2 + z3 * z3);
;                     }
;                 s1 += __shfl_xor(s1, 16); s2 += __shfl_xor(s2, 16); s1 += __shfl_xor(s1, 32); s2 += __shfl_xor(s2, 32);
;                 if (fq == 0) { float* p = stm_n + (size_t)row * 32 + (u.pn * 4 + wc) * 2; p[0] = s1; p[1] = s2; }
	v_lshlrev_b32_e32 v3, 16, v88
	v_pk_fma_f32 v[80:81], v[86:87], s[72:73], v[80:81] op_sel_hi:[1,0,1]
	v_cvt_pk_bf16_f32 v87, v82, v83
	v_cvt_pk_bf16_f32 v86, v80, v81
	v_and_b32_e32 v81, 0xffff0000, v88
	v_lshlrev_b32_e32 v83, 16, v89
	v_and_b32_e32 v90, 0xffff0000, v89
	v_mov_b64_e32 v[148:149], v[86:87]
	v_sub_f32_e32 v89, v81, v96
	v_sub_f32_e32 v88, v3, v96
	v_sub_f32_e32 v91, v90, v96
	v_sub_f32_e32 v90, v83, v96
	v_pk_mul_f32 v[94:95], v[98:99], v[90:91] op_sel_hi:[0,1]
	v_pk_mul_f32 v[104:105], v[98:99], v[88:89] op_sel_hi:[0,1]
	ds_read_b128 v[88:91], v244 offset:64
	ds_read_b128 v[100:103], v244 offset:320
	v_and_b32_e32 v82, 0xffff0000, v86
	v_lshlrev_b32_e32 v80, 16, v87
	s_waitcnt lgkmcnt(0)
	v_pk_fma_f32 v[88:89], v[88:89], v[104:105], v[100:101]
	s_nop 0
	v_pk_fma_f32 v[76:77], v[88:89], s[72:73], v[76:77] op_sel_hi:[1,0,1]
	s_waitcnt vmcnt(11)
	v_mov_b64_e32 v[88:89], v[238:239]
	global_load_dwordx2 v[238:239], v243, s[70:71] offset:256
	v_pk_fma_f32 v[90:91], v[90:91], v[94:95], v[102:103]
	v_cvt_pk_bf16_f32 v94, v76, v77
	v_pk_fma_f32 v[78:79], v[90:91], s[72:73], v[78:79] op_sel_hi:[1,0,1]
	s_waitcnt lgkmcnt(0)
	v_lshlrev_b32_e32 v3, 16, v88
	v_cvt_pk_bf16_f32 v95, v78, v79
	v_lshlrev_b32_e32 v78, 16, v95
	v_and_b32_e32 v79, 0xffff0000, v95
	v_mul_f32_e32 v76, v78, v78
	v_pk_fma_f32 v[76:77], v[78:79], v[78:79], v[76:77] op_sel_hi:[1,1,0]
	v_lshlrev_b32_e32 v81, 16, v89
	v_and_b32_e32 v76, 0xffff0000, v88
	v_and_b32_e32 v83, 0xffff0000, v89
	v_mov_b64_e32 v[150:151], v[94:95]
	v_lshrrev_b32_e32 v106, 4, v219
	v_lshlrev_b32_e32 v106, 3, v106
	v_mov_b32_e32 v107, v2
	v_permlane32_swap_b32_e32 v148, v150
	v_permlane32_swap_b32_e32 v149, v151
	v_lshl_add_u64 v[106:107], v[106:107], 0, v[92:93]
	s_nop 0
	v_permlane16_swap_b32_e32 v148, v150
	v_permlane16_swap_b32_e32 v149, v151
	global_store_dwordx4 v[106:107], v[148:151], off sc0
	v_sub_f32_e32 v89, v76, v96
	v_sub_f32_e32 v88, v3, v96
	v_sub_f32_e32 v91, v83, v96
	v_sub_f32_e32 v90, v81, v96
	v_pk_mul_f32 v[104:105], v[98:99], v[90:91] op_sel_hi:[0,1]
	v_pk_mul_f32 v[106:107], v[98:99], v[88:89] op_sel_hi:[0,1]
	ds_read_b128 v[88:91], v244 offset:128
	ds_read_b128 v[100:103], v244 offset:384
	v_and_b32_e32 v95, 0xffff0000, v94
	s_waitcnt lgkmcnt(0)
	v_pk_fma_f32 v[88:89], v[88:89], v[106:107], v[100:101]
	s_waitcnt vmcnt(11)
	v_mov_b64_e32 v[100:101], v[240:241]
	global_load_dwordx2 v[240:241], v243, s[70:71] offset:288
	v_pk_fma_f32 v[90:91], v[90:91], v[104:105], v[102:103]
	v_pk_fma_f32 v[72:73], v[88:89], s[72:73], v[72:73] op_sel_hi:[1,0,1]
	v_pk_fma_f32 v[74:75], v[90:91], s[72:73], v[74:75] op_sel_hi:[1,0,1]
	v_cvt_pk_bf16_f32 v72, v72, v73
	v_cvt_pk_bf16_f32 v73, v74, v75
	v_mov_b64_e32 v[148:149], v[72:73]
	v_lshlrev_b32_e32 v88, 16, v72
	v_and_b32_e32 v90, 0xffff0000, v72
	v_lshlrev_b32_e32 v72, 16, v73
	v_and_b32_e32 v74, 0xffff0000, v73
	v_mul_f32_e32 v89, v88, v88
	v_mul_f32_e32 v91, v90, v90
	v_mul_f32_e32 v73, v72, v72
	v_mul_f32_e32 v75, v74, v74
	v_pk_add_f32 v[72:73], v[72:73], v[74:75]
	s_waitcnt lgkmcnt(0)
	v_lshlrev_b32_e32 v3, 16, v100
	v_and_b32_e32 v76, 0xffff0000, v100
	v_lshlrev_b32_e32 v81, 16, v101
	v_and_b32_e32 v83, 0xffff0000, v101
	v_sub_f32_e32 v101, v76, v96
	v_sub_f32_e32 v100, v3, v96
	v_sub_f32_e32 v97, v83, v96
	v_sub_f32_e32 v96, v81, v96
	v_pk_mul_f32 v[96:97], v[98:99], v[96:97] op_sel_hi:[0,1]
	v_pk_mul_f32 v[98:99], v[98:99], v[100:101] op_sel_hi:[0,1]
	ds_read_b128 v[100:103], v244 offset:192
	ds_read_b128 v[104:107], v244 offset:448
	v_mov_b32_e32 v81, v95
	v_mov_b32_e32 v3, v77
	s_waitcnt lgkmcnt(0)
	v_pk_fma_f32 v[98:99], v[100:101], v[98:99], v[104:105]
	s_nop 0
	v_pk_fma_f32 v[68:69], v[98:99], s[72:73], v[68:69] op_sel_hi:[1,0,1]
	v_lshlrev_b32_e32 v99, 16, v94
	v_lshlrev_b32_e32 v98, 16, v86
	v_mov_b32_e32 v83, v99
	v_pk_fma_f32 v[96:97], v[102:103], v[96:97], v[106:107]
	v_pk_mul_f32 v[100:101], v[98:99], v[98:99]
	v_pk_mul_f32 v[102:103], v[82:83], v[82:83]
	v_and_b32_e32 v94, 0xffff0000, v87
	v_pk_mul_f32 v[86:87], v[80:81], v[80:81]
	v_pk_mul_f32 v[104:105], v[94:95], v[94:95]
	v_pk_mov_b32 v[106:107], v[98:99], v[100:101] op_sel:[1,0]
	v_pk_mov_b32 v[102:103], v[94:95], v[102:103] op_sel:[1,0]
	v_pk_add_f32 v[82:83], v[98:99], v[82:83]
	v_pk_add_f32 v[80:81], v[94:95], v[80:81]
	v_pk_fma_f32 v[70:71], v[96:97], s[72:73], v[70:71] op_sel_hi:[1,0,1]
	v_pk_add_f32 v[102:103], v[106:107], v[102:103]
	v_mov_b32_e32 v106, v78
	v_mov_b32_e32 v107, v86
	v_pk_mov_b32 v[78:79], v[78:79], v[104:105] op_sel:[1,0]
	v_mov_b32_e32 v83, v101
	v_mov_b32_e32 v81, v105
	v_cvt_pk_bf16_f32 v68, v68, v69
	v_cvt_pk_bf16_f32 v69, v70, v71
	v_pk_add_f32 v[78:79], v[106:107], v[78:79]
	v_pk_add_f32 v[80:81], v[82:83], v[80:81]
	v_mov_b64_e32 v[150:151], v[68:69]
	v_lshrrev_b32_e32 v152, 4, v219
	v_lshlrev_b32_e32 v152, 3, v152
	v_mov_b32_e32 v153, v2
	v_permlane32_swap_b32_e32 v148, v150
	v_permlane32_swap_b32_e32 v149, v151
	v_lshl_add_u64 v[152:153], v[152:153], 0, v[92:93]
	s_nop 0
	v_permlane16_swap_b32_e32 v148, v150
	v_permlane16_swap_b32_e32 v149, v151
	global_store_dwordx4 v[152:153], v[148:151], off offset:256 sc0
	v_lshlrev_b32_e32 v92, 16, v68
	v_and_b32_e32 v96, 0xffff0000, v68
	v_lshlrev_b32_e32 v68, 16, v69
	v_and_b32_e32 v70, 0xffff0000, v69
	v_pk_add_f32 v[78:79], v[102:103], v[78:79]
	v_pk_add_f32 v[76:77], v[80:81], v[2:3]
	v_mul_f32_e32 v93, v92, v92
	v_mul_f32_e32 v97, v96, v96
	v_mul_f32_e32 v69, v68, v68
	v_mul_f32_e32 v71, v70, v70
	v_pk_add_f32 v[76:77], v[78:79], v[76:77]
	v_pk_add_f32 v[78:79], v[88:89], v[90:91]
	v_pk_add_f32 v[74:75], v[92:93], v[96:97]
	v_pk_add_f32 v[72:73], v[78:79], v[72:73]
	v_pk_add_f32 v[68:69], v[68:69], v[70:71]
	v_pk_add_f32 v[72:73], v[76:77], v[72:73]
	v_pk_add_f32 v[68:69], v[74:75], v[68:69]
	s_nop 0
	v_pk_add_f32 v[68:69], v[72:73], v[68:69]
	ds_bpermute_b32 v70, v181, v68
	ds_bpermute_b32 v71, v181, v69
	s_waitcnt lgkmcnt(0)
	v_pk_add_f32 v[68:69], v[68:69], v[70:71]
	ds_bpermute_b32 v70, v180, v68
	ds_bpermute_b32 v71, v180, v69
	s_and_saveexec_b64 s[0:1], s[40:41]
	s_cbranch_execz .LBB0_2211
	v_lshl_add_u64 v[72:73], s[50:51], 0, v[84:85]
	v_lshl_add_u64 v[72:73], s[60:61], 2, v[72:73]
	s_waitcnt lgkmcnt(0)
	v_pk_add_f32 v[68:69], v[68:69], v[70:71]
	global_store_dwordx2 v[72:73], v[68:69], off
; __device__ __forceinline__ u32x2 pk4(f32x4 v) { u32x2 r; r.x = pk2(v.x, v.y); r.y = pk2(v.z, v.w); return r; }
; __device__ __forceinline__ void stats_main(const float* stm, int row, int fq, float& mu, float& rs) {
;     const f32x4* p = (const f32x4*)(stm + (size_t)row * 32 + fq * 8);
;     const f32x4 a = p[0], b = p[1];
;     float s1 = (a.x + a.z) + (b.x + b.z), s2 = (a.y + a.w) + (b.y + b.w);
;     s1 += __shfl_xor(s1, 16); s2 += __shfl_xor(s2, 16); s1 += __shfl_xor(s1, 32); s2 += __shfl_xor(s2, 32);
;     mu = s1 * (1.f / DM); rs = __builtin_amdgcn_rsqf(fmaxf(s2 * (1.f / DM) - mu * mu, 0.f) + LN_EPS);
; }
;     __device__ __forceinline__ void operator()(const f32x4 (&acc)[2][2][4][2], const pg8::Unit& u, int wr, int wc, int fr, int fq) const {
;     ...
;                 const int row = u.pm * 256 + ai * 128 + wr * 64 + m * 16 + fr;
;                 float mu = 0.f, rs = 1.f; if (ln) stats_main(stm_p, row, fq, mu, rs);
;                 float s1 = 0.f, s2 = 0.f;
; #pragma unroll
;                 for (int bj = 0; bj < 2; ++bj)
; #pragma unroll
;                     for (int n = 0; n < 2; ++n) {
;                         const int col = u.pn * 256 + bj * 128 + wc * 32 + n * 16 + fq * 4;
;                         const u32x2 raw = *(const u32x2*)(src + (size_t)row * DM + col);
;                         f32x4 x = (f32x4){bflo(raw.x), bfhi(raw.x), bflo(raw.y), bfhi(raw.y)};
;                         if (ln) x = (x - mu) * rs * *(const f32x4*)(g + col) + *(const f32x4*)(b + col);
;                         const u32x2 pz = pk4(x * ALPHA + acc[ai][bj][m][n]);
;                         *(u32x2*)(dst + (size_t)row * DM + col) = pz;
;                         const float z0 = bflo(pz.x), z1 = bfhi(pz.x), z2 = bflo(pz.y), z3 = bfhi(pz.y);
;                         s1 += (z0 + z1) + (z2 + z3); s2 += (z0 * z0 + z1 * z1) + (z2 * z2 + z3 * z3);
;                     }
;                 s1 += __shfl_xor(s1, 16); s2 += __shfl_xor(s2, 16); s1 += __shfl_xor(s1, 32); s2 += __shfl_xor(s2, 32);
;                 if (fq == 0) { float* p = stm_n + (size_t)row * 32 + (u.pn * 4 + wc) * 2; p[0] = s1; p[1] = s2; }
.LBB0_2211:
	s_or_b64 exec, exec, s[0:1]
	v_add_u32_e32 v78, 0x80, v146
	v_ashrrev_i32_e32 v79, 31, v78
	v_lshlrev_b64 v[68:69], 7, v[78:79]
	v_lshl_add_u64 v[74:75], v[134:135], 0, v[68:69]
	s_waitcnt lgkmcnt(0)
	s_waitcnt vmcnt(11)
	v_mov_b64_e32 v[70:71], v[190:191]
	v_mov_b64_e32 v[72:73], v[192:193]
	global_load_dwordx4 v[190:193], v[248:249], off offset:16
	s_nop 0
	s_waitcnt vmcnt(11)
	v_mov_b64_e32 v[74:75], v[194:195]
	v_mov_b64_e32 v[76:77], v[196:197]
	global_load_dwordx4 v[194:197], v[248:249], off
	s_waitcnt lgkmcnt(0)
	v_pk_add_f32 v[70:71], v[70:71], v[72:73]
	s_waitcnt lgkmcnt(0)
	v_pk_add_f32 v[74:75], v[74:75], v[76:77]
	s_nop 0
	v_pk_add_f32 v[70:71], v[74:75], v[70:71]
	ds_bpermute_b32 v72, v181, v70
	ds_bpermute_b32 v73, v181, v71
	s_waitcnt lgkmcnt(0)
	v_pk_add_f32 v[70:71], v[70:71], v[72:73]
	ds_bpermute_b32 v72, v180, v70
	ds_bpermute_b32 v73, v180, v71
	s_waitcnt lgkmcnt(0)
	v_pk_add_f32 v[70:71], v[70:71], v[72:73]
	s_nop 0
	v_pk_mul_f32 v[80:81], v[70:71], s[82:83] op_sel_hi:[1,0]
	v_lshlrev_b64 v[70:71], 11, v[78:79]
	v_lshl_add_u64 v[70:71], s[70:71], 0, v[70:71]
	v_lshl_add_u64 v[76:77], v[144:145], 1, v[70:71]
	v_add_u32_e32 v243, 0x50000, v242
	s_waitcnt vmcnt(11)
	v_mov_b64_e32 v[70:71], v[198:199]
	global_load_dwordx2 v[198:199], v243, s[70:71]
	v_fma_f32 v3, -v80, v80, v81
	v_max_f32_e32 v3, 0, v3
	v_add_f32_e32 v3, 0x3727c5ac, v3
	v_rsq_f32_e32 v82, v3
	s_waitcnt lgkmcnt(0)
	v_lshlrev_b32_e32 v3, 16, v70
	v_and_b32_e32 v70, 0xffff0000, v70
	v_lshlrev_b32_e32 v72, 16, v71
	v_and_b32_e32 v73, 0xffff0000, v71
	v_sub_f32_e32 v71, v70, v80
	v_sub_f32_e32 v70, v3, v80
	v_sub_f32_e32 v73, v73, v80
	v_sub_f32_e32 v72, v72, v80
	v_pk_mul_f32 v[74:75], v[72:73], v[82:83] op_sel_hi:[1,0]
	v_pk_mul_f32 v[78:79], v[70:71], v[82:83] op_sel_hi:[1,0]
	ds_read_b128 v[70:73], v244
	ds_read_b128 v[84:87], v244 offset:256
	s_waitcnt lgkmcnt(0)
	v_pk_fma_f32 v[72:73], v[72:73], v[74:75], v[86:87]
	s_nop 0
	v_pk_fma_f32 v[66:67], v[72:73], s[72:73], v[66:67] op_sel_hi:[1,0,1]
	s_waitcnt vmcnt(11)
	v_mov_b64_e32 v[72:73], v[200:201]
	global_load_dwordx2 v[200:201], v243, s[70:71] offset:32
	v_pk_fma_f32 v[70:71], v[70:71], v[78:79], v[84:85]
	s_waitcnt lgkmcnt(0)
	v_lshlrev_b32_e32 v3, 16, v72
	v_pk_fma_f32 v[64:65], v[70:71], s[72:73], v[64:65] op_sel_hi:[1,0,1]
	v_cvt_pk_bf16_f32 v71, v66, v67
	v_cvt_pk_bf16_f32 v70, v64, v65
	v_and_b32_e32 v65, 0xffff0000, v72
	v_lshlrev_b32_e32 v67, 16, v73
	v_and_b32_e32 v74, 0xffff0000, v73
	v_mov_b64_e32 v[148:149], v[70:71]
	v_sub_f32_e32 v73, v65, v80
	v_sub_f32_e32 v72, v3, v80
	v_sub_f32_e32 v75, v74, v80
	v_sub_f32_e32 v74, v67, v80
	v_pk_mul_f32 v[78:79], v[82:83], v[74:75] op_sel_hi:[0,1]
	v_pk_mul_f32 v[88:89], v[82:83], v[72:73] op_sel_hi:[0,1]
	ds_read_b128 v[72:75], v244 offset:64
	ds_read_b128 v[84:87], v244 offset:320
	v_and_b32_e32 v66, 0xffff0000, v70
	v_lshlrev_b32_e32 v64, 16, v71
	s_waitcnt lgkmcnt(0)
	v_pk_fma_f32 v[72:73], v[72:73], v[88:89], v[84:85]
	s_nop 0
	v_pk_fma_f32 v[60:61], v[72:73], s[72:73], v[60:61] op_sel_hi:[1,0,1]
	s_waitcnt vmcnt(11)
	v_mov_b64_e32 v[72:73], v[202:203]
	global_load_dwordx2 v[202:203], v243, s[70:71] offset:256
	v_pk_fma_f32 v[74:75], v[74:75], v[78:79], v[86:87]
	v_cvt_pk_bf16_f32 v78, v60, v61
	v_pk_fma_f32 v[62:63], v[74:75], s[72:73], v[62:63] op_sel_hi:[1,0,1]
	s_waitcnt lgkmcnt(0)
	v_lshlrev_b32_e32 v3, 16, v72
	v_cvt_pk_bf16_f32 v79, v62, v63
	v_lshlrev_b32_e32 v62, 16, v79
	v_and_b32_e32 v63, 0xffff0000, v79
	v_mul_f32_e32 v60, v62, v62
	v_pk_fma_f32 v[60:61], v[62:63], v[62:63], v[60:61] op_sel_hi:[1,1,0]
	v_lshlrev_b32_e32 v65, 16, v73
	v_and_b32_e32 v60, 0xffff0000, v72
	v_and_b32_e32 v67, 0xffff0000, v73
	v_mov_b64_e32 v[150:151], v[78:79]
	v_lshrrev_b32_e32 v90, 4, v219
	v_lshlrev_b32_e32 v90, 3, v90
	v_mov_b32_e32 v91, v2
	v_permlane32_swap_b32_e32 v148, v150
	v_permlane32_swap_b32_e32 v149, v151
	v_lshl_add_u64 v[90:91], v[90:91], 0, v[76:77]
	s_nop 0
	v_permlane16_swap_b32_e32 v148, v150
	v_permlane16_swap_b32_e32 v149, v151
	global_store_dwordx4 v[90:91], v[148:151], off sc0
	v_sub_f32_e32 v73, v60, v80
	v_sub_f32_e32 v72, v3, v80
	v_sub_f32_e32 v75, v67, v80
	v_sub_f32_e32 v74, v65, v80
	v_pk_mul_f32 v[88:89], v[82:83], v[74:75] op_sel_hi:[0,1]
	v_pk_mul_f32 v[90:91], v[82:83], v[72:73] op_sel_hi:[0,1]
	ds_read_b128 v[72:75], v244 offset:128
	ds_read_b128 v[84:87], v244 offset:384
	v_and_b32_e32 v79, 0xffff0000, v78
	s_waitcnt lgkmcnt(0)
	v_pk_fma_f32 v[72:73], v[72:73], v[90:91], v[84:85]
	s_waitcnt vmcnt(11)
	v_mov_b64_e32 v[84:85], v[204:205]
	global_load_dwordx2 v[204:205], v243, s[70:71] offset:288
	v_pk_fma_f32 v[74:75], v[74:75], v[88:89], v[86:87]
	v_pk_fma_f32 v[56:57], v[72:73], s[72:73], v[56:57] op_sel_hi:[1,0,1]
	v_pk_fma_f32 v[58:59], v[74:75], s[72:73], v[58:59] op_sel_hi:[1,0,1]
	v_cvt_pk_bf16_f32 v56, v56, v57
	v_cvt_pk_bf16_f32 v57, v58, v59
	v_mov_b64_e32 v[148:149], v[56:57]
	v_lshlrev_b32_e32 v72, 16, v56
	v_and_b32_e32 v74, 0xffff0000, v56
	v_lshlrev_b32_e32 v56, 16, v57
	v_and_b32_e32 v58, 0xffff0000, v57
	v_mul_f32_e32 v73, v72, v72
	v_mul_f32_e32 v75, v74, v74
	v_mul_f32_e32 v57, v56, v56
	v_mul_f32_e32 v59, v58, v58
	v_pk_add_f32 v[56:57], v[56:57], v[58:59]
	s_waitcnt lgkmcnt(0)
	v_lshlrev_b32_e32 v3, 16, v84
	v_and_b32_e32 v60, 0xffff0000, v84
	v_lshlrev_b32_e32 v65, 16, v85
	v_and_b32_e32 v67, 0xffff0000, v85
	v_sub_f32_e32 v85, v60, v80
	v_sub_f32_e32 v84, v3, v80
	v_sub_f32_e32 v81, v67, v80
	v_sub_f32_e32 v80, v65, v80
	v_pk_mul_f32 v[80:81], v[82:83], v[80:81] op_sel_hi:[0,1]
	v_pk_mul_f32 v[82:83], v[82:83], v[84:85] op_sel_hi:[0,1]
	ds_read_b128 v[84:87], v244 offset:192
	ds_read_b128 v[88:91], v244 offset:448
	v_mov_b32_e32 v65, v79
	v_mov_b32_e32 v3, v61
	s_waitcnt lgkmcnt(0)
; __device__ __forceinline__ u32x2 pk4(f32x4 v) { u32x2 r; r.x = pk2(v.x, v.y); r.y = pk2(v.z, v.w); return r; }
; __device__ __forceinline__ void stats_main(const float* stm, int row, int fq, float& mu, float& rs) {
;     const f32x4* p = (const f32x4*)(stm + (size_t)row * 32 + fq * 8);
;     const f32x4 a = p[0], b = p[1];
;     float s1 = (a.x + a.z) + (b.x + b.z), s2 = (a.y + a.w) + (b.y + b.w);
;     s1 += __shfl_xor(s1, 16); s2 += __shfl_xor(s2, 16); s1 += __shfl_xor(s1, 32); s2 += __shfl_xor(s2, 32);
;     mu = s1 * (1.f / DM); rs = __builtin_amdgcn_rsqf(fmaxf(s2 * (1.f / DM) - mu * mu, 0.f) + LN_EPS);
; }
;     __device__ __forceinline__ void operator()(const f32x4 (&acc)[2][2][4][2], const pg8::Unit& u, int wr, int wc, int fr, int fq) const {
;     ...
;                 for (int bj = 0; bj < 2; ++bj)
; #pragma unroll
;                     for (int n = 0; n < 2; ++n) {
;                         const int col = u.pn * 256 + bj * 128 + wc * 32 + n * 16 + fq * 4;
;                         const u32x2 raw = *(const u32x2*)(src + (size_t)row * DM + col);
;                         f32x4 x = (f32x4){bflo(raw.x), bfhi(raw.x), bflo(raw.y), bfhi(raw.y)};
;                         if (ln) x = (x - mu) * rs * *(const f32x4*)(g + col) + *(const f32x4*)(b + col);
;                         const u32x2 pz = pk4(x * ALPHA + acc[ai][bj][m][n]);
;                         *(u32x2*)(dst + (size_t)row * DM + col) = pz;
;                         const float z0 = bflo(pz.x), z1 = bfhi(pz.x), z2 = bflo(pz.y), z3 = bfhi(pz.y);
;                         s1 += (z0 + z1) + (z2 + z3); s2 += (z0 * z0 + z1 * z1) + (z2 * z2 + z3 * z3);
;                     }
;                 s1 += __shfl_xor(s1, 16); s2 += __shfl_xor(s2, 16); s1 += __shfl_xor(s1, 32); s2 += __shfl_xor(s2, 32);
;                 if (fq == 0) { float* p = stm_n + (size_t)row * 32 + (u.pn * 4 + wc) * 2; p[0] = s1; p[1] = s2; }
	v_pk_fma_f32 v[82:83], v[84:85], v[82:83], v[88:89]
	s_nop 0
	v_pk_fma_f32 v[52:53], v[82:83], s[72:73], v[52:53] op_sel_hi:[1,0,1]
	v_lshlrev_b32_e32 v83, 16, v78
	v_lshlrev_b32_e32 v82, 16, v70
	v_mov_b32_e32 v67, v83
	v_pk_fma_f32 v[80:81], v[86:87], v[80:81], v[90:91]
	v_pk_mul_f32 v[84:85], v[82:83], v[82:83]
	v_pk_mul_f32 v[86:87], v[66:67], v[66:67]
	v_and_b32_e32 v78, 0xffff0000, v71
	v_pk_mul_f32 v[70:71], v[64:65], v[64:65]
	v_pk_mul_f32 v[88:89], v[78:79], v[78:79]
	v_pk_mov_b32 v[90:91], v[82:83], v[84:85] op_sel:[1,0]
	v_pk_mov_b32 v[86:87], v[78:79], v[86:87] op_sel:[1,0]
	v_pk_add_f32 v[66:67], v[82:83], v[66:67]
	v_pk_add_f32 v[64:65], v[78:79], v[64:65]
	v_pk_fma_f32 v[54:55], v[80:81], s[72:73], v[54:55] op_sel_hi:[1,0,1]
	v_pk_add_f32 v[86:87], v[90:91], v[86:87]
	v_mov_b32_e32 v90, v62
	v_mov_b32_e32 v91, v70
	v_pk_mov_b32 v[62:63], v[62:63], v[88:89] op_sel:[1,0]
	v_mov_b32_e32 v67, v85
	v_mov_b32_e32 v65, v89
	v_cvt_pk_bf16_f32 v52, v52, v53
	v_cvt_pk_bf16_f32 v53, v54, v55
	v_pk_add_f32 v[62:63], v[90:91], v[62:63]
	v_pk_add_f32 v[64:65], v[66:67], v[64:65]
	v_mov_b64_e32 v[150:151], v[52:53]
	v_lshrrev_b32_e32 v152, 4, v219
	v_lshlrev_b32_e32 v152, 3, v152
	v_mov_b32_e32 v153, v2
	v_permlane32_swap_b32_e32 v148, v150
	v_permlane32_swap_b32_e32 v149, v151
	v_lshl_add_u64 v[152:153], v[152:153], 0, v[76:77]
	s_nop 0
	v_permlane16_swap_b32_e32 v148, v150
	v_permlane16_swap_b32_e32 v149, v151
	global_store_dwordx4 v[152:153], v[148:151], off offset:256 sc0
	v_lshlrev_b32_e32 v76, 16, v52
	v_and_b32_e32 v80, 0xffff0000, v52
	v_lshlrev_b32_e32 v52, 16, v53
	v_and_b32_e32 v54, 0xffff0000, v53
	v_pk_add_f32 v[62:63], v[86:87], v[62:63]
	v_pk_add_f32 v[60:61], v[64:65], v[2:3]
	v_mul_f32_e32 v77, v76, v76
	v_mul_f32_e32 v81, v80, v80
	v_mul_f32_e32 v53, v52, v52
	v_mul_f32_e32 v55, v54, v54
	v_pk_add_f32 v[60:61], v[62:63], v[60:61]
	v_pk_add_f32 v[62:63], v[72:73], v[74:75]
	v_pk_add_f32 v[58:59], v[76:77], v[80:81]
	v_pk_add_f32 v[56:57], v[62:63], v[56:57]
	v_pk_add_f32 v[52:53], v[52:53], v[54:55]
	v_pk_add_f32 v[56:57], v[60:61], v[56:57]
	v_pk_add_f32 v[52:53], v[58:59], v[52:53]
	s_nop 0
	v_pk_add_f32 v[52:53], v[56:57], v[52:53]
	ds_bpermute_b32 v54, v181, v52
	ds_bpermute_b32 v55, v181, v53
	s_waitcnt lgkmcnt(0)
	v_pk_add_f32 v[52:53], v[52:53], v[54:55]
	ds_bpermute_b32 v54, v180, v52
	ds_bpermute_b32 v55, v180, v53
	s_and_saveexec_b64 s[0:1], s[40:41]
	s_cbranch_execz .LBB0_2213
	v_lshl_add_u64 v[56:57], s[50:51], 0, v[68:69]
	v_lshl_add_u64 v[56:57], s[60:61], 2, v[56:57]
	s_waitcnt lgkmcnt(0)
	v_pk_add_f32 v[52:53], v[52:53], v[54:55]
	global_store_dwordx2 v[56:57], v[52:53], off
.LBB0_2213:
	s_or_b64 exec, exec, s[0:1]
	v_add_u32_e32 v62, 0x90, v146
	v_ashrrev_i32_e32 v63, 31, v62
	v_lshlrev_b64 v[52:53], 7, v[62:63]
	v_lshl_add_u64 v[58:59], v[134:135], 0, v[52:53]
	s_waitcnt lgkmcnt(0)
	s_waitcnt vmcnt(11)
	v_mov_b64_e32 v[54:55], v[206:207]
	v_mov_b64_e32 v[56:57], v[208:209]
	global_load_dwordx4 v[206:209], v[248:249], off offset:2064
	s_nop 0
	s_waitcnt vmcnt(11)
	v_mov_b64_e32 v[58:59], v[214:215]
	v_mov_b64_e32 v[60:61], v[216:217]
	global_load_dwordx4 v[214:217], v[248:249], off offset:2048
	s_waitcnt lgkmcnt(0)
	v_pk_add_f32 v[54:55], v[54:55], v[56:57]
	s_waitcnt lgkmcnt(0)
	v_pk_add_f32 v[58:59], v[58:59], v[60:61]
	s_nop 0
	v_pk_add_f32 v[54:55], v[58:59], v[54:55]
	ds_bpermute_b32 v56, v181, v54
	ds_bpermute_b32 v57, v181, v55
	s_waitcnt lgkmcnt(0)
	v_pk_add_f32 v[54:55], v[54:55], v[56:57]
	ds_bpermute_b32 v56, v180, v54
	ds_bpermute_b32 v57, v180, v55
	s_waitcnt lgkmcnt(0)
	v_pk_add_f32 v[54:55], v[54:55], v[56:57]
	s_nop 0
	v_pk_mul_f32 v[64:65], v[54:55], s[82:83] op_sel_hi:[1,0]
	v_lshlrev_b64 v[54:55], 11, v[62:63]
	v_lshl_add_u64 v[54:55], s[70:71], 0, v[54:55]
	v_lshl_add_u64 v[60:61], v[144:145], 1, v[54:55]
	v_add_u32_e32 v243, 0x58000, v242
	s_waitcnt vmcnt(11)
	v_mov_b64_e32 v[54:55], v[234:235]
	global_load_dwordx2 v[234:235], v243, s[70:71]
	v_fma_f32 v3, -v64, v64, v65
	v_max_f32_e32 v3, 0, v3
	v_add_f32_e32 v3, 0x3727c5ac, v3
	v_rsq_f32_e32 v66, v3
	s_waitcnt lgkmcnt(0)
	v_lshlrev_b32_e32 v3, 16, v54
	v_and_b32_e32 v54, 0xffff0000, v54
	v_lshlrev_b32_e32 v56, 16, v55
	v_and_b32_e32 v57, 0xffff0000, v55
	v_sub_f32_e32 v55, v54, v64
	v_sub_f32_e32 v54, v3, v64
	v_sub_f32_e32 v57, v57, v64
	v_sub_f32_e32 v56, v56, v64
	v_pk_mul_f32 v[58:59], v[56:57], v[66:67] op_sel_hi:[1,0]
	v_pk_mul_f32 v[62:63], v[54:55], v[66:67] op_sel_hi:[1,0]
	ds_read_b128 v[54:57], v244
	ds_read_b128 v[68:71], v244 offset:256
	s_waitcnt lgkmcnt(0)
	v_pk_fma_f32 v[56:57], v[56:57], v[58:59], v[70:71]
	s_nop 0
	v_pk_fma_f32 v[50:51], v[56:57], s[72:73], v[50:51] op_sel_hi:[1,0,1]
	s_waitcnt vmcnt(11)
	v_mov_b64_e32 v[56:57], v[236:237]
	global_load_dwordx2 v[236:237], v243, s[70:71] offset:32
	v_pk_fma_f32 v[54:55], v[54:55], v[62:63], v[68:69]
	s_waitcnt lgkmcnt(0)
	v_lshlrev_b32_e32 v3, 16, v56
	v_pk_fma_f32 v[48:49], v[54:55], s[72:73], v[48:49] op_sel_hi:[1,0,1]
	v_cvt_pk_bf16_f32 v55, v50, v51
	v_cvt_pk_bf16_f32 v54, v48, v49
	v_and_b32_e32 v49, 0xffff0000, v56
	v_lshlrev_b32_e32 v51, 16, v57
	v_and_b32_e32 v58, 0xffff0000, v57
	v_mov_b64_e32 v[148:149], v[54:55]
	v_sub_f32_e32 v57, v49, v64
	v_sub_f32_e32 v56, v3, v64
	v_sub_f32_e32 v59, v58, v64
	v_sub_f32_e32 v58, v51, v64
	v_pk_mul_f32 v[62:63], v[66:67], v[58:59] op_sel_hi:[0,1]
	v_pk_mul_f32 v[72:73], v[66:67], v[56:57] op_sel_hi:[0,1]
	ds_read_b128 v[56:59], v244 offset:64
	ds_read_b128 v[68:71], v244 offset:320
	v_and_b32_e32 v50, 0xffff0000, v54
	v_lshlrev_b32_e32 v48, 16, v55
	s_waitcnt lgkmcnt(0)
; __device__ __forceinline__ u32x2 pk4(f32x4 v) { u32x2 r; r.x = pk2(v.x, v.y); r.y = pk2(v.z, v.w); return r; }
;     __device__ __forceinline__ void operator()(const f32x4 (&acc)[2][2][4][2], const pg8::Unit& u, int wr, int wc, int fr, int fq) const {
;     ...
;                 for (int bj = 0; bj < 2; ++bj)
; #pragma unroll
;                     for (int n = 0; n < 2; ++n) {
;                         const int col = u.pn * 256 + bj * 128 + wc * 32 + n * 16 + fq * 4;
;                         const u32x2 raw = *(const u32x2*)(src + (size_t)row * DM + col);
;                         f32x4 x = (f32x4){bflo(raw.x), bfhi(raw.x), bflo(raw.y), bfhi(raw.y)};
;                         if (ln) x = (x - mu) * rs * *(const f32x4*)(g + col) + *(const f32x4*)(b + col);
;                         const u32x2 pz = pk4(x * ALPHA + acc[ai][bj][m][n]);
;                         *(u32x2*)(dst + (size_t)row * DM + col) = pz;
;                         const float z0 = bflo(pz.x), z1 = bfhi(pz.x), z2 = bflo(pz.y), z3 = bfhi(pz.y);
;                         s1 += (z0 + z1) + (z2 + z3); s2 += (z0 * z0 + z1 * z1) + (z2 * z2 + z3 * z3);
;                     }
;                 s1 += __shfl_xor(s1, 16); s2 += __shfl_xor(s2, 16); s1 += __shfl_xor(s1, 32); s2 += __shfl_xor(s2, 32);
;                 if (fq == 0) { float* p = stm_n + (size_t)row * 32 + (u.pn * 4 + wc) * 2; p[0] = s1; p[1] = s2; }
	v_pk_fma_f32 v[56:57], v[56:57], v[72:73], v[68:69]
	s_nop 0
	v_pk_fma_f32 v[44:45], v[56:57], s[72:73], v[44:45] op_sel_hi:[1,0,1]
	s_waitcnt vmcnt(11)
	v_mov_b64_e32 v[56:57], v[238:239]
	global_load_dwordx2 v[238:239], v243, s[70:71] offset:256
	v_pk_fma_f32 v[58:59], v[58:59], v[62:63], v[70:71]
	v_cvt_pk_bf16_f32 v62, v44, v45
	v_pk_fma_f32 v[46:47], v[58:59], s[72:73], v[46:47] op_sel_hi:[1,0,1]
	s_waitcnt lgkmcnt(0)
	v_lshlrev_b32_e32 v3, 16, v56
	v_cvt_pk_bf16_f32 v63, v46, v47
	v_lshlrev_b32_e32 v46, 16, v63
	v_and_b32_e32 v47, 0xffff0000, v63
	v_mul_f32_e32 v44, v46, v46
	v_pk_fma_f32 v[44:45], v[46:47], v[46:47], v[44:45] op_sel_hi:[1,1,0]
	v_lshlrev_b32_e32 v49, 16, v57
	v_and_b32_e32 v44, 0xffff0000, v56
	v_and_b32_e32 v51, 0xffff0000, v57
	v_mov_b64_e32 v[150:151], v[62:63]
	v_lshrrev_b32_e32 v74, 4, v219
	v_lshlrev_b32_e32 v74, 3, v74
	v_mov_b32_e32 v75, v2
	v_permlane32_swap_b32_e32 v148, v150
	v_permlane32_swap_b32_e32 v149, v151
	v_lshl_add_u64 v[74:75], v[74:75], 0, v[60:61]
	s_nop 0
	v_permlane16_swap_b32_e32 v148, v150
	v_permlane16_swap_b32_e32 v149, v151
	global_store_dwordx4 v[74:75], v[148:151], off sc0
	v_sub_f32_e32 v57, v44, v64
	v_sub_f32_e32 v56, v3, v64
	v_sub_f32_e32 v59, v51, v64
	v_sub_f32_e32 v58, v49, v64
	v_pk_mul_f32 v[72:73], v[66:67], v[58:59] op_sel_hi:[0,1]
	v_pk_mul_f32 v[74:75], v[66:67], v[56:57] op_sel_hi:[0,1]
	ds_read_b128 v[56:59], v244 offset:128
	ds_read_b128 v[68:71], v244 offset:384
	v_and_b32_e32 v63, 0xffff0000, v62
	s_waitcnt lgkmcnt(0)
	v_pk_fma_f32 v[56:57], v[56:57], v[74:75], v[68:69]
	s_waitcnt vmcnt(11)
	v_mov_b64_e32 v[68:69], v[240:241]
	global_load_dwordx2 v[240:241], v243, s[70:71] offset:288
	v_pk_fma_f32 v[58:59], v[58:59], v[72:73], v[70:71]
	v_pk_fma_f32 v[40:41], v[56:57], s[72:73], v[40:41] op_sel_hi:[1,0,1]
	v_pk_fma_f32 v[42:43], v[58:59], s[72:73], v[42:43] op_sel_hi:[1,0,1]
	v_cvt_pk_bf16_f32 v40, v40, v41
	v_cvt_pk_bf16_f32 v41, v42, v43
	v_mov_b64_e32 v[148:149], v[40:41]
	v_lshlrev_b32_e32 v56, 16, v40
	v_and_b32_e32 v58, 0xffff0000, v40
	v_lshlrev_b32_e32 v40, 16, v41
	v_and_b32_e32 v42, 0xffff0000, v41
	v_mul_f32_e32 v57, v56, v56
	v_mul_f32_e32 v59, v58, v58
	v_mul_f32_e32 v41, v40, v40
	v_mul_f32_e32 v43, v42, v42
	v_pk_add_f32 v[40:41], v[40:41], v[42:43]
	s_waitcnt lgkmcnt(0)
	v_lshlrev_b32_e32 v3, 16, v68
	v_and_b32_e32 v44, 0xffff0000, v68
	v_lshlrev_b32_e32 v49, 16, v69
	v_and_b32_e32 v51, 0xffff0000, v69
	v_sub_f32_e32 v69, v44, v64
	v_sub_f32_e32 v68, v3, v64
	v_sub_f32_e32 v65, v51, v64
	v_sub_f32_e32 v64, v49, v64
	v_pk_mul_f32 v[64:65], v[66:67], v[64:65] op_sel_hi:[0,1]
	v_pk_mul_f32 v[66:67], v[66:67], v[68:69] op_sel_hi:[0,1]
	ds_read_b128 v[68:71], v244 offset:192
	ds_read_b128 v[72:75], v244 offset:448
	v_mov_b32_e32 v49, v63
	v_mov_b32_e32 v3, v45
	s_waitcnt lgkmcnt(0)
	v_pk_fma_f32 v[66:67], v[68:69], v[66:67], v[72:73]
	s_nop 0
	v_pk_fma_f32 v[36:37], v[66:67], s[72:73], v[36:37] op_sel_hi:[1,0,1]
	v_lshlrev_b32_e32 v67, 16, v62
	v_lshlrev_b32_e32 v66, 16, v54
	v_mov_b32_e32 v51, v67
	v_pk_fma_f32 v[64:65], v[70:71], v[64:65], v[74:75]
	v_pk_mul_f32 v[68:69], v[66:67], v[66:67]
	v_pk_mul_f32 v[70:71], v[50:51], v[50:51]
	v_and_b32_e32 v62, 0xffff0000, v55
	v_pk_mul_f32 v[54:55], v[48:49], v[48:49]
	v_pk_mul_f32 v[72:73], v[62:63], v[62:63]
	v_pk_mov_b32 v[74:75], v[66:67], v[68:69] op_sel:[1,0]
	v_pk_mov_b32 v[70:71], v[62:63], v[70:71] op_sel:[1,0]
	v_pk_add_f32 v[50:51], v[66:67], v[50:51]
	v_pk_add_f32 v[48:49], v[62:63], v[48:49]
	v_pk_fma_f32 v[38:39], v[64:65], s[72:73], v[38:39] op_sel_hi:[1,0,1]
	v_pk_add_f32 v[70:71], v[74:75], v[70:71]
	v_mov_b32_e32 v74, v46
	v_mov_b32_e32 v75, v54
	v_pk_mov_b32 v[46:47], v[46:47], v[72:73] op_sel:[1,0]
	v_mov_b32_e32 v51, v69
	v_mov_b32_e32 v49, v73
	v_cvt_pk_bf16_f32 v36, v36, v37
	v_cvt_pk_bf16_f32 v37, v38, v39
	v_pk_add_f32 v[46:47], v[74:75], v[46:47]
	v_pk_add_f32 v[48:49], v[50:51], v[48:49]
	v_mov_b64_e32 v[150:151], v[36:37]
	v_lshrrev_b32_e32 v152, 4, v219
	v_lshlrev_b32_e32 v152, 3, v152
	v_mov_b32_e32 v153, v2
	v_permlane32_swap_b32_e32 v148, v150
	v_permlane32_swap_b32_e32 v149, v151
	v_lshl_add_u64 v[152:153], v[152:153], 0, v[60:61]
	s_nop 0
	v_permlane16_swap_b32_e32 v148, v150
	v_permlane16_swap_b32_e32 v149, v151
	global_store_dwordx4 v[152:153], v[148:151], off offset:256 sc0
	v_lshlrev_b32_e32 v60, 16, v36
	v_and_b32_e32 v64, 0xffff0000, v36
	v_lshlrev_b32_e32 v36, 16, v37
	v_and_b32_e32 v38, 0xffff0000, v37
	v_pk_add_f32 v[46:47], v[70:71], v[46:47]
	v_pk_add_f32 v[44:45], v[48:49], v[2:3]
	v_mul_f32_e32 v61, v60, v60
	v_mul_f32_e32 v65, v64, v64
	v_mul_f32_e32 v37, v36, v36
	v_mul_f32_e32 v39, v38, v38
	v_pk_add_f32 v[44:45], v[46:47], v[44:45]
	v_pk_add_f32 v[46:47], v[56:57], v[58:59]
	v_pk_add_f32 v[42:43], v[60:61], v[64:65]
	v_pk_add_f32 v[40:41], v[46:47], v[40:41]
	v_pk_add_f32 v[36:37], v[36:37], v[38:39]
	v_pk_add_f32 v[40:41], v[44:45], v[40:41]
	v_pk_add_f32 v[36:37], v[42:43], v[36:37]
	s_nop 0
	v_pk_add_f32 v[36:37], v[40:41], v[36:37]
	ds_bpermute_b32 v38, v181, v36
	ds_bpermute_b32 v39, v181, v37
	s_waitcnt lgkmcnt(0)
	v_pk_add_f32 v[36:37], v[36:37], v[38:39]
	ds_bpermute_b32 v38, v180, v36
	ds_bpermute_b32 v39, v180, v37
	s_and_saveexec_b64 s[0:1], s[40:41]
	s_cbranch_execz .LBB0_2215
	v_lshl_add_u64 v[40:41], s[50:51], 0, v[52:53]
	v_lshl_add_u64 v[40:41], s[60:61], 2, v[40:41]
	s_waitcnt lgkmcnt(0)
	v_pk_add_f32 v[36:37], v[36:37], v[38:39]
	global_store_dwordx2 v[40:41], v[36:37], off
; __device__ __forceinline__ u32x2 pk4(f32x4 v) { u32x2 r; r.x = pk2(v.x, v.y); r.y = pk2(v.z, v.w); return r; }
; __device__ __forceinline__ void stats_main(const float* stm, int row, int fq, float& mu, float& rs) {
;     const f32x4* p = (const f32x4*)(stm + (size_t)row * 32 + fq * 8);
;     const f32x4 a = p[0], b = p[1];
;     float s1 = (a.x + a.z) + (b.x + b.z), s2 = (a.y + a.w) + (b.y + b.w);
;     s1 += __shfl_xor(s1, 16); s2 += __shfl_xor(s2, 16); s1 += __shfl_xor(s1, 32); s2 += __shfl_xor(s2, 32);
;     mu = s1 * (1.f / DM); rs = __builtin_amdgcn_rsqf(fmaxf(s2 * (1.f / DM) - mu * mu, 0.f) + LN_EPS);
; }
;     __device__ __forceinline__ void operator()(const f32x4 (&acc)[2][2][4][2], const pg8::Unit& u, int wr, int wc, int fr, int fq) const {
;     ...
;                 const int row = u.pm * 256 + ai * 128 + wr * 64 + m * 16 + fr;
;                 float mu = 0.f, rs = 1.f; if (ln) stats_main(stm_p, row, fq, mu, rs);
;                 float s1 = 0.f, s2 = 0.f;
; #pragma unroll
;                 for (int bj = 0; bj < 2; ++bj)
; #pragma unroll
;                     for (int n = 0; n < 2; ++n) {
;                         const int col = u.pn * 256 + bj * 128 + wc * 32 + n * 16 + fq * 4;
;                         const u32x2 raw = *(const u32x2*)(src + (size_t)row * DM + col);
;                         f32x4 x = (f32x4){bflo(raw.x), bfhi(raw.x), bflo(raw.y), bfhi(raw.y)};
;                         if (ln) x = (x - mu) * rs * *(const f32x4*)(g + col) + *(const f32x4*)(b + col);
;                         const u32x2 pz = pk4(x * ALPHA + acc[ai][bj][m][n]);
;                         *(u32x2*)(dst + (size_t)row * DM + col) = pz;
;                         const float z0 = bflo(pz.x), z1 = bfhi(pz.x), z2 = bflo(pz.y), z3 = bfhi(pz.y);
;                         s1 += (z0 + z1) + (z2 + z3); s2 += (z0 * z0 + z1 * z1) + (z2 * z2 + z3 * z3);
;                     }
;                 s1 += __shfl_xor(s1, 16); s2 += __shfl_xor(s2, 16); s1 += __shfl_xor(s1, 32); s2 += __shfl_xor(s2, 32);
;                 if (fq == 0) { float* p = stm_n + (size_t)row * 32 + (u.pn * 4 + wc) * 2; p[0] = s1; p[1] = s2; }
.LBB0_2215:
	s_or_b64 exec, exec, s[0:1]
	v_add_u32_e32 v46, 0xa0, v146
	v_ashrrev_i32_e32 v47, 31, v46
	v_lshlrev_b64 v[36:37], 7, v[46:47]
	v_lshl_add_u64 v[42:43], v[134:135], 0, v[36:37]
	s_waitcnt lgkmcnt(0)
	s_waitcnt vmcnt(11)
	v_mov_b64_e32 v[38:39], v[190:191]
	v_mov_b64_e32 v[40:41], v[192:193]
	s_nop 0
	s_waitcnt vmcnt(10)
	v_mov_b64_e32 v[42:43], v[194:195]
	v_mov_b64_e32 v[44:45], v[196:197]
	s_waitcnt lgkmcnt(0)
	v_pk_add_f32 v[38:39], v[38:39], v[40:41]
	s_waitcnt lgkmcnt(0)
	v_pk_add_f32 v[42:43], v[42:43], v[44:45]
	s_nop 0
	v_pk_add_f32 v[38:39], v[42:43], v[38:39]
	ds_bpermute_b32 v40, v181, v38
	ds_bpermute_b32 v41, v181, v39
	s_waitcnt lgkmcnt(0)
	v_pk_add_f32 v[38:39], v[38:39], v[40:41]
	ds_bpermute_b32 v40, v180, v38
	ds_bpermute_b32 v41, v180, v39
	s_waitcnt lgkmcnt(0)
	v_pk_add_f32 v[38:39], v[38:39], v[40:41]
	s_nop 0
	v_pk_mul_f32 v[48:49], v[38:39], s[82:83] op_sel_hi:[1,0]
	v_lshlrev_b64 v[38:39], 11, v[46:47]
	v_lshl_add_u64 v[38:39], s[70:71], 0, v[38:39]
	v_lshl_add_u64 v[44:45], v[144:145], 1, v[38:39]
	s_waitcnt vmcnt(9)
	v_mov_b64_e32 v[38:39], v[198:199]
	v_fma_f32 v3, -v48, v48, v49
	v_max_f32_e32 v3, 0, v3
	v_add_f32_e32 v3, 0x3727c5ac, v3
	v_rsq_f32_e32 v50, v3
	s_waitcnt lgkmcnt(0)
	v_lshlrev_b32_e32 v3, 16, v38
	v_and_b32_e32 v38, 0xffff0000, v38
	v_lshlrev_b32_e32 v40, 16, v39
	v_and_b32_e32 v41, 0xffff0000, v39
	v_sub_f32_e32 v39, v38, v48
	v_sub_f32_e32 v38, v3, v48
	v_sub_f32_e32 v41, v41, v48
	v_sub_f32_e32 v40, v40, v48
	v_pk_mul_f32 v[42:43], v[40:41], v[50:51] op_sel_hi:[1,0]
	v_pk_mul_f32 v[46:47], v[38:39], v[50:51] op_sel_hi:[1,0]
	ds_read_b128 v[38:41], v244
	ds_read_b128 v[52:55], v244 offset:256
	s_waitcnt lgkmcnt(0)
	v_pk_fma_f32 v[40:41], v[40:41], v[42:43], v[54:55]
	s_nop 0
	v_pk_fma_f32 v[34:35], v[40:41], s[72:73], v[34:35] op_sel_hi:[1,0,1]
	s_waitcnt vmcnt(8)
	v_mov_b64_e32 v[40:41], v[200:201]
	v_pk_fma_f32 v[38:39], v[38:39], v[46:47], v[52:53]
	s_waitcnt lgkmcnt(0)
	v_lshlrev_b32_e32 v3, 16, v40
	v_pk_fma_f32 v[32:33], v[38:39], s[72:73], v[32:33] op_sel_hi:[1,0,1]
	v_cvt_pk_bf16_f32 v39, v34, v35
	v_cvt_pk_bf16_f32 v38, v32, v33
	v_and_b32_e32 v33, 0xffff0000, v40
	v_lshlrev_b32_e32 v35, 16, v41
	v_and_b32_e32 v42, 0xffff0000, v41
	v_mov_b64_e32 v[148:149], v[38:39]
	v_sub_f32_e32 v41, v33, v48
	v_sub_f32_e32 v40, v3, v48
	v_sub_f32_e32 v43, v42, v48
	v_sub_f32_e32 v42, v35, v48
	v_pk_mul_f32 v[46:47], v[50:51], v[42:43] op_sel_hi:[0,1]
	v_pk_mul_f32 v[56:57], v[50:51], v[40:41] op_sel_hi:[0,1]
	ds_read_b128 v[40:43], v244 offset:64
	ds_read_b128 v[52:55], v244 offset:320
	v_and_b32_e32 v34, 0xffff0000, v38
	v_lshlrev_b32_e32 v32, 16, v39
	s_waitcnt lgkmcnt(0)
	v_pk_fma_f32 v[40:41], v[40:41], v[56:57], v[52:53]
	s_nop 0
	v_pk_fma_f32 v[28:29], v[40:41], s[72:73], v[28:29] op_sel_hi:[1,0,1]
	s_waitcnt vmcnt(7)
	v_mov_b64_e32 v[40:41], v[202:203]
	v_pk_fma_f32 v[42:43], v[42:43], v[46:47], v[54:55]
	v_cvt_pk_bf16_f32 v46, v28, v29
	v_pk_fma_f32 v[30:31], v[42:43], s[72:73], v[30:31] op_sel_hi:[1,0,1]
	s_waitcnt lgkmcnt(0)
	v_lshlrev_b32_e32 v3, 16, v40
	v_cvt_pk_bf16_f32 v47, v30, v31
	v_lshlrev_b32_e32 v30, 16, v47
	v_and_b32_e32 v31, 0xffff0000, v47
	v_mul_f32_e32 v28, v30, v30
	v_pk_fma_f32 v[28:29], v[30:31], v[30:31], v[28:29] op_sel_hi:[1,1,0]
	v_lshlrev_b32_e32 v33, 16, v41
	v_and_b32_e32 v28, 0xffff0000, v40
	v_and_b32_e32 v35, 0xffff0000, v41
	v_mov_b64_e32 v[150:151], v[46:47]
	v_lshrrev_b32_e32 v58, 4, v219
	v_lshlrev_b32_e32 v58, 3, v58
	v_mov_b32_e32 v59, v2
	v_permlane32_swap_b32_e32 v148, v150
	v_permlane32_swap_b32_e32 v149, v151
	v_lshl_add_u64 v[58:59], v[58:59], 0, v[44:45]
	s_nop 0
	v_permlane16_swap_b32_e32 v148, v150
	v_permlane16_swap_b32_e32 v149, v151
	global_store_dwordx4 v[58:59], v[148:151], off sc0
	v_sub_f32_e32 v41, v28, v48
	v_sub_f32_e32 v40, v3, v48
	v_sub_f32_e32 v43, v35, v48
	v_sub_f32_e32 v42, v33, v48
	v_pk_mul_f32 v[56:57], v[50:51], v[42:43] op_sel_hi:[0,1]
	v_pk_mul_f32 v[58:59], v[50:51], v[40:41] op_sel_hi:[0,1]
	ds_read_b128 v[40:43], v244 offset:128
	ds_read_b128 v[52:55], v244 offset:384
	v_and_b32_e32 v47, 0xffff0000, v46
	s_waitcnt lgkmcnt(0)
	v_pk_fma_f32 v[40:41], v[40:41], v[58:59], v[52:53]
	s_waitcnt vmcnt(6)
	v_mov_b64_e32 v[52:53], v[204:205]
	v_pk_fma_f32 v[42:43], v[42:43], v[56:57], v[54:55]
	v_pk_fma_f32 v[24:25], v[40:41], s[72:73], v[24:25] op_sel_hi:[1,0,1]
	v_pk_fma_f32 v[26:27], v[42:43], s[72:73], v[26:27] op_sel_hi:[1,0,1]
	v_cvt_pk_bf16_f32 v24, v24, v25
	v_cvt_pk_bf16_f32 v25, v26, v27
	v_mov_b64_e32 v[148:149], v[24:25]
	v_lshlrev_b32_e32 v40, 16, v24
	v_and_b32_e32 v42, 0xffff0000, v24
	v_lshlrev_b32_e32 v24, 16, v25
	v_and_b32_e32 v26, 0xffff0000, v25
	v_mul_f32_e32 v41, v40, v40
	v_mul_f32_e32 v43, v42, v42
	v_mul_f32_e32 v25, v24, v24
	v_mul_f32_e32 v27, v26, v26
	v_pk_add_f32 v[24:25], v[24:25], v[26:27]
	s_waitcnt lgkmcnt(0)
	v_lshlrev_b32_e32 v3, 16, v52
	v_and_b32_e32 v28, 0xffff0000, v52
	v_lshlrev_b32_e32 v33, 16, v53
	v_and_b32_e32 v35, 0xffff0000, v53
	v_sub_f32_e32 v53, v28, v48
	v_sub_f32_e32 v52, v3, v48
	v_sub_f32_e32 v49, v35, v48
	v_sub_f32_e32 v48, v33, v48
	v_pk_mul_f32 v[48:49], v[50:51], v[48:49] op_sel_hi:[0,1]
	v_pk_mul_f32 v[50:51], v[50:51], v[52:53] op_sel_hi:[0,1]
	ds_read_b128 v[52:55], v244 offset:192
	ds_read_b128 v[56:59], v244 offset:448
	v_mov_b32_e32 v33, v47
	v_mov_b32_e32 v3, v29
	s_waitcnt lgkmcnt(0)
; __device__ __forceinline__ u32x2 pk4(f32x4 v) { u32x2 r; r.x = pk2(v.x, v.y); r.y = pk2(v.z, v.w); return r; }
; __device__ __forceinline__ void stats_main(const float* stm, int row, int fq, float& mu, float& rs) {
;     const f32x4* p = (const f32x4*)(stm + (size_t)row * 32 + fq * 8);
;     const f32x4 a = p[0], b = p[1];
;     float s1 = (a.x + a.z) + (b.x + b.z), s2 = (a.y + a.w) + (b.y + b.w);
;     s1 += __shfl_xor(s1, 16); s2 += __shfl_xor(s2, 16); s1 += __shfl_xor(s1, 32); s2 += __shfl_xor(s2, 32);
;     mu = s1 * (1.f / DM); rs = __builtin_amdgcn_rsqf(fmaxf(s2 * (1.f / DM) - mu * mu, 0.f) + LN_EPS);
; }
;     __device__ __forceinline__ void operator()(const f32x4 (&acc)[2][2][4][2], const pg8::Unit& u, int wr, int wc, int fr, int fq) const {
;     ...
;                 for (int bj = 0; bj < 2; ++bj)
; #pragma unroll
;                     for (int n = 0; n < 2; ++n) {
;                         const int col = u.pn * 256 + bj * 128 + wc * 32 + n * 16 + fq * 4;
;                         const u32x2 raw = *(const u32x2*)(src + (size_t)row * DM + col);
;                         f32x4 x = (f32x4){bflo(raw.x), bfhi(raw.x), bflo(raw.y), bfhi(raw.y)};
;                         if (ln) x = (x - mu) * rs * *(const f32x4*)(g + col) + *(const f32x4*)(b + col);
;                         const u32x2 pz = pk4(x * ALPHA + acc[ai][bj][m][n]);
;                         *(u32x2*)(dst + (size_t)row * DM + col) = pz;
;                         const float z0 = bflo(pz.x), z1 = bfhi(pz.x), z2 = bflo(pz.y), z3 = bfhi(pz.y);
;                         s1 += (z0 + z1) + (z2 + z3); s2 += (z0 * z0 + z1 * z1) + (z2 * z2 + z3 * z3);
;                     }
;                 s1 += __shfl_xor(s1, 16); s2 += __shfl_xor(s2, 16); s1 += __shfl_xor(s1, 32); s2 += __shfl_xor(s2, 32);
;                 if (fq == 0) { float* p = stm_n + (size_t)row * 32 + (u.pn * 4 + wc) * 2; p[0] = s1; p[1] = s2; }
	v_pk_fma_f32 v[50:51], v[52:53], v[50:51], v[56:57]
	s_nop 0
	v_pk_fma_f32 v[20:21], v[50:51], s[72:73], v[20:21] op_sel_hi:[1,0,1]
	v_lshlrev_b32_e32 v51, 16, v46
	v_lshlrev_b32_e32 v50, 16, v38
	v_mov_b32_e32 v35, v51
	v_pk_fma_f32 v[48:49], v[54:55], v[48:49], v[58:59]
	v_pk_mul_f32 v[52:53], v[50:51], v[50:51]
	v_pk_mul_f32 v[54:55], v[34:35], v[34:35]
	v_and_b32_e32 v46, 0xffff0000, v39
	v_pk_mul_f32 v[38:39], v[32:33], v[32:33]
	v_pk_mul_f32 v[56:57], v[46:47], v[46:47]
	v_pk_mov_b32 v[58:59], v[50:51], v[52:53] op_sel:[1,0]
	v_pk_mov_b32 v[54:55], v[46:47], v[54:55] op_sel:[1,0]
	v_pk_add_f32 v[34:35], v[50:51], v[34:35]
	v_pk_add_f32 v[32:33], v[46:47], v[32:33]
	v_pk_fma_f32 v[22:23], v[48:49], s[72:73], v[22:23] op_sel_hi:[1,0,1]
	v_pk_add_f32 v[54:55], v[58:59], v[54:55]
	v_mov_b32_e32 v58, v30
	v_mov_b32_e32 v59, v38
	v_pk_mov_b32 v[30:31], v[30:31], v[56:57] op_sel:[1,0]
	v_mov_b32_e32 v35, v53
	v_mov_b32_e32 v33, v57
	v_cvt_pk_bf16_f32 v20, v20, v21
	v_cvt_pk_bf16_f32 v21, v22, v23
	v_pk_add_f32 v[30:31], v[58:59], v[30:31]
	v_pk_add_f32 v[32:33], v[34:35], v[32:33]
	v_mov_b64_e32 v[150:151], v[20:21]
	v_lshrrev_b32_e32 v152, 4, v219
	v_lshlrev_b32_e32 v152, 3, v152
	v_mov_b32_e32 v153, v2
	v_permlane32_swap_b32_e32 v148, v150
	v_permlane32_swap_b32_e32 v149, v151
	v_lshl_add_u64 v[152:153], v[152:153], 0, v[44:45]
	s_nop 0
	v_permlane16_swap_b32_e32 v148, v150
	v_permlane16_swap_b32_e32 v149, v151
	global_store_dwordx4 v[152:153], v[148:151], off offset:256 sc0
	v_lshlrev_b32_e32 v44, 16, v20
	v_and_b32_e32 v48, 0xffff0000, v20
	v_lshlrev_b32_e32 v20, 16, v21
	v_and_b32_e32 v22, 0xffff0000, v21
	v_pk_add_f32 v[30:31], v[54:55], v[30:31]
	v_pk_add_f32 v[28:29], v[32:33], v[2:3]
	v_mul_f32_e32 v45, v44, v44
	v_mul_f32_e32 v49, v48, v48
	v_mul_f32_e32 v21, v20, v20
	v_mul_f32_e32 v23, v22, v22
	v_pk_add_f32 v[28:29], v[30:31], v[28:29]
	v_pk_add_f32 v[30:31], v[40:41], v[42:43]
	v_pk_add_f32 v[26:27], v[44:45], v[48:49]
	v_pk_add_f32 v[24:25], v[30:31], v[24:25]
	v_pk_add_f32 v[20:21], v[20:21], v[22:23]
	v_pk_add_f32 v[24:25], v[28:29], v[24:25]
	v_pk_add_f32 v[20:21], v[26:27], v[20:21]
	s_nop 0
	v_pk_add_f32 v[20:21], v[24:25], v[20:21]
	ds_bpermute_b32 v22, v181, v20
	ds_bpermute_b32 v23, v181, v21
	s_waitcnt lgkmcnt(0)
	v_pk_add_f32 v[20:21], v[20:21], v[22:23]
	ds_bpermute_b32 v22, v180, v20
	ds_bpermute_b32 v23, v180, v21
	s_and_saveexec_b64 s[0:1], s[40:41]
	s_cbranch_execz .LBB0_2217
	v_lshl_add_u64 v[24:25], s[50:51], 0, v[36:37]
	v_lshl_add_u64 v[24:25], s[60:61], 2, v[24:25]
	s_waitcnt lgkmcnt(0)
	v_pk_add_f32 v[20:21], v[20:21], v[22:23]
	global_store_dwordx2 v[24:25], v[20:21], off
.LBB0_2217:
	s_or_b64 exec, exec, s[0:1]
	v_add_u32_e32 v30, 0xb0, v146
	v_ashrrev_i32_e32 v31, 31, v30
	v_lshlrev_b64 v[20:21], 7, v[30:31]
	v_lshl_add_u64 v[26:27], v[134:135], 0, v[20:21]
	s_waitcnt lgkmcnt(0)
	s_waitcnt vmcnt(5)
	v_mov_b64_e32 v[22:23], v[206:207]
	v_mov_b64_e32 v[24:25], v[208:209]
	s_nop 0
	s_waitcnt vmcnt(4)
	v_mov_b64_e32 v[26:27], v[214:215]
	v_mov_b64_e32 v[28:29], v[216:217]
	s_waitcnt lgkmcnt(0)
	v_pk_add_f32 v[22:23], v[22:23], v[24:25]
	s_waitcnt lgkmcnt(0)
	v_pk_add_f32 v[26:27], v[26:27], v[28:29]
	s_nop 0
	v_pk_add_f32 v[22:23], v[26:27], v[22:23]
	ds_bpermute_b32 v24, v181, v22
	ds_bpermute_b32 v25, v181, v23
	s_waitcnt lgkmcnt(0)
	v_pk_add_f32 v[22:23], v[22:23], v[24:25]
	ds_bpermute_b32 v24, v180, v22
	ds_bpermute_b32 v25, v180, v23
	s_waitcnt lgkmcnt(0)
	v_pk_add_f32 v[22:23], v[22:23], v[24:25]
	s_nop 0
	v_pk_mul_f32 v[32:33], v[22:23], s[82:83] op_sel_hi:[1,0]
	v_lshlrev_b64 v[22:23], 11, v[30:31]
	v_lshl_add_u64 v[22:23], s[70:71], 0, v[22:23]
	v_lshl_add_u64 v[28:29], v[144:145], 1, v[22:23]
	s_waitcnt vmcnt(3)
	v_mov_b64_e32 v[22:23], v[234:235]
	v_fma_f32 v3, -v32, v32, v33
	v_max_f32_e32 v3, 0, v3
	v_add_f32_e32 v3, 0x3727c5ac, v3
	v_rsq_f32_e32 v34, v3
	s_waitcnt lgkmcnt(0)
	v_lshlrev_b32_e32 v3, 16, v22
	v_and_b32_e32 v22, 0xffff0000, v22
	v_lshlrev_b32_e32 v24, 16, v23
	v_and_b32_e32 v25, 0xffff0000, v23
	v_sub_f32_e32 v23, v22, v32
	v_sub_f32_e32 v22, v3, v32
	v_sub_f32_e32 v25, v25, v32
	v_sub_f32_e32 v24, v24, v32
	v_pk_mul_f32 v[26:27], v[24:25], v[34:35] op_sel_hi:[1,0]
	v_pk_mul_f32 v[30:31], v[22:23], v[34:35] op_sel_hi:[1,0]
	ds_read_b128 v[22:25], v244
	ds_read_b128 v[36:39], v244 offset:256
	s_waitcnt lgkmcnt(0)
	v_pk_fma_f32 v[24:25], v[24:25], v[26:27], v[38:39]
	s_nop 0
	v_pk_fma_f32 v[18:19], v[24:25], s[72:73], v[18:19] op_sel_hi:[1,0,1]
	s_waitcnt vmcnt(2)
	v_mov_b64_e32 v[24:25], v[236:237]
	v_pk_fma_f32 v[22:23], v[22:23], v[30:31], v[36:37]
	s_waitcnt lgkmcnt(0)
	v_lshlrev_b32_e32 v3, 16, v24
	v_pk_fma_f32 v[16:17], v[22:23], s[72:73], v[16:17] op_sel_hi:[1,0,1]
	v_cvt_pk_bf16_f32 v23, v18, v19
	v_cvt_pk_bf16_f32 v22, v16, v17
	v_and_b32_e32 v17, 0xffff0000, v24
	v_lshlrev_b32_e32 v19, 16, v25
	v_and_b32_e32 v26, 0xffff0000, v25
	v_mov_b64_e32 v[148:149], v[22:23]
	v_sub_f32_e32 v25, v17, v32
	v_sub_f32_e32 v24, v3, v32
	v_sub_f32_e32 v27, v26, v32
	v_sub_f32_e32 v26, v19, v32
	v_pk_mul_f32 v[30:31], v[34:35], v[26:27] op_sel_hi:[0,1]
	v_pk_mul_f32 v[40:41], v[34:35], v[24:25] op_sel_hi:[0,1]
	ds_read_b128 v[24:27], v244 offset:64
	ds_read_b128 v[36:39], v244 offset:320
	v_and_b32_e32 v18, 0xffff0000, v22
	v_lshlrev_b32_e32 v16, 16, v23
	s_waitcnt lgkmcnt(0)
; __device__ __forceinline__ u32x2 pk4(f32x4 v) { u32x2 r; r.x = pk2(v.x, v.y); r.y = pk2(v.z, v.w); return r; }
;     __device__ __forceinline__ void operator()(const f32x4 (&acc)[2][2][4][2], const pg8::Unit& u, int wr, int wc, int fr, int fq) const {
;     ...
;                 for (int bj = 0; bj < 2; ++bj)
; #pragma unroll
;                     for (int n = 0; n < 2; ++n) {
;                         const int col = u.pn * 256 + bj * 128 + wc * 32 + n * 16 + fq * 4;
;                         const u32x2 raw = *(const u32x2*)(src + (size_t)row * DM + col);
;                         f32x4 x = (f32x4){bflo(raw.x), bfhi(raw.x), bflo(raw.y), bfhi(raw.y)};
;                         if (ln) x = (x - mu) * rs * *(const f32x4*)(g + col) + *(const f32x4*)(b + col);
;                         const u32x2 pz = pk4(x * ALPHA + acc[ai][bj][m][n]);
;                         *(u32x2*)(dst + (size_t)row * DM + col) = pz;
;                         const float z0 = bflo(pz.x), z1 = bfhi(pz.x), z2 = bflo(pz.y), z3 = bfhi(pz.y);
;                         s1 += (z0 + z1) + (z2 + z3); s2 += (z0 * z0 + z1 * z1) + (z2 * z2 + z3 * z3);
;                     }
;                 s1 += __shfl_xor(s1, 16); s2 += __shfl_xor(s2, 16); s1 += __shfl_xor(s1, 32); s2 += __shfl_xor(s2, 32);
;                 if (fq == 0) { float* p = stm_n + (size_t)row * 32 + (u.pn * 4 + wc) * 2; p[0] = s1; p[1] = s2; }
	v_pk_fma_f32 v[24:25], v[24:25], v[40:41], v[36:37]
	s_nop 0
	v_pk_fma_f32 v[12:13], v[24:25], s[72:73], v[12:13] op_sel_hi:[1,0,1]
	s_waitcnt vmcnt(1)
	v_mov_b64_e32 v[24:25], v[238:239]
	v_pk_fma_f32 v[26:27], v[26:27], v[30:31], v[38:39]
	v_cvt_pk_bf16_f32 v30, v12, v13
	v_pk_fma_f32 v[14:15], v[26:27], s[72:73], v[14:15] op_sel_hi:[1,0,1]
	s_waitcnt lgkmcnt(0)
	v_lshlrev_b32_e32 v3, 16, v24
	v_cvt_pk_bf16_f32 v31, v14, v15
	v_lshlrev_b32_e32 v14, 16, v31
	v_and_b32_e32 v15, 0xffff0000, v31
	v_mul_f32_e32 v12, v14, v14
	v_pk_fma_f32 v[12:13], v[14:15], v[14:15], v[12:13] op_sel_hi:[1,1,0]
	v_lshlrev_b32_e32 v17, 16, v25
	v_and_b32_e32 v12, 0xffff0000, v24
	v_and_b32_e32 v19, 0xffff0000, v25
	v_mov_b64_e32 v[150:151], v[30:31]
	v_lshrrev_b32_e32 v42, 4, v219
	v_lshlrev_b32_e32 v42, 3, v42
	v_mov_b32_e32 v43, v2
	v_permlane32_swap_b32_e32 v148, v150
	v_permlane32_swap_b32_e32 v149, v151
	v_lshl_add_u64 v[42:43], v[42:43], 0, v[28:29]
	s_nop 0
	v_permlane16_swap_b32_e32 v148, v150
	v_permlane16_swap_b32_e32 v149, v151
	global_store_dwordx4 v[42:43], v[148:151], off sc0
	v_sub_f32_e32 v25, v12, v32
	v_sub_f32_e32 v24, v3, v32
	v_sub_f32_e32 v27, v19, v32
	v_sub_f32_e32 v26, v17, v32
	v_pk_mul_f32 v[40:41], v[34:35], v[26:27] op_sel_hi:[0,1]
	v_pk_mul_f32 v[42:43], v[34:35], v[24:25] op_sel_hi:[0,1]
	ds_read_b128 v[24:27], v244 offset:128
	ds_read_b128 v[36:39], v244 offset:384
	v_and_b32_e32 v31, 0xffff0000, v30
	s_waitcnt lgkmcnt(0)
	v_pk_fma_f32 v[24:25], v[24:25], v[42:43], v[36:37]
	s_waitcnt vmcnt(0)
	v_mov_b64_e32 v[36:37], v[240:241]
	v_pk_fma_f32 v[26:27], v[26:27], v[40:41], v[38:39]
	v_pk_fma_f32 v[8:9], v[24:25], s[72:73], v[8:9] op_sel_hi:[1,0,1]
	v_pk_fma_f32 v[10:11], v[26:27], s[72:73], v[10:11] op_sel_hi:[1,0,1]
	v_cvt_pk_bf16_f32 v8, v8, v9
	v_cvt_pk_bf16_f32 v9, v10, v11
	v_mov_b64_e32 v[148:149], v[8:9]
	v_lshlrev_b32_e32 v24, 16, v8
	v_and_b32_e32 v26, 0xffff0000, v8
	v_lshlrev_b32_e32 v8, 16, v9
	v_and_b32_e32 v10, 0xffff0000, v9
	v_mul_f32_e32 v25, v24, v24
	v_mul_f32_e32 v27, v26, v26
	v_mul_f32_e32 v9, v8, v8
	v_mul_f32_e32 v11, v10, v10
	v_pk_add_f32 v[8:9], v[8:9], v[10:11]
	s_waitcnt lgkmcnt(0)
	v_lshlrev_b32_e32 v3, 16, v36
	v_and_b32_e32 v12, 0xffff0000, v36
	v_lshlrev_b32_e32 v17, 16, v37
	v_and_b32_e32 v19, 0xffff0000, v37
	v_sub_f32_e32 v37, v12, v32
	v_sub_f32_e32 v36, v3, v32
	v_sub_f32_e32 v33, v19, v32
	v_sub_f32_e32 v32, v17, v32
	v_pk_mul_f32 v[32:33], v[34:35], v[32:33] op_sel_hi:[0,1]
	v_pk_mul_f32 v[34:35], v[34:35], v[36:37] op_sel_hi:[0,1]
	ds_read_b128 v[36:39], v244 offset:192
	ds_read_b128 v[40:43], v244 offset:448
	v_mov_b32_e32 v17, v31
	v_mov_b32_e32 v3, v13
	s_waitcnt lgkmcnt(0)
	v_pk_fma_f32 v[34:35], v[36:37], v[34:35], v[40:41]
	s_nop 0
	v_pk_fma_f32 v[4:5], v[34:35], s[72:73], v[4:5] op_sel_hi:[1,0,1]
	v_lshlrev_b32_e32 v35, 16, v30
	v_lshlrev_b32_e32 v34, 16, v22
	v_mov_b32_e32 v19, v35
	v_pk_fma_f32 v[32:33], v[38:39], v[32:33], v[42:43]
	v_pk_mul_f32 v[36:37], v[34:35], v[34:35]
	v_pk_mul_f32 v[38:39], v[18:19], v[18:19]
	v_and_b32_e32 v30, 0xffff0000, v23
	v_pk_mul_f32 v[22:23], v[16:17], v[16:17]
	v_pk_mul_f32 v[40:41], v[30:31], v[30:31]
	v_pk_mov_b32 v[42:43], v[34:35], v[36:37] op_sel:[1,0]
	v_pk_mov_b32 v[38:39], v[30:31], v[38:39] op_sel:[1,0]
	v_pk_add_f32 v[18:19], v[34:35], v[18:19]
	v_pk_add_f32 v[16:17], v[30:31], v[16:17]
	v_pk_fma_f32 v[6:7], v[32:33], s[72:73], v[6:7] op_sel_hi:[1,0,1]
	v_pk_add_f32 v[38:39], v[42:43], v[38:39]
	v_mov_b32_e32 v42, v14
	v_mov_b32_e32 v43, v22
	v_pk_mov_b32 v[14:15], v[14:15], v[40:41] op_sel:[1,0]
	v_mov_b32_e32 v19, v37
	v_mov_b32_e32 v17, v41
	v_cvt_pk_bf16_f32 v4, v4, v5
	v_cvt_pk_bf16_f32 v5, v6, v7
	v_pk_add_f32 v[14:15], v[42:43], v[14:15]
	v_pk_add_f32 v[16:17], v[18:19], v[16:17]
	v_mov_b64_e32 v[150:151], v[4:5]
	v_lshrrev_b32_e32 v146, 4, v219
	v_lshlrev_b32_e32 v146, 3, v146
	v_mov_b32_e32 v147, v2
	v_permlane32_swap_b32_e32 v148, v150
	v_permlane32_swap_b32_e32 v149, v151
	v_lshl_add_u64 v[146:147], v[146:147], 0, v[28:29]
	s_nop 0
	v_permlane16_swap_b32_e32 v148, v150
	v_permlane16_swap_b32_e32 v149, v151
	global_store_dwordx4 v[146:147], v[148:151], off offset:256 sc0
	v_lshlrev_b32_e32 v28, 16, v4
	v_and_b32_e32 v32, 0xffff0000, v4
	v_lshlrev_b32_e32 v4, 16, v5
	v_and_b32_e32 v6, 0xffff0000, v5
	v_pk_add_f32 v[14:15], v[38:39], v[14:15]
	v_pk_add_f32 v[12:13], v[16:17], v[2:3]
	v_mul_f32_e32 v29, v28, v28
	v_mul_f32_e32 v33, v32, v32
	v_mul_f32_e32 v5, v4, v4
	v_mul_f32_e32 v7, v6, v6
	v_pk_add_f32 v[12:13], v[14:15], v[12:13]
	v_pk_add_f32 v[14:15], v[24:25], v[26:27]
	v_pk_add_f32 v[10:11], v[28:29], v[32:33]
	v_pk_add_f32 v[8:9], v[14:15], v[8:9]
	v_pk_add_f32 v[4:5], v[4:5], v[6:7]
	v_pk_add_f32 v[8:9], v[12:13], v[8:9]
	v_pk_add_f32 v[4:5], v[10:11], v[4:5]
	s_nop 0
	v_pk_add_f32 v[4:5], v[8:9], v[4:5]
	ds_bpermute_b32 v6, v181, v4
	ds_bpermute_b32 v7, v181, v5
	s_waitcnt lgkmcnt(0)
	v_pk_add_f32 v[4:5], v[4:5], v[6:7]
	ds_bpermute_b32 v6, v180, v4
	ds_bpermute_b32 v7, v180, v5
	s_and_saveexec_b64 s[0:1], s[40:41]
	s_cbranch_execz .LBB0_2219
	v_lshl_add_u64 v[8:9], s[50:51], 0, v[20:21]
	v_lshl_add_u64 v[8:9], s[60:61], 2, v[8:9]
	s_waitcnt lgkmcnt(0)
	v_pk_add_f32 v[4:5], v[4:5], v[6:7]
	global_store_dwordx2 v[8:9], v[4:5], off

; __device__ __forceinline__ u32x2 pk4(f32x4 v) { u32x2 r; r.x = pk2(v.x, v.y); r.y = pk2(v.z, v.w); return r; }
; __device__ __forceinline__ void stats_main(const float* stm, int row, int fq, float& mu, float& rs) {
;     const f32x4* p = (const f32x4*)(stm + (size_t)row * 32 + fq * 8);
;     const f32x4 a = p[0], b = p[1];
;     float s1 = (a.x + a.z) + (b.x + b.z), s2 = (a.y + a.w) + (b.y + b.w);
;     s1 += __shfl_xor(s1, 16); s2 += __shfl_xor(s2, 16); s1 += __shfl_xor(s1, 32); s2 += __shfl_xor(s2, 32);
;     mu = s1 * (1.f / DM); rs = __builtin_amdgcn_rsqf(fmaxf(s2 * (1.f / DM) - mu * mu, 0.f) + LN_EPS);
;     __device__ __forceinline__ void operator()(const f32x4 (&acc)[2][2][4][2], const pg8::Unit& u, int wr, int wc, int fr, int fq) const {
;     ...
;                 const int row = u.pm * 256 + ai * 128 + wr * 64 + m * 16 + fr;
;                 float mu = 0.f, rs = 1.f; if (ln) stats_main(stm_p, row, fq, mu, rs);
;                 float s1 = 0.f, s2 = 0.f;
; #pragma unroll
;                 for (int bj = 0; bj < 2; ++bj)
; #pragma unroll
;                     for (int n = 0; n < 2; ++n) {
;                         const int col = u.pn * 256 + bj * 128 + wc * 32 + n * 16 + fq * 4;
;                         const u32x2 raw = *(const u32x2*)(src + (size_t)row * DM + col);
;                         f32x4 x = (f32x4){bflo(raw.x), bfhi(raw.x), bflo(raw.y), bfhi(raw.y)};
;                         if (ln) x = (x - mu) * rs * *(const f32x4*)(g + col) + *(const f32x4*)(b + col);
;                         const u32x2 pz = pk4(x * ALPHA + acc[ai][bj][m][n]);
;                         *(u32x2*)(dst + (size_t)row * DM + col) = pz;
;                         const float z0 = bflo(pz.x), z1 = bfhi(pz.x), z2 = bflo(pz.y), z3 = bfhi(pz.y);
;                         s1 += (z0 + z1) + (z2 + z3); s2 += (z0 * z0 + z1 * z1) + (z2 * z2 + z3 * z3);
;                     }
;                 s1 += __shfl_xor(s1, 16); s2 += __shfl_xor(s2, 16); s1 += __shfl_xor(s1, 32); s2 += __shfl_xor(s2, 32);
;                 if (fq == 0) { float* p = stm_n + (size_t)row * 32 + (u.pn * 4 + wc) * 2; p[0] = s1; p[1] = s2; }
.LBB0_2381:
	s_or_b64 exec, exec, s[0:1]
	v_or_b32_e32 v110, 32, v146
	v_ashrrev_i32_e32 v111, 31, v110
	v_lshlrev_b64 v[100:101], 7, v[110:111]
	v_lshl_add_u64 v[106:107], v[134:135], 0, v[100:101]
	s_waitcnt lgkmcnt(0)
	s_waitcnt vmcnt(11)
	v_mov_b64_e32 v[102:103], v[190:191]
	v_mov_b64_e32 v[104:105], v[192:193]
	global_load_dwordx4 v[190:193], v[248:249], off offset:-4080
	s_nop 0
	s_waitcnt vmcnt(11)
	v_mov_b64_e32 v[106:107], v[194:195]
	v_mov_b64_e32 v[108:109], v[196:197]
	global_load_dwordx4 v[194:197], v[248:249], off offset:-4096
	s_waitcnt lgkmcnt(0)
	v_pk_add_f32 v[102:103], v[102:103], v[104:105]
	s_waitcnt lgkmcnt(0)
	v_pk_add_f32 v[106:107], v[106:107], v[108:109]
	s_nop 0
	v_pk_add_f32 v[102:103], v[106:107], v[102:103]
	ds_bpermute_b32 v104, v181, v102
	ds_bpermute_b32 v105, v181, v103
	s_waitcnt lgkmcnt(0)
	v_pk_add_f32 v[102:103], v[102:103], v[104:105]
	ds_bpermute_b32 v104, v180, v102
	ds_bpermute_b32 v105, v180, v103
	s_waitcnt lgkmcnt(0)
	v_pk_add_f32 v[102:103], v[102:103], v[104:105]
	s_nop 0
	v_pk_mul_f32 v[112:113], v[102:103], s[82:83] op_sel_hi:[1,0]
	v_lshlrev_b64 v[102:103], 11, v[110:111]
	v_lshl_add_u64 v[102:103], s[70:71], 0, v[102:103]
	v_lshl_add_u64 v[108:109], v[144:145], 1, v[102:103]
	v_add_u32_e32 v243, 0x40000, v242
	s_waitcnt vmcnt(11)
	v_mov_b64_e32 v[102:103], v[198:199]
	global_load_dwordx2 v[198:199], v243, s[70:71]
	v_fma_f32 v3, -v112, v112, v113
	v_max_f32_e32 v3, 0, v3
	v_add_f32_e32 v3, 0x3727c5ac, v3
	v_rsq_f32_e32 v114, v3
	s_waitcnt lgkmcnt(0)
	v_lshlrev_b32_e32 v3, 16, v102
	v_and_b32_e32 v102, 0xffff0000, v102
	v_lshlrev_b32_e32 v104, 16, v103
	v_and_b32_e32 v105, 0xffff0000, v103
	v_sub_f32_e32 v103, v102, v112
	v_sub_f32_e32 v102, v3, v112
	v_sub_f32_e32 v105, v105, v112
	v_sub_f32_e32 v104, v104, v112
	v_pk_mul_f32 v[106:107], v[104:105], v[114:115] op_sel_hi:[1,0]
	v_pk_mul_f32 v[110:111], v[102:103], v[114:115] op_sel_hi:[1,0]
	ds_read_b128 v[102:105], v244
	ds_read_b128 v[116:119], v244 offset:256
	s_waitcnt lgkmcnt(0)
	v_pk_fma_f32 v[104:105], v[104:105], v[106:107], v[118:119]
	s_nop 0
	v_pk_fma_f32 v[98:99], v[104:105], s[72:73], v[98:99] op_sel_hi:[1,0,1]
	s_waitcnt vmcnt(11)
	v_mov_b64_e32 v[104:105], v[200:201]
	global_load_dwordx2 v[200:201], v243, s[70:71] offset:32
	v_pk_fma_f32 v[102:103], v[102:103], v[110:111], v[116:117]
	s_waitcnt lgkmcnt(0)
	v_lshlrev_b32_e32 v3, 16, v104
	v_pk_fma_f32 v[96:97], v[102:103], s[72:73], v[96:97] op_sel_hi:[1,0,1]
	v_cvt_pk_bf16_f32 v103, v98, v99
	v_cvt_pk_bf16_f32 v102, v96, v97
	v_and_b32_e32 v97, 0xffff0000, v104
	v_lshlrev_b32_e32 v99, 16, v105
	v_and_b32_e32 v106, 0xffff0000, v105
	v_mov_b64_e32 v[148:149], v[102:103]
	v_sub_f32_e32 v105, v97, v112
	v_sub_f32_e32 v104, v3, v112
	v_sub_f32_e32 v107, v106, v112
	v_sub_f32_e32 v106, v99, v112
	v_pk_mul_f32 v[110:111], v[114:115], v[106:107] op_sel_hi:[0,1]
	v_pk_mul_f32 v[120:121], v[114:115], v[104:105] op_sel_hi:[0,1]
	ds_read_b128 v[104:107], v244 offset:64
	ds_read_b128 v[116:119], v244 offset:320
	v_and_b32_e32 v98, 0xffff0000, v102
	v_lshlrev_b32_e32 v96, 16, v103
	s_waitcnt lgkmcnt(0)
	v_pk_fma_f32 v[104:105], v[104:105], v[120:121], v[116:117]
	s_nop 0
	v_pk_fma_f32 v[92:93], v[104:105], s[72:73], v[92:93] op_sel_hi:[1,0,1]
	s_waitcnt vmcnt(11)
	v_mov_b64_e32 v[104:105], v[202:203]
	global_load_dwordx2 v[202:203], v243, s[70:71] offset:256
	v_pk_fma_f32 v[106:107], v[106:107], v[110:111], v[118:119]
	v_cvt_pk_bf16_f32 v110, v92, v93
	v_pk_fma_f32 v[94:95], v[106:107], s[72:73], v[94:95] op_sel_hi:[1,0,1]
	s_waitcnt lgkmcnt(0)
	v_lshlrev_b32_e32 v3, 16, v104
	v_cvt_pk_bf16_f32 v111, v94, v95
	v_lshlrev_b32_e32 v94, 16, v111
	v_and_b32_e32 v95, 0xffff0000, v111
	v_mul_f32_e32 v92, v94, v94
	v_pk_fma_f32 v[92:93], v[94:95], v[94:95], v[92:93] op_sel_hi:[1,1,0]
	v_lshlrev_b32_e32 v97, 16, v105
	v_and_b32_e32 v92, 0xffff0000, v104
	v_and_b32_e32 v99, 0xffff0000, v105
	v_mov_b64_e32 v[150:151], v[110:111]
	v_lshrrev_b32_e32 v122, 4, v219
	v_lshlrev_b32_e32 v122, 3, v122
	v_mov_b32_e32 v123, v2
	v_permlane32_swap_b32_e32 v148, v150
	v_permlane32_swap_b32_e32 v149, v151
	v_lshl_add_u64 v[122:123], v[122:123], 0, v[108:109]
	s_nop 0
	v_permlane16_swap_b32_e32 v148, v150
	v_permlane16_swap_b32_e32 v149, v151
	global_store_dwordx4 v[122:123], v[148:151], off sc0
	v_sub_f32_e32 v105, v92, v112
	v_sub_f32_e32 v104, v3, v112
	v_sub_f32_e32 v107, v99, v112
	v_sub_f32_e32 v106, v97, v112
	v_pk_mul_f32 v[120:121], v[114:115], v[106:107] op_sel_hi:[0,1]
	v_pk_mul_f32 v[122:123], v[114:115], v[104:105] op_sel_hi:[0,1]
	ds_read_b128 v[104:107], v244 offset:128
	ds_read_b128 v[116:119], v244 offset:384
	v_and_b32_e32 v111, 0xffff0000, v110
	s_waitcnt lgkmcnt(0)
	v_pk_fma_f32 v[104:105], v[104:105], v[122:123], v[116:117]
	s_waitcnt vmcnt(11)
	v_mov_b64_e32 v[116:117], v[204:205]
	global_load_dwordx2 v[204:205], v243, s[70:71] offset:288
	v_pk_fma_f32 v[106:107], v[106:107], v[120:121], v[118:119]
	v_pk_fma_f32 v[88:89], v[104:105], s[72:73], v[88:89] op_sel_hi:[1,0,1]
	v_pk_fma_f32 v[90:91], v[106:107], s[72:73], v[90:91] op_sel_hi:[1,0,1]
	v_cvt_pk_bf16_f32 v88, v88, v89
	v_cvt_pk_bf16_f32 v89, v90, v91
	v_mov_b64_e32 v[148:149], v[88:89]
	v_lshlrev_b32_e32 v104, 16, v88
	v_and_b32_e32 v106, 0xffff0000, v88
	v_lshlrev_b32_e32 v88, 16, v89
	v_and_b32_e32 v90, 0xffff0000, v89
	v_mul_f32_e32 v105, v104, v104
	v_mul_f32_e32 v107, v106, v106
	v_mul_f32_e32 v89, v88, v88
	v_mul_f32_e32 v91, v90, v90
	v_pk_add_f32 v[88:89], v[88:89], v[90:91]
	s_waitcnt lgkmcnt(0)
; __device__ __forceinline__ u32x2 pk4(f32x4 v) { u32x2 r; r.x = pk2(v.x, v.y); r.y = pk2(v.z, v.w); return r; }
; __device__ __forceinline__ void stats_main(const float* stm, int row, int fq, float& mu, float& rs) {
;     const f32x4* p = (const f32x4*)(stm + (size_t)row * 32 + fq * 8);
;     const f32x4 a = p[0], b = p[1];
;     float s1 = (a.x + a.z) + (b.x + b.z), s2 = (a.y + a.w) + (b.y + b.w);
;     s1 += __shfl_xor(s1, 16); s2 += __shfl_xor(s2, 16); s1 += __shfl_xor(s1, 32); s2 += __shfl_xor(s2, 32);
;     mu = s1 * (1.f / DM); rs = __builtin_amdgcn_rsqf(fmaxf(s2 * (1.f / DM) - mu * mu, 0.f) + LN_EPS);
;     __device__ __forceinline__ void operator()(const f32x4 (&acc)[2][2][4][2], const pg8::Unit& u, int wr, int wc, int fr, int fq) const {
;     ...
;                 const int row = u.pm * 256 + ai * 128 + wr * 64 + m * 16 + fr;
;                 float mu = 0.f, rs = 1.f; if (ln) stats_main(stm_p, row, fq, mu, rs);
;                 float s1 = 0.f, s2 = 0.f;
; #pragma unroll
;                 for (int bj = 0; bj < 2; ++bj)
; #pragma unroll
;                     for (int n = 0; n < 2; ++n) {
;                         const int col = u.pn * 256 + bj * 128 + wc * 32 + n * 16 + fq * 4;
;                         const u32x2 raw = *(const u32x2*)(src + (size_t)row * DM + col);
;                         f32x4 x = (f32x4){bflo(raw.x), bfhi(raw.x), bflo(raw.y), bfhi(raw.y)};
;                         if (ln) x = (x - mu) * rs * *(const f32x4*)(g + col) + *(const f32x4*)(b + col);
;                         const u32x2 pz = pk4(x * ALPHA + acc[ai][bj][m][n]);
;                         *(u32x2*)(dst + (size_t)row * DM + col) = pz;
;                         const float z0 = bflo(pz.x), z1 = bfhi(pz.x), z2 = bflo(pz.y), z3 = bfhi(pz.y);
;                         s1 += (z0 + z1) + (z2 + z3); s2 += (z0 * z0 + z1 * z1) + (z2 * z2 + z3 * z3);
;                     }
;                 s1 += __shfl_xor(s1, 16); s2 += __shfl_xor(s2, 16); s1 += __shfl_xor(s1, 32); s2 += __shfl_xor(s2, 32);
;                 if (fq == 0) { float* p = stm_n + (size_t)row * 32 + (u.pn * 4 + wc) * 2; p[0] = s1; p[1] = s2; }
	v_lshlrev_b32_e32 v3, 16, v116
	v_and_b32_e32 v92, 0xffff0000, v116
	v_lshlrev_b32_e32 v97, 16, v117
	v_and_b32_e32 v99, 0xffff0000, v117
	v_sub_f32_e32 v117, v92, v112
	v_sub_f32_e32 v116, v3, v112
	v_sub_f32_e32 v113, v99, v112
	v_sub_f32_e32 v112, v97, v112
	v_pk_mul_f32 v[112:113], v[114:115], v[112:113] op_sel_hi:[0,1]
	v_pk_mul_f32 v[114:115], v[114:115], v[116:117] op_sel_hi:[0,1]
	ds_read_b128 v[116:119], v244 offset:192
	ds_read_b128 v[120:123], v244 offset:448
	v_mov_b32_e32 v97, v111
	v_mov_b32_e32 v3, v93
	s_waitcnt lgkmcnt(0)
	v_pk_fma_f32 v[114:115], v[116:117], v[114:115], v[120:121]
	s_nop 0
	v_pk_fma_f32 v[84:85], v[114:115], s[72:73], v[84:85] op_sel_hi:[1,0,1]
	v_lshlrev_b32_e32 v115, 16, v110
	v_lshlrev_b32_e32 v114, 16, v102
	v_mov_b32_e32 v99, v115
	v_pk_fma_f32 v[112:113], v[118:119], v[112:113], v[122:123]
	v_pk_mul_f32 v[116:117], v[114:115], v[114:115]
	v_pk_mul_f32 v[118:119], v[98:99], v[98:99]
	v_and_b32_e32 v110, 0xffff0000, v103
	v_pk_mul_f32 v[102:103], v[96:97], v[96:97]
	v_pk_mul_f32 v[120:121], v[110:111], v[110:111]
	v_pk_mov_b32 v[122:123], v[114:115], v[116:117] op_sel:[1,0]
	v_pk_mov_b32 v[118:119], v[110:111], v[118:119] op_sel:[1,0]
	v_pk_add_f32 v[98:99], v[114:115], v[98:99]
	v_pk_add_f32 v[96:97], v[110:111], v[96:97]
	v_pk_fma_f32 v[86:87], v[112:113], s[72:73], v[86:87] op_sel_hi:[1,0,1]
	v_pk_add_f32 v[118:119], v[122:123], v[118:119]
	v_mov_b32_e32 v122, v94
	v_mov_b32_e32 v123, v102
	v_pk_mov_b32 v[94:95], v[94:95], v[120:121] op_sel:[1,0]
	v_mov_b32_e32 v99, v117
	v_mov_b32_e32 v97, v121
	v_cvt_pk_bf16_f32 v84, v84, v85
	v_cvt_pk_bf16_f32 v85, v86, v87
	v_pk_add_f32 v[94:95], v[122:123], v[94:95]
	v_pk_add_f32 v[96:97], v[98:99], v[96:97]
	v_mov_b64_e32 v[150:151], v[84:85]
	v_lshrrev_b32_e32 v152, 4, v219
	v_lshlrev_b32_e32 v152, 3, v152
	v_mov_b32_e32 v153, v2
	v_permlane32_swap_b32_e32 v148, v150
	v_permlane32_swap_b32_e32 v149, v151
	v_lshl_add_u64 v[152:153], v[152:153], 0, v[108:109]
	s_nop 0
	v_permlane16_swap_b32_e32 v148, v150
	v_permlane16_swap_b32_e32 v149, v151
	global_store_dwordx4 v[152:153], v[148:151], off offset:256 sc0
	v_lshlrev_b32_e32 v108, 16, v84
	v_and_b32_e32 v112, 0xffff0000, v84
	v_lshlrev_b32_e32 v84, 16, v85
	v_and_b32_e32 v86, 0xffff0000, v85
	v_pk_add_f32 v[94:95], v[118:119], v[94:95]
	v_pk_add_f32 v[92:93], v[96:97], v[2:3]
	v_mul_f32_e32 v109, v108, v108
	v_mul_f32_e32 v113, v112, v112
	v_mul_f32_e32 v85, v84, v84
	v_mul_f32_e32 v87, v86, v86
	v_pk_add_f32 v[92:93], v[94:95], v[92:93]
	v_pk_add_f32 v[94:95], v[104:105], v[106:107]
	v_pk_add_f32 v[90:91], v[108:109], v[112:113]
	v_pk_add_f32 v[88:89], v[94:95], v[88:89]
	v_pk_add_f32 v[84:85], v[84:85], v[86:87]
	v_pk_add_f32 v[88:89], v[92:93], v[88:89]
	v_pk_add_f32 v[84:85], v[90:91], v[84:85]
	s_nop 0
	v_pk_add_f32 v[84:85], v[88:89], v[84:85]
	ds_bpermute_b32 v86, v181, v84
	ds_bpermute_b32 v87, v181, v85
	s_waitcnt lgkmcnt(0)
	v_pk_add_f32 v[84:85], v[84:85], v[86:87]
	ds_bpermute_b32 v86, v180, v84
	ds_bpermute_b32 v87, v180, v85
	s_and_saveexec_b64 s[0:1], s[40:41]
	s_mov_b32 s78, 0x20000
	s_mov_b32 s76, 0x30000
	s_cbranch_execz .LBB0_2383
	v_lshl_add_u64 v[88:89], s[52:53], 0, v[100:101]
	v_lshl_add_u64 v[88:89], s[68:69], 2, v[88:89]
	s_waitcnt lgkmcnt(0)
	v_pk_add_f32 v[84:85], v[84:85], v[86:87]
	global_store_dwordx2 v[88:89], v[84:85], off
.LBB0_2383:
	s_or_b64 exec, exec, s[0:1]
	v_or_b32_e32 v94, 48, v146
	v_ashrrev_i32_e32 v95, 31, v94
	v_lshlrev_b64 v[84:85], 7, v[94:95]
	v_lshl_add_u64 v[90:91], v[134:135], 0, v[84:85]
	s_waitcnt lgkmcnt(0)
	s_waitcnt vmcnt(11)
	v_mov_b64_e32 v[86:87], v[206:207]
	v_mov_b64_e32 v[88:89], v[208:209]
	global_load_dwordx4 v[206:209], v[248:249], off offset:-2032
	s_nop 0
	s_waitcnt vmcnt(11)
	v_mov_b64_e32 v[90:91], v[214:215]
	v_mov_b64_e32 v[92:93], v[216:217]
	global_load_dwordx4 v[214:217], v[248:249], off offset:-2048
	s_waitcnt lgkmcnt(0)
	v_pk_add_f32 v[86:87], v[86:87], v[88:89]
	s_waitcnt lgkmcnt(0)
	v_pk_add_f32 v[90:91], v[90:91], v[92:93]
	s_nop 0
	v_pk_add_f32 v[86:87], v[90:91], v[86:87]
	ds_bpermute_b32 v88, v181, v86
	ds_bpermute_b32 v89, v181, v87
	s_waitcnt lgkmcnt(0)
	v_pk_add_f32 v[86:87], v[86:87], v[88:89]
	ds_bpermute_b32 v88, v180, v86
	ds_bpermute_b32 v89, v180, v87
	s_waitcnt lgkmcnt(0)
	v_pk_add_f32 v[86:87], v[86:87], v[88:89]
	s_nop 0
	v_pk_mul_f32 v[96:97], v[86:87], s[82:83] op_sel_hi:[1,0]
	v_lshlrev_b64 v[86:87], 11, v[94:95]
	v_lshl_add_u64 v[86:87], s[70:71], 0, v[86:87]
	v_lshl_add_u64 v[92:93], v[144:145], 1, v[86:87]
	v_add_u32_e32 v243, 0x48000, v242
	s_waitcnt vmcnt(11)
	v_mov_b64_e32 v[86:87], v[234:235]
	global_load_dwordx2 v[234:235], v243, s[70:71]
	v_fma_f32 v3, -v96, v96, v97
	v_max_f32_e32 v3, 0, v3
	v_add_f32_e32 v3, 0x3727c5ac, v3
	v_rsq_f32_e32 v98, v3
	s_waitcnt lgkmcnt(0)
	v_lshlrev_b32_e32 v3, 16, v86
	v_and_b32_e32 v86, 0xffff0000, v86
	v_lshlrev_b32_e32 v88, 16, v87
	v_and_b32_e32 v89, 0xffff0000, v87
	v_sub_f32_e32 v87, v86, v96
	v_sub_f32_e32 v86, v3, v96
	v_sub_f32_e32 v89, v89, v96
	v_sub_f32_e32 v88, v88, v96
	v_pk_mul_f32 v[90:91], v[88:89], v[98:99] op_sel_hi:[1,0]
	v_pk_mul_f32 v[94:95], v[86:87], v[98:99] op_sel_hi:[1,0]
	ds_read_b128 v[86:89], v244
	ds_read_b128 v[100:103], v244 offset:256
	s_waitcnt lgkmcnt(0)
	v_pk_fma_f32 v[88:89], v[88:89], v[90:91], v[102:103]
	s_nop 0
	v_pk_fma_f32 v[82:83], v[88:89], s[72:73], v[82:83] op_sel_hi:[1,0,1]
	s_waitcnt vmcnt(11)
	v_mov_b64_e32 v[88:89], v[236:237]
	global_load_dwordx2 v[236:237], v243, s[70:71] offset:32
	v_pk_fma_f32 v[86:87], v[86:87], v[94:95], v[100:101]
	s_waitcnt lgkmcnt(0)
; __device__ __forceinline__ u32x2 pk4(f32x4 v) { u32x2 r; r.x = pk2(v.x, v.y); r.y = pk2(v.z, v.w); return r; }
;     __device__ __forceinline__ void operator()(const f32x4 (&acc)[2][2][4][2], const pg8::Unit& u, int wr, int wc, int fr, int fq) const {
;     ...
;                 for (int bj = 0; bj < 2; ++bj)
; #pragma unroll
;                     for (int n = 0; n < 2; ++n) {
;                         const int col = u.pn * 256 + bj * 128 + wc * 32 + n * 16 + fq * 4;
;                         const u32x2 raw = *(const u32x2*)(src + (size_t)row * DM + col);
;                         f32x4 x = (f32x4){bflo(raw.x), bfhi(raw.x), bflo(raw.y), bfhi(raw.y)};
;                         if (ln) x = (x - mu) * rs * *(const f32x4*)(g + col) + *(const f32x4*)(b + col);
;                         const u32x2 pz = pk4(x * ALPHA + acc[ai][bj][m][n]);
;                         *(u32x2*)(dst + (size_t)row * DM + col) = pz;
;                         const float z0 = bflo(pz.x), z1 = bfhi(pz.x), z2 = bflo(pz.y), z3 = bfhi(pz.y);
;                         s1 += (z0 + z1) + (z2 + z3); s2 += (z0 * z0 + z1 * z1) + (z2 * z2 + z3 * z3);
;                     }
;                 s1 += __shfl_xor(s1, 16); s2 += __shfl_xor(s2, 16); s1 += __shfl_xor(s1, 32); s2 += __shfl_xor(s2, 32);
;                 if (fq == 0) { float* p = stm_n + (size_t)row * 32 + (u.pn * 4 + wc) * 2; p[0] = s1; p[1] = s2; }
	v_lshlrev_b32_e32 v3, 16, v88
	v_pk_fma_f32 v[80:81], v[86:87], s[72:73], v[80:81] op_sel_hi:[1,0,1]
	v_cvt_pk_bf16_f32 v87, v82, v83
	v_cvt_pk_bf16_f32 v86, v80, v81
	v_and_b32_e32 v81, 0xffff0000, v88
	v_lshlrev_b32_e32 v83, 16, v89
	v_and_b32_e32 v90, 0xffff0000, v89
	v_mov_b64_e32 v[148:149], v[86:87]
	v_sub_f32_e32 v89, v81, v96
	v_sub_f32_e32 v88, v3, v96
	v_sub_f32_e32 v91, v90, v96
	v_sub_f32_e32 v90, v83, v96
	v_pk_mul_f32 v[94:95], v[98:99], v[90:91] op_sel_hi:[0,1]
	v_pk_mul_f32 v[104:105], v[98:99], v[88:89] op_sel_hi:[0,1]
	ds_read_b128 v[88:91], v244 offset:64
	ds_read_b128 v[100:103], v244 offset:320
	v_and_b32_e32 v82, 0xffff0000, v86
	v_lshlrev_b32_e32 v80, 16, v87
	s_waitcnt lgkmcnt(0)
	v_pk_fma_f32 v[88:89], v[88:89], v[104:105], v[100:101]
	s_nop 0
	v_pk_fma_f32 v[76:77], v[88:89], s[72:73], v[76:77] op_sel_hi:[1,0,1]
	s_waitcnt vmcnt(11)
	v_mov_b64_e32 v[88:89], v[238:239]
	global_load_dwordx2 v[238:239], v243, s[70:71] offset:256
	v_pk_fma_f32 v[90:91], v[90:91], v[94:95], v[102:103]
	v_cvt_pk_bf16_f32 v94, v76, v77
	v_pk_fma_f32 v[78:79], v[90:91], s[72:73], v[78:79] op_sel_hi:[1,0,1]
	s_waitcnt lgkmcnt(0)
	v_lshlrev_b32_e32 v3, 16, v88
	v_cvt_pk_bf16_f32 v95, v78, v79
	v_lshlrev_b32_e32 v78, 16, v95
	v_and_b32_e32 v79, 0xffff0000, v95
	v_mul_f32_e32 v76, v78, v78
	v_pk_fma_f32 v[76:77], v[78:79], v[78:79], v[76:77] op_sel_hi:[1,1,0]
	v_lshlrev_b32_e32 v81, 16, v89
	v_and_b32_e32 v76, 0xffff0000, v88
	v_and_b32_e32 v83, 0xffff0000, v89
	v_mov_b64_e32 v[150:151], v[94:95]
	v_lshrrev_b32_e32 v106, 4, v219
	v_lshlrev_b32_e32 v106, 3, v106
	v_mov_b32_e32 v107, v2
	v_permlane32_swap_b32_e32 v148, v150
	v_permlane32_swap_b32_e32 v149, v151
	v_lshl_add_u64 v[106:107], v[106:107], 0, v[92:93]
	s_nop 0
	v_permlane16_swap_b32_e32 v148, v150
	v_permlane16_swap_b32_e32 v149, v151
	global_store_dwordx4 v[106:107], v[148:151], off sc0
	v_sub_f32_e32 v89, v76, v96
	v_sub_f32_e32 v88, v3, v96
	v_sub_f32_e32 v91, v83, v96
	v_sub_f32_e32 v90, v81, v96
	v_pk_mul_f32 v[104:105], v[98:99], v[90:91] op_sel_hi:[0,1]
	v_pk_mul_f32 v[106:107], v[98:99], v[88:89] op_sel_hi:[0,1]
	ds_read_b128 v[88:91], v244 offset:128
	ds_read_b128 v[100:103], v244 offset:384
	v_and_b32_e32 v95, 0xffff0000, v94
	s_waitcnt lgkmcnt(0)
	v_pk_fma_f32 v[88:89], v[88:89], v[106:107], v[100:101]
	s_waitcnt vmcnt(11)
	v_mov_b64_e32 v[100:101], v[240:241]
	global_load_dwordx2 v[240:241], v243, s[70:71] offset:288
	v_pk_fma_f32 v[90:91], v[90:91], v[104:105], v[102:103]
	v_pk_fma_f32 v[72:73], v[88:89], s[72:73], v[72:73] op_sel_hi:[1,0,1]
	v_pk_fma_f32 v[74:75], v[90:91], s[72:73], v[74:75] op_sel_hi:[1,0,1]
	v_cvt_pk_bf16_f32 v72, v72, v73
	v_cvt_pk_bf16_f32 v73, v74, v75
	v_mov_b64_e32 v[148:149], v[72:73]
	v_lshlrev_b32_e32 v88, 16, v72
	v_and_b32_e32 v90, 0xffff0000, v72
	v_lshlrev_b32_e32 v72, 16, v73
	v_and_b32_e32 v74, 0xffff0000, v73
	v_mul_f32_e32 v89, v88, v88
	v_mul_f32_e32 v91, v90, v90
	v_mul_f32_e32 v73, v72, v72
	v_mul_f32_e32 v75, v74, v74
	v_pk_add_f32 v[72:73], v[72:73], v[74:75]
	s_waitcnt lgkmcnt(0)
	v_lshlrev_b32_e32 v3, 16, v100
	v_and_b32_e32 v76, 0xffff0000, v100
	v_lshlrev_b32_e32 v81, 16, v101
	v_and_b32_e32 v83, 0xffff0000, v101
	v_sub_f32_e32 v101, v76, v96
	v_sub_f32_e32 v100, v3, v96
	v_sub_f32_e32 v97, v83, v96
	v_sub_f32_e32 v96, v81, v96
	v_pk_mul_f32 v[96:97], v[98:99], v[96:97] op_sel_hi:[0,1]
	v_pk_mul_f32 v[98:99], v[98:99], v[100:101] op_sel_hi:[0,1]
	ds_read_b128 v[100:103], v244 offset:192
	ds_read_b128 v[104:107], v244 offset:448
	v_mov_b32_e32 v81, v95
	v_mov_b32_e32 v3, v77
	s_waitcnt lgkmcnt(0)
	v_pk_fma_f32 v[98:99], v[100:101], v[98:99], v[104:105]
	s_nop 0
	v_pk_fma_f32 v[68:69], v[98:99], s[72:73], v[68:69] op_sel_hi:[1,0,1]
	v_lshlrev_b32_e32 v99, 16, v94
	v_lshlrev_b32_e32 v98, 16, v86
	v_mov_b32_e32 v83, v99
	v_pk_fma_f32 v[96:97], v[102:103], v[96:97], v[106:107]
	v_pk_mul_f32 v[100:101], v[98:99], v[98:99]
	v_pk_mul_f32 v[102:103], v[82:83], v[82:83]
	v_and_b32_e32 v94, 0xffff0000, v87
	v_pk_mul_f32 v[86:87], v[80:81], v[80:81]
	v_pk_mul_f32 v[104:105], v[94:95], v[94:95]
	v_pk_mov_b32 v[106:107], v[98:99], v[100:101] op_sel:[1,0]
	v_pk_mov_b32 v[102:103], v[94:95], v[102:103] op_sel:[1,0]
	v_pk_add_f32 v[82:83], v[98:99], v[82:83]
	v_pk_add_f32 v[80:81], v[94:95], v[80:81]
	v_pk_fma_f32 v[70:71], v[96:97], s[72:73], v[70:71] op_sel_hi:[1,0,1]
	v_pk_add_f32 v[102:103], v[106:107], v[102:103]
	v_mov_b32_e32 v106, v78
	v_mov_b32_e32 v107, v86
	v_pk_mov_b32 v[78:79], v[78:79], v[104:105] op_sel:[1,0]
	v_mov_b32_e32 v83, v101
	v_mov_b32_e32 v81, v105
	v_cvt_pk_bf16_f32 v68, v68, v69
	v_cvt_pk_bf16_f32 v69, v70, v71
	v_pk_add_f32 v[78:79], v[106:107], v[78:79]
	v_pk_add_f32 v[80:81], v[82:83], v[80:81]
	v_mov_b64_e32 v[150:151], v[68:69]
	v_lshrrev_b32_e32 v152, 4, v219
	v_lshlrev_b32_e32 v152, 3, v152
	v_mov_b32_e32 v153, v2
	v_permlane32_swap_b32_e32 v148, v150
	v_permlane32_swap_b32_e32 v149, v151
	v_lshl_add_u64 v[152:153], v[152:153], 0, v[92:93]
	s_nop 0
	v_permlane16_swap_b32_e32 v148, v150
	v_permlane16_swap_b32_e32 v149, v151
	global_store_dwordx4 v[152:153], v[148:151], off offset:256 sc0
	v_lshlrev_b32_e32 v92, 16, v68
	v_and_b32_e32 v96, 0xffff0000, v68
	v_lshlrev_b32_e32 v68, 16, v69
	v_and_b32_e32 v70, 0xffff0000, v69
	v_pk_add_f32 v[78:79], v[102:103], v[78:79]
	v_pk_add_f32 v[76:77], v[80:81], v[2:3]
	v_mul_f32_e32 v93, v92, v92
	v_mul_f32_e32 v97, v96, v96
	v_mul_f32_e32 v69, v68, v68
	v_mul_f32_e32 v71, v70, v70
	v_pk_add_f32 v[76:77], v[78:79], v[76:77]
	v_pk_add_f32 v[78:79], v[88:89], v[90:91]
	v_pk_add_f32 v[74:75], v[92:93], v[96:97]
	v_pk_add_f32 v[72:73], v[78:79], v[72:73]
	v_pk_add_f32 v[68:69], v[68:69], v[70:71]
	v_pk_add_f32 v[72:73], v[76:77], v[72:73]
	v_pk_add_f32 v[68:69], v[74:75], v[68:69]
	s_nop 0
	v_pk_add_f32 v[68:69], v[72:73], v[68:69]
	ds_bpermute_b32 v70, v181, v68
	ds_bpermute_b32 v71, v181, v69
	s_waitcnt lgkmcnt(0)
	v_pk_add_f32 v[68:69], v[68:69], v[70:71]
	ds_bpermute_b32 v70, v180, v68
	ds_bpermute_b32 v71, v180, v69
	s_and_saveexec_b64 s[0:1], s[40:41]
	s_cbranch_execz .LBB0_2385
	v_lshl_add_u64 v[72:73], s[52:53], 0, v[84:85]
	v_lshl_add_u64 v[72:73], s[68:69], 2, v[72:73]
	s_waitcnt lgkmcnt(0)
	v_pk_add_f32 v[68:69], v[68:69], v[70:71]
	global_store_dwordx2 v[72:73], v[68:69], off
; __device__ __forceinline__ u32x2 pk4(f32x4 v) { u32x2 r; r.x = pk2(v.x, v.y); r.y = pk2(v.z, v.w); return r; }
; __device__ __forceinline__ void stats_main(const float* stm, int row, int fq, float& mu, float& rs) {
;     const f32x4* p = (const f32x4*)(stm + (size_t)row * 32 + fq * 8);
;     const f32x4 a = p[0], b = p[1];
;     float s1 = (a.x + a.z) + (b.x + b.z), s2 = (a.y + a.w) + (b.y + b.w);
;     s1 += __shfl_xor(s1, 16); s2 += __shfl_xor(s2, 16); s1 += __shfl_xor(s1, 32); s2 += __shfl_xor(s2, 32);
;     mu = s1 * (1.f / DM); rs = __builtin_amdgcn_rsqf(fmaxf(s2 * (1.f / DM) - mu * mu, 0.f) + LN_EPS);
;     __device__ __forceinline__ void operator()(const f32x4 (&acc)[2][2][4][2], const pg8::Unit& u, int wr, int wc, int fr, int fq) const {
;     ...
;                 const int row = u.pm * 256 + ai * 128 + wr * 64 + m * 16 + fr;
;                 float mu = 0.f, rs = 1.f; if (ln) stats_main(stm_p, row, fq, mu, rs);
;                 float s1 = 0.f, s2 = 0.f;
; #pragma unroll
;                 for (int bj = 0; bj < 2; ++bj)
; #pragma unroll
;                     for (int n = 0; n < 2; ++n) {
;                         const int col = u.pn * 256 + bj * 128 + wc * 32 + n * 16 + fq * 4;
;                         const u32x2 raw = *(const u32x2*)(src + (size_t)row * DM + col);
;                         f32x4 x = (f32x4){bflo(raw.x), bfhi(raw.x), bflo(raw.y), bfhi(raw.y)};
;                         if (ln) x = (x - mu) * rs * *(const f32x4*)(g + col) + *(const f32x4*)(b + col);
;                         const u32x2 pz = pk4(x * ALPHA + acc[ai][bj][m][n]);
;                         *(u32x2*)(dst + (size_t)row * DM + col) = pz;
;                         const float z0 = bflo(pz.x), z1 = bfhi(pz.x), z2 = bflo(pz.y), z3 = bfhi(pz.y);
;                         s1 += (z0 + z1) + (z2 + z3); s2 += (z0 * z0 + z1 * z1) + (z2 * z2 + z3 * z3);
.LBB0_2385:
	s_or_b64 exec, exec, s[0:1]
	v_add_u32_e32 v78, 0x80, v146
	v_ashrrev_i32_e32 v79, 31, v78
	v_lshlrev_b64 v[68:69], 7, v[78:79]
	v_lshl_add_u64 v[74:75], v[134:135], 0, v[68:69]
	s_waitcnt lgkmcnt(0)
	s_waitcnt vmcnt(11)
	v_mov_b64_e32 v[70:71], v[190:191]
	v_mov_b64_e32 v[72:73], v[192:193]
	global_load_dwordx4 v[190:193], v[248:249], off offset:16
	s_nop 0
	s_waitcnt vmcnt(11)
	v_mov_b64_e32 v[74:75], v[194:195]
	v_mov_b64_e32 v[76:77], v[196:197]
	global_load_dwordx4 v[194:197], v[248:249], off
	s_waitcnt lgkmcnt(0)
	v_pk_add_f32 v[70:71], v[70:71], v[72:73]
	s_waitcnt lgkmcnt(0)
	v_pk_add_f32 v[74:75], v[74:75], v[76:77]
	s_nop 0
	v_pk_add_f32 v[70:71], v[74:75], v[70:71]
	ds_bpermute_b32 v72, v181, v70
	ds_bpermute_b32 v73, v181, v71
	s_waitcnt lgkmcnt(0)
	v_pk_add_f32 v[70:71], v[70:71], v[72:73]
	ds_bpermute_b32 v72, v180, v70
	ds_bpermute_b32 v73, v180, v71
	s_waitcnt lgkmcnt(0)
	v_pk_add_f32 v[70:71], v[70:71], v[72:73]
	s_nop 0
	v_pk_mul_f32 v[80:81], v[70:71], s[82:83] op_sel_hi:[1,0]
	v_lshlrev_b64 v[70:71], 11, v[78:79]
	v_lshl_add_u64 v[70:71], s[70:71], 0, v[70:71]
	v_lshl_add_u64 v[76:77], v[144:145], 1, v[70:71]
	v_add_u32_e32 v243, 0x50000, v242
	s_waitcnt vmcnt(11)
	v_mov_b64_e32 v[70:71], v[198:199]
	global_load_dwordx2 v[198:199], v243, s[70:71]
	v_fma_f32 v3, -v80, v80, v81
	v_max_f32_e32 v3, 0, v3
	v_add_f32_e32 v3, 0x3727c5ac, v3
	v_rsq_f32_e32 v82, v3
	s_waitcnt lgkmcnt(0)
	v_lshlrev_b32_e32 v3, 16, v70
	v_and_b32_e32 v70, 0xffff0000, v70
	v_lshlrev_b32_e32 v72, 16, v71
	v_and_b32_e32 v73, 0xffff0000, v71
	v_sub_f32_e32 v71, v70, v80
	v_sub_f32_e32 v70, v3, v80
	v_sub_f32_e32 v73, v73, v80
	v_sub_f32_e32 v72, v72, v80
	v_pk_mul_f32 v[74:75], v[72:73], v[82:83] op_sel_hi:[1,0]
	v_pk_mul_f32 v[78:79], v[70:71], v[82:83] op_sel_hi:[1,0]
	ds_read_b128 v[70:73], v244
	ds_read_b128 v[84:87], v244 offset:256
	s_waitcnt lgkmcnt(0)
	v_pk_fma_f32 v[72:73], v[72:73], v[74:75], v[86:87]
	s_nop 0
	v_pk_fma_f32 v[66:67], v[72:73], s[72:73], v[66:67] op_sel_hi:[1,0,1]
	s_waitcnt vmcnt(11)
	v_mov_b64_e32 v[72:73], v[200:201]
	global_load_dwordx2 v[200:201], v243, s[70:71] offset:32
	v_pk_fma_f32 v[70:71], v[70:71], v[78:79], v[84:85]
	s_waitcnt lgkmcnt(0)
	v_lshlrev_b32_e32 v3, 16, v72
	v_pk_fma_f32 v[64:65], v[70:71], s[72:73], v[64:65] op_sel_hi:[1,0,1]
	v_cvt_pk_bf16_f32 v71, v66, v67
	v_cvt_pk_bf16_f32 v70, v64, v65
	v_and_b32_e32 v65, 0xffff0000, v72
	v_lshlrev_b32_e32 v67, 16, v73
	v_and_b32_e32 v74, 0xffff0000, v73
	v_mov_b64_e32 v[148:149], v[70:71]
	v_sub_f32_e32 v73, v65, v80
	v_sub_f32_e32 v72, v3, v80
	v_sub_f32_e32 v75, v74, v80
	v_sub_f32_e32 v74, v67, v80
	v_pk_mul_f32 v[78:79], v[82:83], v[74:75] op_sel_hi:[0,1]
	v_pk_mul_f32 v[88:89], v[82:83], v[72:73] op_sel_hi:[0,1]
	ds_read_b128 v[72:75], v244 offset:64
	ds_read_b128 v[84:87], v244 offset:320
	v_and_b32_e32 v66, 0xffff0000, v70
	v_lshlrev_b32_e32 v64, 16, v71
	s_waitcnt lgkmcnt(0)
	v_pk_fma_f32 v[72:73], v[72:73], v[88:89], v[84:85]
	s_nop 0
	v_pk_fma_f32 v[60:61], v[72:73], s[72:73], v[60:61] op_sel_hi:[1,0,1]
	s_waitcnt vmcnt(11)
	v_mov_b64_e32 v[72:73], v[202:203]
	global_load_dwordx2 v[202:203], v243, s[70:71] offset:256
	v_pk_fma_f32 v[74:75], v[74:75], v[78:79], v[86:87]
	v_cvt_pk_bf16_f32 v78, v60, v61
	v_pk_fma_f32 v[62:63], v[74:75], s[72:73], v[62:63] op_sel_hi:[1,0,1]
	s_waitcnt lgkmcnt(0)
	v_lshlrev_b32_e32 v3, 16, v72
	v_cvt_pk_bf16_f32 v79, v62, v63
	v_lshlrev_b32_e32 v62, 16, v79
	v_and_b32_e32 v63, 0xffff0000, v79
	v_mul_f32_e32 v60, v62, v62
	v_pk_fma_f32 v[60:61], v[62:63], v[62:63], v[60:61] op_sel_hi:[1,1,0]
	v_lshlrev_b32_e32 v65, 16, v73
	v_and_b32_e32 v60, 0xffff0000, v72
	v_and_b32_e32 v67, 0xffff0000, v73
	v_mov_b64_e32 v[150:151], v[78:79]
	v_lshrrev_b32_e32 v90, 4, v219
	v_lshlrev_b32_e32 v90, 3, v90
	v_mov_b32_e32 v91, v2
	v_permlane32_swap_b32_e32 v148, v150
	v_permlane32_swap_b32_e32 v149, v151
	v_lshl_add_u64 v[90:91], v[90:91], 0, v[76:77]
	s_nop 0
	v_permlane16_swap_b32_e32 v148, v150
	v_permlane16_swap_b32_e32 v149, v151
	global_store_dwordx4 v[90:91], v[148:151], off sc0
	v_sub_f32_e32 v73, v60, v80
	v_sub_f32_e32 v72, v3, v80
	v_sub_f32_e32 v75, v67, v80
	v_sub_f32_e32 v74, v65, v80
	v_pk_mul_f32 v[88:89], v[82:83], v[74:75] op_sel_hi:[0,1]
	v_pk_mul_f32 v[90:91], v[82:83], v[72:73] op_sel_hi:[0,1]
	ds_read_b128 v[72:75], v244 offset:128
	ds_read_b128 v[84:87], v244 offset:384
	v_and_b32_e32 v79, 0xffff0000, v78
	s_waitcnt lgkmcnt(0)
	v_pk_fma_f32 v[72:73], v[72:73], v[90:91], v[84:85]
	s_waitcnt vmcnt(11)
	v_mov_b64_e32 v[84:85], v[204:205]
	global_load_dwordx2 v[204:205], v243, s[70:71] offset:288
	v_pk_fma_f32 v[74:75], v[74:75], v[88:89], v[86:87]
	v_pk_fma_f32 v[56:57], v[72:73], s[72:73], v[56:57] op_sel_hi:[1,0,1]
	v_pk_fma_f32 v[58:59], v[74:75], s[72:73], v[58:59] op_sel_hi:[1,0,1]
	v_cvt_pk_bf16_f32 v56, v56, v57
	v_cvt_pk_bf16_f32 v57, v58, v59
	v_mov_b64_e32 v[148:149], v[56:57]
	v_lshlrev_b32_e32 v72, 16, v56
	v_and_b32_e32 v74, 0xffff0000, v56
	v_lshlrev_b32_e32 v56, 16, v57
	v_and_b32_e32 v58, 0xffff0000, v57
	v_mul_f32_e32 v73, v72, v72
	v_mul_f32_e32 v75, v74, v74
	v_mul_f32_e32 v57, v56, v56
	v_mul_f32_e32 v59, v58, v58
	v_pk_add_f32 v[56:57], v[56:57], v[58:59]
	s_waitcnt lgkmcnt(0)
	v_lshlrev_b32_e32 v3, 16, v84
	v_and_b32_e32 v60, 0xffff0000, v84
	v_lshlrev_b32_e32 v65, 16, v85
	v_and_b32_e32 v67, 0xffff0000, v85
	v_sub_f32_e32 v85, v60, v80
	v_sub_f32_e32 v84, v3, v80
	v_sub_f32_e32 v81, v67, v80
	v_sub_f32_e32 v80, v65, v80
	v_pk_mul_f32 v[80:81], v[82:83], v[80:81] op_sel_hi:[0,1]
	v_pk_mul_f32 v[82:83], v[82:83], v[84:85] op_sel_hi:[0,1]
	ds_read_b128 v[84:87], v244 offset:192
	ds_read_b128 v[88:91], v244 offset:448
	v_mov_b32_e32 v65, v79
	v_mov_b32_e32 v3, v61
	s_waitcnt lgkmcnt(0)
; __device__ __forceinline__ u32x2 pk4(f32x4 v) { u32x2 r; r.x = pk2(v.x, v.y); r.y = pk2(v.z, v.w); return r; }
; __device__ __forceinline__ void stats_main(const float* stm, int row, int fq, float& mu, float& rs) {
;     const f32x4* p = (const f32x4*)(stm + (size_t)row * 32 + fq * 8);
;     const f32x4 a = p[0], b = p[1];
;     float s1 = (a.x + a.z) + (b.x + b.z), s2 = (a.y + a.w) + (b.y + b.w);
;     s1 += __shfl_xor(s1, 16); s2 += __shfl_xor(s2, 16); s1 += __shfl_xor(s1, 32); s2 += __shfl_xor(s2, 32);
;     mu = s1 * (1.f / DM); rs = __builtin_amdgcn_rsqf(fmaxf(s2 * (1.f / DM) - mu * mu, 0.f) + LN_EPS);
;     __device__ __forceinline__ void operator()(const f32x4 (&acc)[2][2][4][2], const pg8::Unit& u, int wr, int wc, int fr, int fq) const {
;     ...
;                 for (int bj = 0; bj < 2; ++bj)
; #pragma unroll
;                     for (int n = 0; n < 2; ++n) {
;                         const int col = u.pn * 256 + bj * 128 + wc * 32 + n * 16 + fq * 4;
;                         const u32x2 raw = *(const u32x2*)(src + (size_t)row * DM + col);
;                         f32x4 x = (f32x4){bflo(raw.x), bfhi(raw.x), bflo(raw.y), bfhi(raw.y)};
;                         if (ln) x = (x - mu) * rs * *(const f32x4*)(g + col) + *(const f32x4*)(b + col);
;                         const u32x2 pz = pk4(x * ALPHA + acc[ai][bj][m][n]);
;                         *(u32x2*)(dst + (size_t)row * DM + col) = pz;
;                         const float z0 = bflo(pz.x), z1 = bfhi(pz.x), z2 = bflo(pz.y), z3 = bfhi(pz.y);
;                         s1 += (z0 + z1) + (z2 + z3); s2 += (z0 * z0 + z1 * z1) + (z2 * z2 + z3 * z3);
;                     }
;                 s1 += __shfl_xor(s1, 16); s2 += __shfl_xor(s2, 16); s1 += __shfl_xor(s1, 32); s2 += __shfl_xor(s2, 32);
;                 if (fq == 0) { float* p = stm_n + (size_t)row * 32 + (u.pn * 4 + wc) * 2; p[0] = s1; p[1] = s2; }
	v_pk_fma_f32 v[82:83], v[84:85], v[82:83], v[88:89]
	s_nop 0
	v_pk_fma_f32 v[52:53], v[82:83], s[72:73], v[52:53] op_sel_hi:[1,0,1]
	v_lshlrev_b32_e32 v83, 16, v78
	v_lshlrev_b32_e32 v82, 16, v70
	v_mov_b32_e32 v67, v83
	v_pk_fma_f32 v[80:81], v[86:87], v[80:81], v[90:91]
	v_pk_mul_f32 v[84:85], v[82:83], v[82:83]
	v_pk_mul_f32 v[86:87], v[66:67], v[66:67]
	v_and_b32_e32 v78, 0xffff0000, v71
	v_pk_mul_f32 v[70:71], v[64:65], v[64:65]
	v_pk_mul_f32 v[88:89], v[78:79], v[78:79]
	v_pk_mov_b32 v[90:91], v[82:83], v[84:85] op_sel:[1,0]
	v_pk_mov_b32 v[86:87], v[78:79], v[86:87] op_sel:[1,0]
	v_pk_add_f32 v[66:67], v[82:83], v[66:67]
	v_pk_add_f32 v[64:65], v[78:79], v[64:65]
	v_pk_fma_f32 v[54:55], v[80:81], s[72:73], v[54:55] op_sel_hi:[1,0,1]
	v_pk_add_f32 v[86:87], v[90:91], v[86:87]
	v_mov_b32_e32 v90, v62
	v_mov_b32_e32 v91, v70
	v_pk_mov_b32 v[62:63], v[62:63], v[88:89] op_sel:[1,0]
	v_mov_b32_e32 v67, v85
	v_mov_b32_e32 v65, v89
	v_cvt_pk_bf16_f32 v52, v52, v53
	v_cvt_pk_bf16_f32 v53, v54, v55
	v_pk_add_f32 v[62:63], v[90:91], v[62:63]
	v_pk_add_f32 v[64:65], v[66:67], v[64:65]
	v_mov_b64_e32 v[150:151], v[52:53]
	v_lshrrev_b32_e32 v152, 4, v219
	v_lshlrev_b32_e32 v152, 3, v152
	v_mov_b32_e32 v153, v2
	v_permlane32_swap_b32_e32 v148, v150
	v_permlane32_swap_b32_e32 v149, v151
	v_lshl_add_u64 v[152:153], v[152:153], 0, v[76:77]
	s_nop 0
	v_permlane16_swap_b32_e32 v148, v150
	v_permlane16_swap_b32_e32 v149, v151
	global_store_dwordx4 v[152:153], v[148:151], off offset:256 sc0
	v_lshlrev_b32_e32 v76, 16, v52
	v_and_b32_e32 v80, 0xffff0000, v52
	v_lshlrev_b32_e32 v52, 16, v53
	v_and_b32_e32 v54, 0xffff0000, v53
	v_pk_add_f32 v[62:63], v[86:87], v[62:63]
	v_pk_add_f32 v[60:61], v[64:65], v[2:3]
	v_mul_f32_e32 v77, v76, v76
	v_mul_f32_e32 v81, v80, v80
	v_mul_f32_e32 v53, v52, v52
	v_mul_f32_e32 v55, v54, v54
	v_pk_add_f32 v[60:61], v[62:63], v[60:61]
	v_pk_add_f32 v[62:63], v[72:73], v[74:75]
	v_pk_add_f32 v[58:59], v[76:77], v[80:81]
	v_pk_add_f32 v[56:57], v[62:63], v[56:57]
	v_pk_add_f32 v[52:53], v[52:53], v[54:55]
	v_pk_add_f32 v[56:57], v[60:61], v[56:57]
	v_pk_add_f32 v[52:53], v[58:59], v[52:53]
	s_nop 0
	v_pk_add_f32 v[52:53], v[56:57], v[52:53]
	ds_bpermute_b32 v54, v181, v52
	ds_bpermute_b32 v55, v181, v53
	s_waitcnt lgkmcnt(0)
	v_pk_add_f32 v[52:53], v[52:53], v[54:55]
	ds_bpermute_b32 v54, v180, v52
	ds_bpermute_b32 v55, v180, v53
	s_and_saveexec_b64 s[0:1], s[40:41]
	s_cbranch_execz .LBB0_2387
	v_lshl_add_u64 v[56:57], s[52:53], 0, v[68:69]
	v_lshl_add_u64 v[56:57], s[68:69], 2, v[56:57]
	s_waitcnt lgkmcnt(0)
	v_pk_add_f32 v[52:53], v[52:53], v[54:55]
	global_store_dwordx2 v[56:57], v[52:53], off
.LBB0_2387:
	s_or_b64 exec, exec, s[0:1]
	v_add_u32_e32 v62, 0x90, v146
	v_ashrrev_i32_e32 v63, 31, v62
	v_lshlrev_b64 v[52:53], 7, v[62:63]
	v_lshl_add_u64 v[58:59], v[134:135], 0, v[52:53]
	s_waitcnt lgkmcnt(0)
	s_waitcnt vmcnt(11)
	v_mov_b64_e32 v[54:55], v[206:207]
	v_mov_b64_e32 v[56:57], v[208:209]
	global_load_dwordx4 v[206:209], v[248:249], off offset:2064
	s_nop 0
	s_waitcnt vmcnt(11)
	v_mov_b64_e32 v[58:59], v[214:215]
	v_mov_b64_e32 v[60:61], v[216:217]
	global_load_dwordx4 v[214:217], v[248:249], off offset:2048
	s_waitcnt lgkmcnt(0)
	v_pk_add_f32 v[54:55], v[54:55], v[56:57]
	s_waitcnt lgkmcnt(0)
	v_pk_add_f32 v[58:59], v[58:59], v[60:61]
	s_nop 0
	v_pk_add_f32 v[54:55], v[58:59], v[54:55]
	ds_bpermute_b32 v56, v181, v54
	ds_bpermute_b32 v57, v181, v55
	s_waitcnt lgkmcnt(0)
	v_pk_add_f32 v[54:55], v[54:55], v[56:57]
	ds_bpermute_b32 v56, v180, v54
	ds_bpermute_b32 v57, v180, v55
	s_waitcnt lgkmcnt(0)
	v_pk_add_f32 v[54:55], v[54:55], v[56:57]
	s_nop 0
	v_pk_mul_f32 v[64:65], v[54:55], s[82:83] op_sel_hi:[1,0]
	v_lshlrev_b64 v[54:55], 11, v[62:63]
	v_lshl_add_u64 v[54:55], s[70:71], 0, v[54:55]
	v_lshl_add_u64 v[60:61], v[144:145], 1, v[54:55]
	v_add_u32_e32 v243, 0x58000, v242
	s_waitcnt vmcnt(11)
	v_mov_b64_e32 v[54:55], v[234:235]
	global_load_dwordx2 v[234:235], v243, s[70:71]
	v_fma_f32 v3, -v64, v64, v65
	v_max_f32_e32 v3, 0, v3
	v_add_f32_e32 v3, 0x3727c5ac, v3
	v_rsq_f32_e32 v66, v3
	s_waitcnt lgkmcnt(0)
	v_lshlrev_b32_e32 v3, 16, v54
	v_and_b32_e32 v54, 0xffff0000, v54
	v_lshlrev_b32_e32 v56, 16, v55
	v_and_b32_e32 v57, 0xffff0000, v55
	v_sub_f32_e32 v55, v54, v64
	v_sub_f32_e32 v54, v3, v64
	v_sub_f32_e32 v57, v57, v64
	v_sub_f32_e32 v56, v56, v64
	v_pk_mul_f32 v[58:59], v[56:57], v[66:67] op_sel_hi:[1,0]
	v_pk_mul_f32 v[62:63], v[54:55], v[66:67] op_sel_hi:[1,0]
	ds_read_b128 v[54:57], v244
	ds_read_b128 v[68:71], v244 offset:256
	s_waitcnt lgkmcnt(0)
	v_pk_fma_f32 v[56:57], v[56:57], v[58:59], v[70:71]
	s_nop 0
	v_pk_fma_f32 v[50:51], v[56:57], s[72:73], v[50:51] op_sel_hi:[1,0,1]
	s_waitcnt vmcnt(11)
	v_mov_b64_e32 v[56:57], v[236:237]
	global_load_dwordx2 v[236:237], v243, s[70:71] offset:32
	v_pk_fma_f32 v[54:55], v[54:55], v[62:63], v[68:69]
	s_waitcnt lgkmcnt(0)
	v_lshlrev_b32_e32 v3, 16, v56
	v_pk_fma_f32 v[48:49], v[54:55], s[72:73], v[48:49] op_sel_hi:[1,0,1]
	v_cvt_pk_bf16_f32 v55, v50, v51
	v_cvt_pk_bf16_f32 v54, v48, v49
	v_and_b32_e32 v49, 0xffff0000, v56
	v_lshlrev_b32_e32 v51, 16, v57
	v_and_b32_e32 v58, 0xffff0000, v57
	v_mov_b64_e32 v[148:149], v[54:55]
	v_sub_f32_e32 v57, v49, v64
	v_sub_f32_e32 v56, v3, v64
	v_sub_f32_e32 v59, v58, v64
	v_sub_f32_e32 v58, v51, v64
	v_pk_mul_f32 v[62:63], v[66:67], v[58:59] op_sel_hi:[0,1]
	v_pk_mul_f32 v[72:73], v[66:67], v[56:57] op_sel_hi:[0,1]
	ds_read_b128 v[56:59], v244 offset:64
	ds_read_b128 v[68:71], v244 offset:320
	v_and_b32_e32 v50, 0xffff0000, v54
	v_lshlrev_b32_e32 v48, 16, v55
	s_waitcnt lgkmcnt(0)
; __device__ __forceinline__ u32x2 pk4(f32x4 v) { u32x2 r; r.x = pk2(v.x, v.y); r.y = pk2(v.z, v.w); return r; }
;     __device__ __forceinline__ void operator()(const f32x4 (&acc)[2][2][4][2], const pg8::Unit& u, int wr, int wc, int fr, int fq) const {
;     ...
;                 for (int bj = 0; bj < 2; ++bj)
; #pragma unroll
;                     for (int n = 0; n < 2; ++n) {
;                         const int col = u.pn * 256 + bj * 128 + wc * 32 + n * 16 + fq * 4;
;                         const u32x2 raw = *(const u32x2*)(src + (size_t)row * DM + col);
;                         f32x4 x = (f32x4){bflo(raw.x), bfhi(raw.x), bflo(raw.y), bfhi(raw.y)};
;                         if (ln) x = (x - mu) * rs * *(const f32x4*)(g + col) + *(const f32x4*)(b + col);
;                         const u32x2 pz = pk4(x * ALPHA + acc[ai][bj][m][n]);
;                         *(u32x2*)(dst + (size_t)row * DM + col) = pz;
;                         const float z0 = bflo(pz.x), z1 = bfhi(pz.x), z2 = bflo(pz.y), z3 = bfhi(pz.y);
;                         s1 += (z0 + z1) + (z2 + z3); s2 += (z0 * z0 + z1 * z1) + (z2 * z2 + z3 * z3);
;                     }
;                 s1 += __shfl_xor(s1, 16); s2 += __shfl_xor(s2, 16); s1 += __shfl_xor(s1, 32); s2 += __shfl_xor(s2, 32);
;                 if (fq == 0) { float* p = stm_n + (size_t)row * 32 + (u.pn * 4 + wc) * 2; p[0] = s1; p[1] = s2; }
	v_pk_fma_f32 v[56:57], v[56:57], v[72:73], v[68:69]
	s_nop 0
	v_pk_fma_f32 v[44:45], v[56:57], s[72:73], v[44:45] op_sel_hi:[1,0,1]
	s_waitcnt vmcnt(11)
	v_mov_b64_e32 v[56:57], v[238:239]
	global_load_dwordx2 v[238:239], v243, s[70:71] offset:256
	v_pk_fma_f32 v[58:59], v[58:59], v[62:63], v[70:71]
	v_cvt_pk_bf16_f32 v62, v44, v45
	v_pk_fma_f32 v[46:47], v[58:59], s[72:73], v[46:47] op_sel_hi:[1,0,1]
	s_waitcnt lgkmcnt(0)
	v_lshlrev_b32_e32 v3, 16, v56
	v_cvt_pk_bf16_f32 v63, v46, v47
	v_lshlrev_b32_e32 v46, 16, v63
	v_and_b32_e32 v47, 0xffff0000, v63
	v_mul_f32_e32 v44, v46, v46
	v_pk_fma_f32 v[44:45], v[46:47], v[46:47], v[44:45] op_sel_hi:[1,1,0]
	v_lshlrev_b32_e32 v49, 16, v57
	v_and_b32_e32 v44, 0xffff0000, v56
	v_and_b32_e32 v51, 0xffff0000, v57
	v_mov_b64_e32 v[150:151], v[62:63]
	v_lshrrev_b32_e32 v74, 4, v219
	v_lshlrev_b32_e32 v74, 3, v74
	v_mov_b32_e32 v75, v2
	v_permlane32_swap_b32_e32 v148, v150
	v_permlane32_swap_b32_e32 v149, v151
	v_lshl_add_u64 v[74:75], v[74:75], 0, v[60:61]
	s_nop 0
	v_permlane16_swap_b32_e32 v148, v150
	v_permlane16_swap_b32_e32 v149, v151
	global_store_dwordx4 v[74:75], v[148:151], off sc0
	v_sub_f32_e32 v57, v44, v64
	v_sub_f32_e32 v56, v3, v64
	v_sub_f32_e32 v59, v51, v64
	v_sub_f32_e32 v58, v49, v64
	v_pk_mul_f32 v[72:73], v[66:67], v[58:59] op_sel_hi:[0,1]
	v_pk_mul_f32 v[74:75], v[66:67], v[56:57] op_sel_hi:[0,1]
	ds_read_b128 v[56:59], v244 offset:128
	ds_read_b128 v[68:71], v244 offset:384
	v_and_b32_e32 v63, 0xffff0000, v62
	s_waitcnt lgkmcnt(0)
	v_pk_fma_f32 v[56:57], v[56:57], v[74:75], v[68:69]
	s_waitcnt vmcnt(11)
	v_mov_b64_e32 v[68:69], v[240:241]
	global_load_dwordx2 v[240:241], v243, s[70:71] offset:288
	v_pk_fma_f32 v[58:59], v[58:59], v[72:73], v[70:71]
	v_pk_fma_f32 v[40:41], v[56:57], s[72:73], v[40:41] op_sel_hi:[1,0,1]
	v_pk_fma_f32 v[42:43], v[58:59], s[72:73], v[42:43] op_sel_hi:[1,0,1]
	v_cvt_pk_bf16_f32 v40, v40, v41
	v_cvt_pk_bf16_f32 v41, v42, v43
	v_mov_b64_e32 v[148:149], v[40:41]
	v_lshlrev_b32_e32 v56, 16, v40
	v_and_b32_e32 v58, 0xffff0000, v40
	v_lshlrev_b32_e32 v40, 16, v41
	v_and_b32_e32 v42, 0xffff0000, v41
	v_mul_f32_e32 v57, v56, v56
	v_mul_f32_e32 v59, v58, v58
	v_mul_f32_e32 v41, v40, v40
	v_mul_f32_e32 v43, v42, v42
	v_pk_add_f32 v[40:41], v[40:41], v[42:43]
	s_waitcnt lgkmcnt(0)
	v_lshlrev_b32_e32 v3, 16, v68
	v_and_b32_e32 v44, 0xffff0000, v68
	v_lshlrev_b32_e32 v49, 16, v69
	v_and_b32_e32 v51, 0xffff0000, v69
	v_sub_f32_e32 v69, v44, v64
	v_sub_f32_e32 v68, v3, v64
	v_sub_f32_e32 v65, v51, v64
	v_sub_f32_e32 v64, v49, v64
	v_pk_mul_f32 v[64:65], v[66:67], v[64:65] op_sel_hi:[0,1]
	v_pk_mul_f32 v[66:67], v[66:67], v[68:69] op_sel_hi:[0,1]
	ds_read_b128 v[68:71], v244 offset:192
	ds_read_b128 v[72:75], v244 offset:448
	v_mov_b32_e32 v49, v63
	v_mov_b32_e32 v3, v45
	s_waitcnt lgkmcnt(0)
	v_pk_fma_f32 v[66:67], v[68:69], v[66:67], v[72:73]
	s_nop 0
	v_pk_fma_f32 v[36:37], v[66:67], s[72:73], v[36:37] op_sel_hi:[1,0,1]
	v_lshlrev_b32_e32 v67, 16, v62
	v_lshlrev_b32_e32 v66, 16, v54
	v_mov_b32_e32 v51, v67
	v_pk_fma_f32 v[64:65], v[70:71], v[64:65], v[74:75]
	v_pk_mul_f32 v[68:69], v[66:67], v[66:67]
	v_pk_mul_f32 v[70:71], v[50:51], v[50:51]
	v_and_b32_e32 v62, 0xffff0000, v55
	v_pk_mul_f32 v[54:55], v[48:49], v[48:49]
	v_pk_mul_f32 v[72:73], v[62:63], v[62:63]
	v_pk_mov_b32 v[74:75], v[66:67], v[68:69] op_sel:[1,0]
	v_pk_mov_b32 v[70:71], v[62:63], v[70:71] op_sel:[1,0]
	v_pk_add_f32 v[50:51], v[66:67], v[50:51]
	v_pk_add_f32 v[48:49], v[62:63], v[48:49]
	v_pk_fma_f32 v[38:39], v[64:65], s[72:73], v[38:39] op_sel_hi:[1,0,1]
	v_pk_add_f32 v[70:71], v[74:75], v[70:71]
	v_mov_b32_e32 v74, v46
	v_mov_b32_e32 v75, v54
	v_pk_mov_b32 v[46:47], v[46:47], v[72:73] op_sel:[1,0]
	v_mov_b32_e32 v51, v69
	v_mov_b32_e32 v49, v73
	v_cvt_pk_bf16_f32 v36, v36, v37
	v_cvt_pk_bf16_f32 v37, v38, v39
	v_pk_add_f32 v[46:47], v[74:75], v[46:47]
	v_pk_add_f32 v[48:49], v[50:51], v[48:49]
	v_mov_b64_e32 v[150:151], v[36:37]
	v_lshrrev_b32_e32 v152, 4, v219
	v_lshlrev_b32_e32 v152, 3, v152
	v_mov_b32_e32 v153, v2
	v_permlane32_swap_b32_e32 v148, v150
	v_permlane32_swap_b32_e32 v149, v151
	v_lshl_add_u64 v[152:153], v[152:153], 0, v[60:61]
	s_nop 0
	v_permlane16_swap_b32_e32 v148, v150
	v_permlane16_swap_b32_e32 v149, v151
	global_store_dwordx4 v[152:153], v[148:151], off offset:256 sc0
	v_lshlrev_b32_e32 v60, 16, v36
	v_and_b32_e32 v64, 0xffff0000, v36
	v_lshlrev_b32_e32 v36, 16, v37
	v_and_b32_e32 v38, 0xffff0000, v37
	v_pk_add_f32 v[46:47], v[70:71], v[46:47]
	v_pk_add_f32 v[44:45], v[48:49], v[2:3]
	v_mul_f32_e32 v61, v60, v60
	v_mul_f32_e32 v65, v64, v64
	v_mul_f32_e32 v37, v36, v36
	v_mul_f32_e32 v39, v38, v38
	v_pk_add_f32 v[44:45], v[46:47], v[44:45]
	v_pk_add_f32 v[46:47], v[56:57], v[58:59]
	v_pk_add_f32 v[42:43], v[60:61], v[64:65]
	v_pk_add_f32 v[40:41], v[46:47], v[40:41]
	v_pk_add_f32 v[36:37], v[36:37], v[38:39]
	v_pk_add_f32 v[40:41], v[44:45], v[40:41]
	v_pk_add_f32 v[36:37], v[42:43], v[36:37]
	s_nop 0
	v_pk_add_f32 v[36:37], v[40:41], v[36:37]
	ds_bpermute_b32 v38, v181, v36
	ds_bpermute_b32 v39, v181, v37
	s_waitcnt lgkmcnt(0)
	v_pk_add_f32 v[36:37], v[36:37], v[38:39]
	ds_bpermute_b32 v38, v180, v36
	ds_bpermute_b32 v39, v180, v37
	s_and_saveexec_b64 s[0:1], s[40:41]
	s_cbranch_execz .LBB0_2389
	v_lshl_add_u64 v[40:41], s[52:53], 0, v[52:53]
	v_lshl_add_u64 v[40:41], s[68:69], 2, v[40:41]
	s_waitcnt lgkmcnt(0)
	v_pk_add_f32 v[36:37], v[36:37], v[38:39]
	global_store_dwordx2 v[40:41], v[36:37], off
; __device__ __forceinline__ u32x2 pk4(f32x4 v) { u32x2 r; r.x = pk2(v.x, v.y); r.y = pk2(v.z, v.w); return r; }
; __device__ __forceinline__ void stats_main(const float* stm, int row, int fq, float& mu, float& rs) {
;     const f32x4* p = (const f32x4*)(stm + (size_t)row * 32 + fq * 8);
;     const f32x4 a = p[0], b = p[1];
;     float s1 = (a.x + a.z) + (b.x + b.z), s2 = (a.y + a.w) + (b.y + b.w);
;     s1 += __shfl_xor(s1, 16); s2 += __shfl_xor(s2, 16); s1 += __shfl_xor(s1, 32); s2 += __shfl_xor(s2, 32);
;     mu = s1 * (1.f / DM); rs = __builtin_amdgcn_rsqf(fmaxf(s2 * (1.f / DM) - mu * mu, 0.f) + LN_EPS);
;     __device__ __forceinline__ void operator()(const f32x4 (&acc)[2][2][4][2], const pg8::Unit& u, int wr, int wc, int fr, int fq) const {
;     ...
;                 const int row = u.pm * 256 + ai * 128 + wr * 64 + m * 16 + fr;
;                 float mu = 0.f, rs = 1.f; if (ln) stats_main(stm_p, row, fq, mu, rs);
;                 float s1 = 0.f, s2 = 0.f;
; #pragma unroll
;                 for (int bj = 0; bj < 2; ++bj)
; #pragma unroll
;                     for (int n = 0; n < 2; ++n) {
;                         const int col = u.pn * 256 + bj * 128 + wc * 32 + n * 16 + fq * 4;
;                         const u32x2 raw = *(const u32x2*)(src + (size_t)row * DM + col);
;                         f32x4 x = (f32x4){bflo(raw.x), bfhi(raw.x), bflo(raw.y), bfhi(raw.y)};
;                         if (ln) x = (x - mu) * rs * *(const f32x4*)(g + col) + *(const f32x4*)(b + col);
;                         const u32x2 pz = pk4(x * ALPHA + acc[ai][bj][m][n]);
;                         *(u32x2*)(dst + (size_t)row * DM + col) = pz;
;                         const float z0 = bflo(pz.x), z1 = bfhi(pz.x), z2 = bflo(pz.y), z3 = bfhi(pz.y);
;                         s1 += (z0 + z1) + (z2 + z3); s2 += (z0 * z0 + z1 * z1) + (z2 * z2 + z3 * z3);
.LBB0_2389:
	s_or_b64 exec, exec, s[0:1]
	v_add_u32_e32 v46, 0xa0, v146
	v_ashrrev_i32_e32 v47, 31, v46
	v_lshlrev_b64 v[36:37], 7, v[46:47]
	v_lshl_add_u64 v[42:43], v[134:135], 0, v[36:37]
	s_waitcnt lgkmcnt(0)
	s_waitcnt vmcnt(11)
	v_mov_b64_e32 v[38:39], v[190:191]
	v_mov_b64_e32 v[40:41], v[192:193]
	s_nop 0
	s_waitcnt vmcnt(10)
	v_mov_b64_e32 v[42:43], v[194:195]
	v_mov_b64_e32 v[44:45], v[196:197]
	s_waitcnt lgkmcnt(0)
	v_pk_add_f32 v[38:39], v[38:39], v[40:41]
	s_waitcnt lgkmcnt(0)
	v_pk_add_f32 v[42:43], v[42:43], v[44:45]
	s_nop 0
	v_pk_add_f32 v[38:39], v[42:43], v[38:39]
	ds_bpermute_b32 v40, v181, v38
	ds_bpermute_b32 v41, v181, v39
	s_waitcnt lgkmcnt(0)
	v_pk_add_f32 v[38:39], v[38:39], v[40:41]
	ds_bpermute_b32 v40, v180, v38
	ds_bpermute_b32 v41, v180, v39
	s_waitcnt lgkmcnt(0)
	v_pk_add_f32 v[38:39], v[38:39], v[40:41]
	s_nop 0
	v_pk_mul_f32 v[48:49], v[38:39], s[82:83] op_sel_hi:[1,0]
	v_lshlrev_b64 v[38:39], 11, v[46:47]
	v_lshl_add_u64 v[38:39], s[70:71], 0, v[38:39]
	v_lshl_add_u64 v[44:45], v[144:145], 1, v[38:39]
	s_waitcnt vmcnt(9)
	v_mov_b64_e32 v[38:39], v[198:199]
	v_fma_f32 v3, -v48, v48, v49
	v_max_f32_e32 v3, 0, v3
	v_add_f32_e32 v3, 0x3727c5ac, v3
	v_rsq_f32_e32 v50, v3
	s_waitcnt lgkmcnt(0)
	v_lshlrev_b32_e32 v3, 16, v38
	v_and_b32_e32 v38, 0xffff0000, v38
	v_lshlrev_b32_e32 v40, 16, v39
	v_and_b32_e32 v41, 0xffff0000, v39
	v_sub_f32_e32 v39, v38, v48
	v_sub_f32_e32 v38, v3, v48
	v_sub_f32_e32 v41, v41, v48
	v_sub_f32_e32 v40, v40, v48
	v_pk_mul_f32 v[42:43], v[40:41], v[50:51] op_sel_hi:[1,0]
	v_pk_mul_f32 v[46:47], v[38:39], v[50:51] op_sel_hi:[1,0]
	ds_read_b128 v[38:41], v244
	ds_read_b128 v[52:55], v244 offset:256
	s_waitcnt lgkmcnt(0)
	v_pk_fma_f32 v[40:41], v[40:41], v[42:43], v[54:55]
	s_nop 0
	v_pk_fma_f32 v[34:35], v[40:41], s[72:73], v[34:35] op_sel_hi:[1,0,1]
	s_waitcnt vmcnt(8)
	v_mov_b64_e32 v[40:41], v[200:201]
	v_pk_fma_f32 v[38:39], v[38:39], v[46:47], v[52:53]
	s_waitcnt lgkmcnt(0)
	v_lshlrev_b32_e32 v3, 16, v40
	v_pk_fma_f32 v[32:33], v[38:39], s[72:73], v[32:33] op_sel_hi:[1,0,1]
	v_cvt_pk_bf16_f32 v39, v34, v35
	v_cvt_pk_bf16_f32 v38, v32, v33
	v_and_b32_e32 v33, 0xffff0000, v40
	v_lshlrev_b32_e32 v35, 16, v41
	v_and_b32_e32 v42, 0xffff0000, v41
	v_mov_b64_e32 v[148:149], v[38:39]
	v_sub_f32_e32 v41, v33, v48
	v_sub_f32_e32 v40, v3, v48
	v_sub_f32_e32 v43, v42, v48
	v_sub_f32_e32 v42, v35, v48
	v_pk_mul_f32 v[46:47], v[50:51], v[42:43] op_sel_hi:[0,1]
	v_pk_mul_f32 v[56:57], v[50:51], v[40:41] op_sel_hi:[0,1]
	ds_read_b128 v[40:43], v244 offset:64
	ds_read_b128 v[52:55], v244 offset:320
	v_and_b32_e32 v34, 0xffff0000, v38
	v_lshlrev_b32_e32 v32, 16, v39
	s_waitcnt lgkmcnt(0)
	v_pk_fma_f32 v[40:41], v[40:41], v[56:57], v[52:53]
	s_nop 0
	v_pk_fma_f32 v[28:29], v[40:41], s[72:73], v[28:29] op_sel_hi:[1,0,1]
	s_waitcnt vmcnt(7)
	v_mov_b64_e32 v[40:41], v[202:203]
	v_pk_fma_f32 v[42:43], v[42:43], v[46:47], v[54:55]
	v_cvt_pk_bf16_f32 v46, v28, v29
	v_pk_fma_f32 v[30:31], v[42:43], s[72:73], v[30:31] op_sel_hi:[1,0,1]
	s_waitcnt lgkmcnt(0)
	v_lshlrev_b32_e32 v3, 16, v40
	v_cvt_pk_bf16_f32 v47, v30, v31
	v_lshlrev_b32_e32 v30, 16, v47
	v_and_b32_e32 v31, 0xffff0000, v47
	v_mul_f32_e32 v28, v30, v30
	v_pk_fma_f32 v[28:29], v[30:31], v[30:31], v[28:29] op_sel_hi:[1,1,0]
	v_lshlrev_b32_e32 v33, 16, v41
	v_and_b32_e32 v28, 0xffff0000, v40
	v_and_b32_e32 v35, 0xffff0000, v41
	v_mov_b64_e32 v[150:151], v[46:47]
	v_lshrrev_b32_e32 v58, 4, v219
	v_lshlrev_b32_e32 v58, 3, v58
	v_mov_b32_e32 v59, v2
	v_permlane32_swap_b32_e32 v148, v150
	v_permlane32_swap_b32_e32 v149, v151
	v_lshl_add_u64 v[58:59], v[58:59], 0, v[44:45]
	s_nop 0
	v_permlane16_swap_b32_e32 v148, v150
	v_permlane16_swap_b32_e32 v149, v151
	global_store_dwordx4 v[58:59], v[148:151], off sc0
	v_sub_f32_e32 v41, v28, v48
	v_sub_f32_e32 v40, v3, v48
	v_sub_f32_e32 v43, v35, v48
	v_sub_f32_e32 v42, v33, v48
	v_pk_mul_f32 v[56:57], v[50:51], v[42:43] op_sel_hi:[0,1]
	v_pk_mul_f32 v[58:59], v[50:51], v[40:41] op_sel_hi:[0,1]
	ds_read_b128 v[40:43], v244 offset:128
	ds_read_b128 v[52:55], v244 offset:384
	v_and_b32_e32 v47, 0xffff0000, v46
	s_waitcnt lgkmcnt(0)
	v_pk_fma_f32 v[40:41], v[40:41], v[58:59], v[52:53]
	s_waitcnt vmcnt(6)
	v_mov_b64_e32 v[52:53], v[204:205]
	v_pk_fma_f32 v[42:43], v[42:43], v[56:57], v[54:55]
	v_pk_fma_f32 v[24:25], v[40:41], s[72:73], v[24:25] op_sel_hi:[1,0,1]
	v_pk_fma_f32 v[26:27], v[42:43], s[72:73], v[26:27] op_sel_hi:[1,0,1]
	v_cvt_pk_bf16_f32 v24, v24, v25
	v_cvt_pk_bf16_f32 v25, v26, v27
	v_mov_b64_e32 v[148:149], v[24:25]
	v_lshlrev_b32_e32 v40, 16, v24
	v_and_b32_e32 v42, 0xffff0000, v24
	v_lshlrev_b32_e32 v24, 16, v25
	v_and_b32_e32 v26, 0xffff0000, v25
	v_mul_f32_e32 v41, v40, v40
	v_mul_f32_e32 v43, v42, v42
	v_mul_f32_e32 v25, v24, v24
	v_mul_f32_e32 v27, v26, v26
	v_pk_add_f32 v[24:25], v[24:25], v[26:27]
	s_waitcnt lgkmcnt(0)
	v_lshlrev_b32_e32 v3, 16, v52
	v_and_b32_e32 v28, 0xffff0000, v52
	v_lshlrev_b32_e32 v33, 16, v53
	v_and_b32_e32 v35, 0xffff0000, v53
	v_sub_f32_e32 v53, v28, v48
	v_sub_f32_e32 v52, v3, v48
	v_sub_f32_e32 v49, v35, v48
	v_sub_f32_e32 v48, v33, v48
	v_pk_mul_f32 v[48:49], v[50:51], v[48:49] op_sel_hi:[0,1]
	v_pk_mul_f32 v[50:51], v[50:51], v[52:53] op_sel_hi:[0,1]
	ds_read_b128 v[52:55], v244 offset:192
	ds_read_b128 v[56:59], v244 offset:448
	v_mov_b32_e32 v33, v47
	v_mov_b32_e32 v3, v29
	s_waitcnt lgkmcnt(0)
; __device__ __forceinline__ u32x2 pk4(f32x4 v) { u32x2 r; r.x = pk2(v.x, v.y); r.y = pk2(v.z, v.w); return r; }
; __device__ __forceinline__ void stats_main(const float* stm, int row, int fq, float& mu, float& rs) {
;     const f32x4* p = (const f32x4*)(stm + (size_t)row * 32 + fq * 8);
;     const f32x4 a = p[0], b = p[1];
;     float s1 = (a.x + a.z) + (b.x + b.z), s2 = (a.y + a.w) + (b.y + b.w);
;     s1 += __shfl_xor(s1, 16); s2 += __shfl_xor(s2, 16); s1 += __shfl_xor(s1, 32); s2 += __shfl_xor(s2, 32);
;     mu = s1 * (1.f / DM); rs = __builtin_amdgcn_rsqf(fmaxf(s2 * (1.f / DM) - mu * mu, 0.f) + LN_EPS);
;     __device__ __forceinline__ void operator()(const f32x4 (&acc)[2][2][4][2], const pg8::Unit& u, int wr, int wc, int fr, int fq) const {
;     ...
;                 for (int bj = 0; bj < 2; ++bj)
; #pragma unroll
;                     for (int n = 0; n < 2; ++n) {
;                         const int col = u.pn * 256 + bj * 128 + wc * 32 + n * 16 + fq * 4;
;                         const u32x2 raw = *(const u32x2*)(src + (size_t)row * DM + col);
;                         f32x4 x = (f32x4){bflo(raw.x), bfhi(raw.x), bflo(raw.y), bfhi(raw.y)};
;                         if (ln) x = (x - mu) * rs * *(const f32x4*)(g + col) + *(const f32x4*)(b + col);
;                         const u32x2 pz = pk4(x * ALPHA + acc[ai][bj][m][n]);
;                         *(u32x2*)(dst + (size_t)row * DM + col) = pz;
;                         const float z0 = bflo(pz.x), z1 = bfhi(pz.x), z2 = bflo(pz.y), z3 = bfhi(pz.y);
;                         s1 += (z0 + z1) + (z2 + z3); s2 += (z0 * z0 + z1 * z1) + (z2 * z2 + z3 * z3);
;                     }
;                 s1 += __shfl_xor(s1, 16); s2 += __shfl_xor(s2, 16); s1 += __shfl_xor(s1, 32); s2 += __shfl_xor(s2, 32);
;                 if (fq == 0) { float* p = stm_n + (size_t)row * 32 + (u.pn * 4 + wc) * 2; p[0] = s1; p[1] = s2; }
	v_pk_fma_f32 v[50:51], v[52:53], v[50:51], v[56:57]
	s_nop 0
	v_pk_fma_f32 v[20:21], v[50:51], s[72:73], v[20:21] op_sel_hi:[1,0,1]
	v_lshlrev_b32_e32 v51, 16, v46
	v_lshlrev_b32_e32 v50, 16, v38
	v_mov_b32_e32 v35, v51
	v_pk_fma_f32 v[48:49], v[54:55], v[48:49], v[58:59]
	v_pk_mul_f32 v[52:53], v[50:51], v[50:51]
	v_pk_mul_f32 v[54:55], v[34:35], v[34:35]
	v_and_b32_e32 v46, 0xffff0000, v39
	v_pk_mul_f32 v[38:39], v[32:33], v[32:33]
	v_pk_mul_f32 v[56:57], v[46:47], v[46:47]
	v_pk_mov_b32 v[58:59], v[50:51], v[52:53] op_sel:[1,0]
	v_pk_mov_b32 v[54:55], v[46:47], v[54:55] op_sel:[1,0]
	v_pk_add_f32 v[34:35], v[50:51], v[34:35]
	v_pk_add_f32 v[32:33], v[46:47], v[32:33]
	v_pk_fma_f32 v[22:23], v[48:49], s[72:73], v[22:23] op_sel_hi:[1,0,1]
	v_pk_add_f32 v[54:55], v[58:59], v[54:55]
	v_mov_b32_e32 v58, v30
	v_mov_b32_e32 v59, v38
	v_pk_mov_b32 v[30:31], v[30:31], v[56:57] op_sel:[1,0]
	v_mov_b32_e32 v35, v53
	v_mov_b32_e32 v33, v57
	v_cvt_pk_bf16_f32 v20, v20, v21
	v_cvt_pk_bf16_f32 v21, v22, v23
	v_pk_add_f32 v[30:31], v[58:59], v[30:31]
	v_pk_add_f32 v[32:33], v[34:35], v[32:33]
	v_mov_b64_e32 v[150:151], v[20:21]
	v_lshrrev_b32_e32 v152, 4, v219
	v_lshlrev_b32_e32 v152, 3, v152
	v_mov_b32_e32 v153, v2
	v_permlane32_swap_b32_e32 v148, v150
	v_permlane32_swap_b32_e32 v149, v151
	v_lshl_add_u64 v[152:153], v[152:153], 0, v[44:45]
	s_nop 0
	v_permlane16_swap_b32_e32 v148, v150
	v_permlane16_swap_b32_e32 v149, v151
	global_store_dwordx4 v[152:153], v[148:151], off offset:256 sc0
	v_lshlrev_b32_e32 v44, 16, v20
	v_and_b32_e32 v48, 0xffff0000, v20
	v_lshlrev_b32_e32 v20, 16, v21
	v_and_b32_e32 v22, 0xffff0000, v21
	v_pk_add_f32 v[30:31], v[54:55], v[30:31]
	v_pk_add_f32 v[28:29], v[32:33], v[2:3]
	v_mul_f32_e32 v45, v44, v44
	v_mul_f32_e32 v49, v48, v48
	v_mul_f32_e32 v21, v20, v20
	v_mul_f32_e32 v23, v22, v22
	v_pk_add_f32 v[28:29], v[30:31], v[28:29]
	v_pk_add_f32 v[30:31], v[40:41], v[42:43]
	v_pk_add_f32 v[26:27], v[44:45], v[48:49]
	v_pk_add_f32 v[24:25], v[30:31], v[24:25]
	v_pk_add_f32 v[20:21], v[20:21], v[22:23]
	v_pk_add_f32 v[24:25], v[28:29], v[24:25]
	v_pk_add_f32 v[20:21], v[26:27], v[20:21]
	s_nop 0
	v_pk_add_f32 v[20:21], v[24:25], v[20:21]
	ds_bpermute_b32 v22, v181, v20
	ds_bpermute_b32 v23, v181, v21
	s_waitcnt lgkmcnt(0)
	v_pk_add_f32 v[20:21], v[20:21], v[22:23]
	ds_bpermute_b32 v22, v180, v20
	ds_bpermute_b32 v23, v180, v21
	s_and_saveexec_b64 s[0:1], s[40:41]
	s_cbranch_execz .LBB0_2391
	v_lshl_add_u64 v[24:25], s[52:53], 0, v[36:37]
	v_lshl_add_u64 v[24:25], s[68:69], 2, v[24:25]
	s_waitcnt lgkmcnt(0)
	v_pk_add_f32 v[20:21], v[20:21], v[22:23]
	global_store_dwordx2 v[24:25], v[20:21], off
.LBB0_2391:
	s_or_b64 exec, exec, s[0:1]
	v_add_u32_e32 v30, 0xb0, v146
	v_ashrrev_i32_e32 v31, 31, v30
	v_lshlrev_b64 v[20:21], 7, v[30:31]
	v_lshl_add_u64 v[26:27], v[134:135], 0, v[20:21]
	s_waitcnt lgkmcnt(0)
	s_waitcnt vmcnt(5)
	v_mov_b64_e32 v[22:23], v[206:207]
	v_mov_b64_e32 v[24:25], v[208:209]
	s_nop 0
	s_waitcnt vmcnt(4)
	v_mov_b64_e32 v[26:27], v[214:215]
	v_mov_b64_e32 v[28:29], v[216:217]
	s_waitcnt lgkmcnt(0)
	v_pk_add_f32 v[22:23], v[22:23], v[24:25]
	s_waitcnt lgkmcnt(0)
	v_pk_add_f32 v[26:27], v[26:27], v[28:29]
	s_nop 0
	v_pk_add_f32 v[22:23], v[26:27], v[22:23]
	ds_bpermute_b32 v24, v181, v22
	ds_bpermute_b32 v25, v181, v23
	s_waitcnt lgkmcnt(0)
	v_pk_add_f32 v[22:23], v[22:23], v[24:25]
	ds_bpermute_b32 v24, v180, v22
	ds_bpermute_b32 v25, v180, v23
	s_waitcnt lgkmcnt(0)
	v_pk_add_f32 v[22:23], v[22:23], v[24:25]
	s_nop 0
	v_pk_mul_f32 v[32:33], v[22:23], s[82:83] op_sel_hi:[1,0]
	v_lshlrev_b64 v[22:23], 11, v[30:31]
	v_lshl_add_u64 v[22:23], s[70:71], 0, v[22:23]
	v_lshl_add_u64 v[28:29], v[144:145], 1, v[22:23]
	s_waitcnt vmcnt(3)
	v_mov_b64_e32 v[22:23], v[234:235]
	v_fma_f32 v3, -v32, v32, v33
	v_max_f32_e32 v3, 0, v3
	v_add_f32_e32 v3, 0x3727c5ac, v3
	v_rsq_f32_e32 v34, v3
	s_waitcnt lgkmcnt(0)
	v_lshlrev_b32_e32 v3, 16, v22
	v_and_b32_e32 v22, 0xffff0000, v22
	v_lshlrev_b32_e32 v24, 16, v23
	v_and_b32_e32 v25, 0xffff0000, v23
	v_sub_f32_e32 v23, v22, v32
	v_sub_f32_e32 v22, v3, v32
	v_sub_f32_e32 v25, v25, v32
	v_sub_f32_e32 v24, v24, v32
	v_pk_mul_f32 v[26:27], v[24:25], v[34:35] op_sel_hi:[1,0]
	v_pk_mul_f32 v[30:31], v[22:23], v[34:35] op_sel_hi:[1,0]
	ds_read_b128 v[22:25], v244
	ds_read_b128 v[36:39], v244 offset:256
	s_waitcnt lgkmcnt(0)
	v_pk_fma_f32 v[24:25], v[24:25], v[26:27], v[38:39]
	s_nop 0
	v_pk_fma_f32 v[18:19], v[24:25], s[72:73], v[18:19] op_sel_hi:[1,0,1]
	s_waitcnt vmcnt(2)
	v_mov_b64_e32 v[24:25], v[236:237]
	v_pk_fma_f32 v[22:23], v[22:23], v[30:31], v[36:37]
	s_waitcnt lgkmcnt(0)
	v_lshlrev_b32_e32 v3, 16, v24
	v_pk_fma_f32 v[16:17], v[22:23], s[72:73], v[16:17] op_sel_hi:[1,0,1]
	v_cvt_pk_bf16_f32 v23, v18, v19
	v_cvt_pk_bf16_f32 v22, v16, v17
	v_and_b32_e32 v17, 0xffff0000, v24
	v_lshlrev_b32_e32 v19, 16, v25
	v_and_b32_e32 v26, 0xffff0000, v25
	v_mov_b64_e32 v[148:149], v[22:23]
	v_sub_f32_e32 v25, v17, v32
	v_sub_f32_e32 v24, v3, v32
	v_sub_f32_e32 v27, v26, v32
	v_sub_f32_e32 v26, v19, v32
	v_pk_mul_f32 v[30:31], v[34:35], v[26:27] op_sel_hi:[0,1]
	v_pk_mul_f32 v[40:41], v[34:35], v[24:25] op_sel_hi:[0,1]
	ds_read_b128 v[24:27], v244 offset:64
	ds_read_b128 v[36:39], v244 offset:320
	v_and_b32_e32 v18, 0xffff0000, v22
	v_lshlrev_b32_e32 v16, 16, v23
	s_waitcnt lgkmcnt(0)
; __device__ __forceinline__ u32x2 pk4(f32x4 v) { u32x2 r; r.x = pk2(v.x, v.y); r.y = pk2(v.z, v.w); return r; }
;     __device__ __forceinline__ void operator()(const f32x4 (&acc)[2][2][4][2], const pg8::Unit& u, int wr, int wc, int fr, int fq) const {
;     ...
;                 for (int bj = 0; bj < 2; ++bj)
; #pragma unroll
;                     for (int n = 0; n < 2; ++n) {
;                         const int col = u.pn * 256 + bj * 128 + wc * 32 + n * 16 + fq * 4;
;                         const u32x2 raw = *(const u32x2*)(src + (size_t)row * DM + col);
;                         f32x4 x = (f32x4){bflo(raw.x), bfhi(raw.x), bflo(raw.y), bfhi(raw.y)};
;                         if (ln) x = (x - mu) * rs * *(const f32x4*)(g + col) + *(const f32x4*)(b + col);
;                         const u32x2 pz = pk4(x * ALPHA + acc[ai][bj][m][n]);
;                         *(u32x2*)(dst + (size_t)row * DM + col) = pz;
;                         const float z0 = bflo(pz.x), z1 = bfhi(pz.x), z2 = bflo(pz.y), z3 = bfhi(pz.y);
;                         s1 += (z0 + z1) + (z2 + z3); s2 += (z0 * z0 + z1 * z1) + (z2 * z2 + z3 * z3);
;                     }
;                 s1 += __shfl_xor(s1, 16); s2 += __shfl_xor(s2, 16); s1 += __shfl_xor(s1, 32); s2 += __shfl_xor(s2, 32);
;                 if (fq == 0) { float* p = stm_n + (size_t)row * 32 + (u.pn * 4 + wc) * 2; p[0] = s1; p[1] = s2; }
	v_pk_fma_f32 v[24:25], v[24:25], v[40:41], v[36:37]
	s_nop 0
	v_pk_fma_f32 v[12:13], v[24:25], s[72:73], v[12:13] op_sel_hi:[1,0,1]
	s_waitcnt vmcnt(1)
	v_mov_b64_e32 v[24:25], v[238:239]
	v_pk_fma_f32 v[26:27], v[26:27], v[30:31], v[38:39]
	v_cvt_pk_bf16_f32 v30, v12, v13
	v_pk_fma_f32 v[14:15], v[26:27], s[72:73], v[14:15] op_sel_hi:[1,0,1]
	s_waitcnt lgkmcnt(0)
	v_lshlrev_b32_e32 v3, 16, v24
	v_cvt_pk_bf16_f32 v31, v14, v15
	v_lshlrev_b32_e32 v14, 16, v31
	v_and_b32_e32 v15, 0xffff0000, v31
	v_mul_f32_e32 v12, v14, v14
	v_pk_fma_f32 v[12:13], v[14:15], v[14:15], v[12:13] op_sel_hi:[1,1,0]
	v_lshlrev_b32_e32 v17, 16, v25
	v_and_b32_e32 v12, 0xffff0000, v24
	v_and_b32_e32 v19, 0xffff0000, v25
	v_mov_b64_e32 v[150:151], v[30:31]
	v_lshrrev_b32_e32 v42, 4, v219
	v_lshlrev_b32_e32 v42, 3, v42
	v_mov_b32_e32 v43, v2
	v_permlane32_swap_b32_e32 v148, v150
	v_permlane32_swap_b32_e32 v149, v151
	v_lshl_add_u64 v[42:43], v[42:43], 0, v[28:29]
	s_nop 0
	v_permlane16_swap_b32_e32 v148, v150
	v_permlane16_swap_b32_e32 v149, v151
	global_store_dwordx4 v[42:43], v[148:151], off sc0
	v_sub_f32_e32 v25, v12, v32
	v_sub_f32_e32 v24, v3, v32
	v_sub_f32_e32 v27, v19, v32
	v_sub_f32_e32 v26, v17, v32
	v_pk_mul_f32 v[40:41], v[34:35], v[26:27] op_sel_hi:[0,1]
	v_pk_mul_f32 v[42:43], v[34:35], v[24:25] op_sel_hi:[0,1]
	ds_read_b128 v[24:27], v244 offset:128
	ds_read_b128 v[36:39], v244 offset:384
	v_and_b32_e32 v31, 0xffff0000, v30
	s_waitcnt lgkmcnt(0)
	v_pk_fma_f32 v[24:25], v[24:25], v[42:43], v[36:37]
	s_waitcnt vmcnt(0)
	v_mov_b64_e32 v[36:37], v[240:241]
	v_pk_fma_f32 v[26:27], v[26:27], v[40:41], v[38:39]
	v_pk_fma_f32 v[8:9], v[24:25], s[72:73], v[8:9] op_sel_hi:[1,0,1]
	v_pk_fma_f32 v[10:11], v[26:27], s[72:73], v[10:11] op_sel_hi:[1,0,1]
	v_cvt_pk_bf16_f32 v8, v8, v9
	v_cvt_pk_bf16_f32 v9, v10, v11
	v_mov_b64_e32 v[148:149], v[8:9]
	v_lshlrev_b32_e32 v24, 16, v8
	v_and_b32_e32 v26, 0xffff0000, v8
	v_lshlrev_b32_e32 v8, 16, v9
	v_and_b32_e32 v10, 0xffff0000, v9
	v_mul_f32_e32 v25, v24, v24
	v_mul_f32_e32 v27, v26, v26
	v_mul_f32_e32 v9, v8, v8
	v_mul_f32_e32 v11, v10, v10
	v_pk_add_f32 v[8:9], v[8:9], v[10:11]
	s_waitcnt lgkmcnt(0)
	v_lshlrev_b32_e32 v3, 16, v36
	v_and_b32_e32 v12, 0xffff0000, v36
	v_lshlrev_b32_e32 v17, 16, v37
	v_and_b32_e32 v19, 0xffff0000, v37
	v_sub_f32_e32 v37, v12, v32
	v_sub_f32_e32 v36, v3, v32
	v_sub_f32_e32 v33, v19, v32
	v_sub_f32_e32 v32, v17, v32
	v_pk_mul_f32 v[32:33], v[34:35], v[32:33] op_sel_hi:[0,1]
	v_pk_mul_f32 v[34:35], v[34:35], v[36:37] op_sel_hi:[0,1]
	ds_read_b128 v[36:39], v244 offset:192
	ds_read_b128 v[40:43], v244 offset:448
	v_mov_b32_e32 v17, v31
	v_mov_b32_e32 v3, v13
	s_waitcnt lgkmcnt(0)
	v_pk_fma_f32 v[34:35], v[36:37], v[34:35], v[40:41]
	s_nop 0
	v_pk_fma_f32 v[4:5], v[34:35], s[72:73], v[4:5] op_sel_hi:[1,0,1]
	v_lshlrev_b32_e32 v35, 16, v30
	v_lshlrev_b32_e32 v34, 16, v22
	v_mov_b32_e32 v19, v35
	v_pk_fma_f32 v[32:33], v[38:39], v[32:33], v[42:43]
	v_pk_mul_f32 v[36:37], v[34:35], v[34:35]
	v_pk_mul_f32 v[38:39], v[18:19], v[18:19]
	v_and_b32_e32 v30, 0xffff0000, v23
	v_pk_mul_f32 v[22:23], v[16:17], v[16:17]
	v_pk_mul_f32 v[40:41], v[30:31], v[30:31]
	v_pk_mov_b32 v[42:43], v[34:35], v[36:37] op_sel:[1,0]
	v_pk_mov_b32 v[38:39], v[30:31], v[38:39] op_sel:[1,0]
	v_pk_add_f32 v[18:19], v[34:35], v[18:19]
	v_pk_add_f32 v[16:17], v[30:31], v[16:17]
	v_pk_fma_f32 v[6:7], v[32:33], s[72:73], v[6:7] op_sel_hi:[1,0,1]
	v_pk_add_f32 v[38:39], v[42:43], v[38:39]
	v_mov_b32_e32 v42, v14
	v_mov_b32_e32 v43, v22
	v_pk_mov_b32 v[14:15], v[14:15], v[40:41] op_sel:[1,0]
	v_mov_b32_e32 v19, v37
	v_mov_b32_e32 v17, v41
	v_cvt_pk_bf16_f32 v4, v4, v5
	v_cvt_pk_bf16_f32 v5, v6, v7
	v_pk_add_f32 v[14:15], v[42:43], v[14:15]
	v_pk_add_f32 v[16:17], v[18:19], v[16:17]
	v_mov_b64_e32 v[150:151], v[4:5]
	v_lshrrev_b32_e32 v146, 4, v219
	v_lshlrev_b32_e32 v146, 3, v146
	v_mov_b32_e32 v147, v2
	v_permlane32_swap_b32_e32 v148, v150
	v_permlane32_swap_b32_e32 v149, v151
	v_lshl_add_u64 v[146:147], v[146:147], 0, v[28:29]
	s_nop 0
	v_permlane16_swap_b32_e32 v148, v150
	v_permlane16_swap_b32_e32 v149, v151
	global_store_dwordx4 v[146:147], v[148:151], off offset:256 sc0
	v_lshlrev_b32_e32 v28, 16, v4
	v_and_b32_e32 v32, 0xffff0000, v4
	v_lshlrev_b32_e32 v4, 16, v5
	v_and_b32_e32 v6, 0xffff0000, v5
	v_pk_add_f32 v[14:15], v[38:39], v[14:15]
	v_pk_add_f32 v[12:13], v[16:17], v[2:3]
	v_mul_f32_e32 v29, v28, v28
	v_mul_f32_e32 v33, v32, v32
	v_mul_f32_e32 v5, v4, v4
	v_mul_f32_e32 v7, v6, v6
	v_pk_add_f32 v[12:13], v[14:15], v[12:13]
	v_pk_add_f32 v[14:15], v[24:25], v[26:27]
	v_pk_add_f32 v[10:11], v[28:29], v[32:33]
	v_pk_add_f32 v[8:9], v[14:15], v[8:9]
	v_pk_add_f32 v[4:5], v[4:5], v[6:7]
	v_pk_add_f32 v[8:9], v[12:13], v[8:9]
	v_pk_add_f32 v[4:5], v[10:11], v[4:5]
	s_nop 0
	v_pk_add_f32 v[4:5], v[8:9], v[4:5]
	ds_bpermute_b32 v6, v181, v4
	ds_bpermute_b32 v7, v181, v5
	s_waitcnt lgkmcnt(0)
	v_pk_add_f32 v[4:5], v[4:5], v[6:7]
	ds_bpermute_b32 v6, v180, v4
	ds_bpermute_b32 v7, v180, v5
	s_and_saveexec_b64 s[0:1], s[40:41]
	s_cbranch_execz .LBB0_2393
	v_lshl_add_u64 v[8:9], s[52:53], 0, v[20:21]
	v_lshl_add_u64 v[8:9], s[68:69], 2, v[8:9]
	s_waitcnt lgkmcnt(0)
	v_pk_add_f32 v[4:5], v[4:5], v[6:7]
	global_store_dwordx2 v[8:9], v[4:5], off
